# v75 with the 32 adjacent s_setprio 0/1 flip pairs inside GEMM sub-phases deleted (guide 7.4 step b, A/B of the per-cluster flips)
# speedup vs baseline: 1.0002x; 1.0002x over previous
.LBB0_190:
	ds_read_b128 v[144:147], v155
	ds_read_b128 v[158:161], v155 offset:1024
	ds_read_b128 v[162:165], v155 offset:2048
	ds_read_b128 v[166:169], v155 offset:3072
	ds_read_b128 v[170:173], v156
	ds_read_b128 v[174:177], v156 offset:1024
	ds_read_b128 v[178:181], v156 offset:2048
	ds_read_b128 v[182:185], v156 offset:3072
	s_add_u32 s0, s4, 0xfff80080
	s_addc_u32 s1, s5, -1
	s_cmp_eq_u32 s73, 28
	s_cselect_b32 s37, s19, s1
	s_cselect_b32 s36, s25, s0
	s_cselect_b32 s35, s23, s72
	s_cselect_b32 s34, s70, s71
	v_lshl_add_u64 v[220:221], s[4:5], 0, v[138:139]
	s_add_i32 m0, s9, 0xc000
	ds_read_b128 v[186:189], v157
	ds_read_b128 v[190:193], v157 offset:1024
	ds_read_b128 v[194:197], v157 offset:2048
	ds_read_b128 v[198:201], v157 offset:3072
	ds_read_b128 v[202:205], v157 offset:4096
	ds_read_b128 v[208:211], v157 offset:5120
	ds_read_b128 v[212:215], v157 offset:6144
	ds_read_b128 v[216:219], v157 offset:7168
	global_load_lds_dwordx4 v[220:221], off
	v_lshl_add_u64 v[220:221], s[4:5], 0, v[140:141]
	s_add_i32 m0, s9, 0xe000
	s_nop 0
	global_load_lds_dwordx4 v[220:221], off
	s_waitcnt vmcnt(8)
	s_waitcnt lgkmcnt(0)
	s_barrier
	s_setprio 1
	s_waitcnt lgkmcnt(0)
	v_mfma_f32_16x16x32_bf16 v[126:129], v[144:147], v[186:189], v[126:129]
	v_mfma_f32_16x16x32_bf16 v[122:125], v[162:165], v[186:189], v[122:125]
	v_mfma_f32_16x16x32_bf16 v[110:113], v[144:147], v[194:197], v[110:113]
	v_mfma_f32_16x16x32_bf16 v[106:109], v[162:165], v[194:197], v[106:109]
	v_mfma_f32_16x16x32_bf16 v[94:97], v[144:147], v[202:205], v[94:97]
	v_mfma_f32_16x16x32_bf16 v[90:93], v[162:165], v[202:205], v[90:93]
	v_mfma_f32_16x16x32_bf16 v[78:81], v[144:147], v[212:215], v[78:81]
	v_mfma_f32_16x16x32_bf16 v[74:77], v[162:165], v[212:215], v[74:77]
	v_mfma_f32_16x16x32_bf16 v[126:129], v[158:161], v[190:193], v[126:129]
	v_mfma_f32_16x16x32_bf16 v[122:125], v[166:169], v[190:193], v[122:125]
	v_mfma_f32_16x16x32_bf16 v[110:113], v[158:161], v[198:201], v[110:113]
	v_mfma_f32_16x16x32_bf16 v[106:109], v[166:169], v[198:201], v[106:109]
	v_mfma_f32_16x16x32_bf16 v[94:97], v[158:161], v[208:211], v[94:97]
	v_mfma_f32_16x16x32_bf16 v[90:93], v[166:169], v[208:211], v[90:93]
	v_mfma_f32_16x16x32_bf16 v[78:81], v[158:161], v[216:219], v[78:81]
	v_mfma_f32_16x16x32_bf16 v[74:77], v[166:169], v[216:219], v[74:77]
	v_mfma_f32_16x16x32_bf16 v[118:121], v[170:173], v[186:189], v[118:121]
	v_mfma_f32_16x16x32_bf16 v[114:117], v[178:181], v[186:189], v[114:117]
	v_mfma_f32_16x16x32_bf16 v[102:105], v[170:173], v[194:197], v[102:105]
	v_mfma_f32_16x16x32_bf16 v[98:101], v[178:181], v[194:197], v[98:101]
	v_mfma_f32_16x16x32_bf16 v[86:89], v[170:173], v[202:205], v[86:89]
	v_mfma_f32_16x16x32_bf16 v[82:85], v[178:181], v[202:205], v[82:85]
	v_mfma_f32_16x16x32_bf16 v[70:73], v[170:173], v[212:215], v[70:73]
	v_mfma_f32_16x16x32_bf16 v[66:69], v[178:181], v[212:215], v[66:69]
	v_mfma_f32_16x16x32_bf16 v[118:121], v[174:177], v[190:193], v[118:121]
	v_mfma_f32_16x16x32_bf16 v[114:117], v[182:185], v[190:193], v[114:117]
	v_mfma_f32_16x16x32_bf16 v[102:105], v[174:177], v[198:201], v[102:105]
	v_mfma_f32_16x16x32_bf16 v[98:101], v[182:185], v[198:201], v[98:101]
	v_mfma_f32_16x16x32_bf16 v[86:89], v[174:177], v[208:211], v[86:89]
	v_mfma_f32_16x16x32_bf16 v[82:85], v[182:185], v[208:211], v[82:85]
	v_mfma_f32_16x16x32_bf16 v[70:73], v[174:177], v[216:219], v[70:73]
	v_mfma_f32_16x16x32_bf16 v[66:69], v[182:185], v[216:219], v[66:69]
	s_setprio 0
	s_barrier
	s_add_i32 s0, s65, s56
	v_lshl_add_u64 v[220:221], s[34:35], 0, v[130:131]
	s_mov_b32 m0, s0
	ds_read_b128 v[186:189], v157 offset:16384
	ds_read_b128 v[190:193], v157 offset:17408
	ds_read_b128 v[194:197], v157 offset:18432
	ds_read_b128 v[198:201], v157 offset:19456
	ds_read_b128 v[202:205], v157 offset:20480
	ds_read_b128 v[208:211], v157 offset:21504
	ds_read_b128 v[212:215], v157 offset:22528
	ds_read_b128 v[216:219], v157 offset:23552
	global_load_lds_dwordx4 v[220:221], off
	s_add_i32 m0, s0, 0x2000
	s_add_u32 s74, s34, 0x80000
	v_lshl_add_u64 v[222:223], s[34:35], 0, v[132:133]
	s_addc_u32 s75, s35, 0
	s_add_i32 s0, s66, s56
	global_load_lds_dwordx4 v[222:223], off
	v_lshl_add_u64 v[224:225], s[74:75], 0, v[130:131]
	s_mov_b32 m0, s0
	v_lshl_add_u64 v[226:227], s[36:37], 0, v[132:133]
	global_load_lds_dwordx4 v[224:225], off
	v_lshl_add_u64 v[224:225], s[74:75], 0, v[132:133]
	s_add_i32 m0, s0, 0x2000
	s_nop 0
	global_load_lds_dwordx4 v[224:225], off
	v_lshl_add_u64 v[224:225], s[36:37], 0, v[130:131]
	s_mov_b32 m0, s9
	s_nop 0
	global_load_lds_dwordx4 v[224:225], off
	s_mov_b32 m0, s57
	s_nop 0
	global_load_lds_dwordx4 v[226:227], off
	s_waitcnt vmcnt(8)
	s_waitcnt lgkmcnt(0)
	s_barrier
	s_setprio 1
	s_waitcnt lgkmcnt(0)
	v_mfma_f32_16x16x32_bf16 v[62:65], v[144:147], v[186:189], v[62:65]
	v_mfma_f32_16x16x32_bf16 v[58:61], v[162:165], v[186:189], v[58:61]
	v_mfma_f32_16x16x32_bf16 v[46:49], v[144:147], v[194:197], v[46:49]
	v_mfma_f32_16x16x32_bf16 v[42:45], v[162:165], v[194:197], v[42:45]
	v_mfma_f32_16x16x32_bf16 v[30:33], v[144:147], v[202:205], v[30:33]
	v_mfma_f32_16x16x32_bf16 v[26:29], v[162:165], v[202:205], v[26:29]
	v_mfma_f32_16x16x32_bf16 v[14:17], v[144:147], v[212:215], v[14:17]
	v_mfma_f32_16x16x32_bf16 v[10:13], v[162:165], v[212:215], v[10:13]
	v_mfma_f32_16x16x32_bf16 v[62:65], v[158:161], v[190:193], v[62:65]
	v_mfma_f32_16x16x32_bf16 v[58:61], v[166:169], v[190:193], v[58:61]
	v_mfma_f32_16x16x32_bf16 v[46:49], v[158:161], v[198:201], v[46:49]
	v_mfma_f32_16x16x32_bf16 v[42:45], v[166:169], v[198:201], v[42:45]
	v_mfma_f32_16x16x32_bf16 v[30:33], v[158:161], v[208:211], v[30:33]
	v_mfma_f32_16x16x32_bf16 v[26:29], v[166:169], v[208:211], v[26:29]
	v_mfma_f32_16x16x32_bf16 v[14:17], v[158:161], v[216:219], v[14:17]
	v_mfma_f32_16x16x32_bf16 v[10:13], v[166:169], v[216:219], v[10:13]
	v_mfma_f32_16x16x32_bf16 v[54:57], v[170:173], v[186:189], v[54:57]
	v_mfma_f32_16x16x32_bf16 v[50:53], v[178:181], v[186:189], v[50:53]
	v_mfma_f32_16x16x32_bf16 v[38:41], v[170:173], v[194:197], v[38:41]
	v_mfma_f32_16x16x32_bf16 v[34:37], v[178:181], v[194:197], v[34:37]
	v_mfma_f32_16x16x32_bf16 v[22:25], v[170:173], v[202:205], v[22:25]
	v_mfma_f32_16x16x32_bf16 v[18:21], v[178:181], v[202:205], v[18:21]
	v_mfma_f32_16x16x32_bf16 v[6:9], v[170:173], v[212:215], v[6:9]
	v_mfma_f32_16x16x32_bf16 v[2:5], v[178:181], v[212:215], v[2:5]
	v_mfma_f32_16x16x32_bf16 v[54:57], v[174:177], v[190:193], v[54:57]
	v_mfma_f32_16x16x32_bf16 v[50:53], v[182:185], v[190:193], v[50:53]
	v_mfma_f32_16x16x32_bf16 v[38:41], v[174:177], v[198:201], v[38:41]
	v_mfma_f32_16x16x32_bf16 v[34:37], v[182:185], v[198:201], v[34:37]
	v_mfma_f32_16x16x32_bf16 v[22:25], v[174:177], v[208:211], v[22:25]
	v_mfma_f32_16x16x32_bf16 v[18:21], v[182:185], v[208:211], v[18:21]
	v_mfma_f32_16x16x32_bf16 v[6:9], v[174:177], v[216:219], v[6:9]
	v_mfma_f32_16x16x32_bf16 v[2:5], v[182:185], v[216:219], v[2:5]
	s_setprio 0
	s_barrier
	s_add_i32 s0, 0, 0x18000
	v_add_u32_e32 v134, s0, v137
	s_add_i32 s1, 0, 0x1c000
	ds_read_b128 v[144:147], v134
	ds_read_b128 v[158:161], v134 offset:1024
	ds_read_b128 v[162:165], v134 offset:2048
	ds_read_b128 v[166:169], v134 offset:3072
	v_add_u32_e32 v134, s1, v137
	ds_read_b128 v[170:173], v134
	ds_read_b128 v[174:177], v134 offset:1024
	ds_read_b128 v[178:181], v134 offset:2048
	ds_read_b128 v[182:185], v134 offset:3072
	s_add_u32 s36, s36, 0x80000
	s_addc_u32 s37, s37, 0
	s_mov_b32 m0, s58
	v_lshl_add_u64 v[228:229], s[36:37], 0, v[130:131]
	ds_read_b128 v[186:189], v157 offset:32768
	ds_read_b128 v[190:193], v157 offset:33792
	ds_read_b128 v[194:197], v157 offset:34816
	ds_read_b128 v[198:201], v157 offset:35840
	ds_read_b128 v[202:205], v157 offset:36864
	ds_read_b128 v[208:211], v157 offset:37888
	ds_read_b128 v[212:215], v157 offset:38912
	ds_read_b128 v[216:219], v157 offset:39936
	global_load_lds_dwordx4 v[228:229], off
	v_lshl_add_u64 v[228:229], s[36:37], 0, v[132:133]
	s_mov_b32 m0, s59
	s_nop 0
	global_load_lds_dwordx4 v[228:229], off
	s_waitcnt vmcnt(8)
	s_waitcnt lgkmcnt(0)
	s_barrier
	s_setprio 1
	s_waitcnt lgkmcnt(0)
	v_mfma_f32_16x16x32_bf16 v[126:129], v[144:147], v[186:189], v[126:129]
	v_mfma_f32_16x16x32_bf16 v[122:125], v[162:165], v[186:189], v[122:125]
	v_mfma_f32_16x16x32_bf16 v[110:113], v[144:147], v[194:197], v[110:113]
	v_mfma_f32_16x16x32_bf16 v[106:109], v[162:165], v[194:197], v[106:109]
	v_mfma_f32_16x16x32_bf16 v[94:97], v[144:147], v[202:205], v[94:97]
	v_mfma_f32_16x16x32_bf16 v[90:93], v[162:165], v[202:205], v[90:93]
	v_mfma_f32_16x16x32_bf16 v[78:81], v[144:147], v[212:215], v[78:81]
	v_mfma_f32_16x16x32_bf16 v[74:77], v[162:165], v[212:215], v[74:77]
	v_mfma_f32_16x16x32_bf16 v[126:129], v[158:161], v[190:193], v[126:129]
	v_mfma_f32_16x16x32_bf16 v[122:125], v[166:169], v[190:193], v[122:125]
	v_mfma_f32_16x16x32_bf16 v[110:113], v[158:161], v[198:201], v[110:113]
	v_mfma_f32_16x16x32_bf16 v[106:109], v[166:169], v[198:201], v[106:109]
	v_mfma_f32_16x16x32_bf16 v[94:97], v[158:161], v[208:211], v[94:97]
	v_mfma_f32_16x16x32_bf16 v[90:93], v[166:169], v[208:211], v[90:93]
	v_mfma_f32_16x16x32_bf16 v[78:81], v[158:161], v[216:219], v[78:81]
	v_mfma_f32_16x16x32_bf16 v[74:77], v[166:169], v[216:219], v[74:77]
	v_mfma_f32_16x16x32_bf16 v[118:121], v[170:173], v[186:189], v[118:121]
	v_mfma_f32_16x16x32_bf16 v[114:117], v[178:181], v[186:189], v[114:117]
	v_mfma_f32_16x16x32_bf16 v[102:105], v[170:173], v[194:197], v[102:105]
	v_mfma_f32_16x16x32_bf16 v[98:101], v[178:181], v[194:197], v[98:101]
	v_mfma_f32_16x16x32_bf16 v[86:89], v[170:173], v[202:205], v[86:89]
	v_mfma_f32_16x16x32_bf16 v[82:85], v[178:181], v[202:205], v[82:85]
	v_mfma_f32_16x16x32_bf16 v[70:73], v[170:173], v[212:215], v[70:73]
	v_mfma_f32_16x16x32_bf16 v[66:69], v[178:181], v[212:215], v[66:69]
	v_mfma_f32_16x16x32_bf16 v[118:121], v[174:177], v[190:193], v[118:121]
	v_mfma_f32_16x16x32_bf16 v[114:117], v[182:185], v[190:193], v[114:117]
	v_mfma_f32_16x16x32_bf16 v[102:105], v[174:177], v[198:201], v[102:105]
	v_mfma_f32_16x16x32_bf16 v[98:101], v[182:185], v[198:201], v[98:101]
	v_mfma_f32_16x16x32_bf16 v[86:89], v[174:177], v[208:211], v[86:89]
	v_mfma_f32_16x16x32_bf16 v[82:85], v[182:185], v[208:211], v[82:85]
	v_mfma_f32_16x16x32_bf16 v[70:73], v[174:177], v[216:219], v[70:73]
	v_mfma_f32_16x16x32_bf16 v[66:69], v[182:185], v[216:219], v[66:69]
	s_setprio 0
	s_barrier
	s_add_i32 s0, s0, s56
	v_lshl_add_u64 v[220:221], v[220:221], 0, s[16:17]
	s_mov_b32 m0, s0
	ds_read_b128 v[186:189], v157 offset:49152
	ds_read_b128 v[190:193], v157 offset:50176
	ds_read_b128 v[194:197], v157 offset:51200
	ds_read_b128 v[198:201], v157 offset:52224
	ds_read_b128 v[202:205], v157 offset:53248
	ds_read_b128 v[208:211], v157 offset:54272
	ds_read_b128 v[212:215], v157 offset:55296
	ds_read_b128 v[216:219], v157 offset:56320
	global_load_lds_dwordx4 v[220:221], off
	s_add_i32 m0, s0, 0x2000
	s_add_u32 s34, s34, 0x80080
	v_lshl_add_u64 v[220:221], v[222:223], 0, s[16:17]
	s_addc_u32 s35, s35, 0
	s_add_i32 s0, s1, s56
	global_load_lds_dwordx4 v[220:221], off
	v_lshl_add_u64 v[220:221], s[34:35], 0, v[130:131]
	s_mov_b32 m0, s0
	s_nop 0
	global_load_lds_dwordx4 v[220:221], off
	v_lshl_add_u64 v[220:221], s[34:35], 0, v[132:133]
	s_add_i32 m0, s0, 0x2000
	s_nop 0
	global_load_lds_dwordx4 v[220:221], off
	v_lshl_add_u64 v[220:221], v[224:225], 0, s[16:17]
	s_mov_b32 m0, s61
	s_nop 0
	global_load_lds_dwordx4 v[220:221], off
	v_lshl_add_u64 v[220:221], v[226:227], 0, s[16:17]
	s_mov_b32 m0, s62
	s_nop 0
	global_load_lds_dwordx4 v[220:221], off
	s_waitcnt vmcnt(8)
	s_waitcnt lgkmcnt(0)
	s_barrier
	s_setprio 1
	s_waitcnt lgkmcnt(0)
	v_mfma_f32_16x16x32_bf16 v[62:65], v[144:147], v[186:189], v[62:65]
	v_mfma_f32_16x16x32_bf16 v[58:61], v[162:165], v[186:189], v[58:61]
	v_mfma_f32_16x16x32_bf16 v[46:49], v[144:147], v[194:197], v[46:49]
	v_mfma_f32_16x16x32_bf16 v[42:45], v[162:165], v[194:197], v[42:45]
	v_mfma_f32_16x16x32_bf16 v[30:33], v[144:147], v[202:205], v[30:33]
	v_mfma_f32_16x16x32_bf16 v[26:29], v[162:165], v[202:205], v[26:29]
	v_mfma_f32_16x16x32_bf16 v[14:17], v[144:147], v[212:215], v[14:17]
	v_mfma_f32_16x16x32_bf16 v[10:13], v[162:165], v[212:215], v[10:13]
	v_mfma_f32_16x16x32_bf16 v[62:65], v[158:161], v[190:193], v[62:65]
	v_mfma_f32_16x16x32_bf16 v[58:61], v[166:169], v[190:193], v[58:61]
	v_mfma_f32_16x16x32_bf16 v[46:49], v[158:161], v[198:201], v[46:49]
	v_mfma_f32_16x16x32_bf16 v[42:45], v[166:169], v[198:201], v[42:45]
	v_mfma_f32_16x16x32_bf16 v[30:33], v[158:161], v[208:211], v[30:33]
	v_mfma_f32_16x16x32_bf16 v[26:29], v[166:169], v[208:211], v[26:29]
	v_mfma_f32_16x16x32_bf16 v[14:17], v[158:161], v[216:219], v[14:17]
	v_mfma_f32_16x16x32_bf16 v[10:13], v[166:169], v[216:219], v[10:13]
	v_mfma_f32_16x16x32_bf16 v[54:57], v[170:173], v[186:189], v[54:57]
	v_mfma_f32_16x16x32_bf16 v[50:53], v[178:181], v[186:189], v[50:53]
	v_mfma_f32_16x16x32_bf16 v[38:41], v[170:173], v[194:197], v[38:41]
	v_mfma_f32_16x16x32_bf16 v[34:37], v[178:181], v[194:197], v[34:37]
	v_mfma_f32_16x16x32_bf16 v[22:25], v[170:173], v[202:205], v[22:25]
	v_mfma_f32_16x16x32_bf16 v[18:21], v[178:181], v[202:205], v[18:21]
	v_mfma_f32_16x16x32_bf16 v[6:9], v[170:173], v[212:215], v[6:9]
	v_mfma_f32_16x16x32_bf16 v[2:5], v[178:181], v[212:215], v[2:5]
	v_mfma_f32_16x16x32_bf16 v[54:57], v[174:177], v[190:193], v[54:57]
	v_mfma_f32_16x16x32_bf16 v[50:53], v[182:185], v[190:193], v[50:53]
	v_mfma_f32_16x16x32_bf16 v[38:41], v[174:177], v[198:201], v[38:41]
	v_mfma_f32_16x16x32_bf16 v[34:37], v[182:185], v[198:201], v[34:37]
	v_mfma_f32_16x16x32_bf16 v[22:25], v[174:177], v[208:211], v[22:25]
	v_mfma_f32_16x16x32_bf16 v[18:21], v[182:185], v[208:211], v[18:21]
	v_mfma_f32_16x16x32_bf16 v[6:9], v[174:177], v[216:219], v[6:9]
	v_mfma_f32_16x16x32_bf16 v[2:5], v[182:185], v[216:219], v[2:5]
	s_setprio 0
	s_barrier
	s_add_i32 s73, s73, 2
	s_add_u32 s4, s4, 0x100
	s_addc_u32 s5, s5, 0
	s_add_u32 s71, s71, 0x100
	s_addc_u32 s72, s72, 0
	s_cmp_gt_u32 s73, 29
	s_cbranch_scc0 .LBB0_190
	s_and_b64 vcc, exec, s[20:21]
	s_cbranch_vccz .LBB0_193
	s_barrier

.LBB0_674:
	ds_read_b128 v[170:173], v166
	ds_read_b128 v[174:177], v166 offset:1024
	ds_read_b128 v[178:181], v166 offset:2048
	ds_read_b128 v[182:185], v166 offset:3072
	ds_read_b128 v[186:189], v167
	ds_read_b128 v[190:193], v167 offset:1024
	ds_read_b128 v[194:197], v167 offset:2048
	ds_read_b128 v[198:201], v167 offset:3072
	s_add_u32 s0, s28, 0xfffc0080
	s_addc_u32 s1, s29, -1
	s_cmp_eq_u32 s66, 28
	s_cselect_b32 s35, s23, s1
	s_cselect_b32 s34, s22, s0
	s_cselect_b32 s31, s21, s65
	s_cselect_b32 s30, s27, s39
	v_lshl_add_u64 v[164:165], s[28:29], 0, v[160:161]
	s_add_i32 m0, s45, 0xc000
	ds_read_b128 v[202:205], v168
	ds_read_b128 v[208:211], v168 offset:1024
	ds_read_b128 v[212:215], v168 offset:2048
	ds_read_b128 v[216:219], v168 offset:3072
	ds_read_b128 v[220:223], v168 offset:4096
	ds_read_b128 v[224:227], v168 offset:5120
	ds_read_b128 v[228:231], v168 offset:6144
	ds_read_b128 v[232:235], v168 offset:7168
	global_load_lds_dwordx4 v[164:165], off
	v_lshl_add_u64 v[164:165], s[28:29], 0, v[162:163]
	s_add_i32 m0, s45, 0xe000
	s_nop 0
	global_load_lds_dwordx4 v[164:165], off
	s_waitcnt vmcnt(8)
	s_waitcnt lgkmcnt(0)
	s_barrier
	s_setprio 1
	s_waitcnt lgkmcnt(0)
	v_mfma_f32_16x16x32_bf16 v[126:129], v[170:173], v[202:205], v[126:129]
	v_mfma_f32_16x16x32_bf16 v[122:125], v[178:181], v[202:205], v[122:125]
	v_mfma_f32_16x16x32_bf16 v[110:113], v[170:173], v[212:215], v[110:113]
	v_mfma_f32_16x16x32_bf16 v[106:109], v[178:181], v[212:215], v[106:109]
	v_mfma_f32_16x16x32_bf16 v[94:97], v[170:173], v[220:223], v[94:97]
	v_mfma_f32_16x16x32_bf16 v[90:93], v[178:181], v[220:223], v[90:93]
	v_mfma_f32_16x16x32_bf16 v[78:81], v[170:173], v[228:231], v[78:81]
	v_mfma_f32_16x16x32_bf16 v[74:77], v[178:181], v[228:231], v[74:77]
	v_mfma_f32_16x16x32_bf16 v[126:129], v[174:177], v[208:211], v[126:129]
	v_mfma_f32_16x16x32_bf16 v[122:125], v[182:185], v[208:211], v[122:125]
	v_mfma_f32_16x16x32_bf16 v[110:113], v[174:177], v[216:219], v[110:113]
	v_mfma_f32_16x16x32_bf16 v[106:109], v[182:185], v[216:219], v[106:109]
	v_mfma_f32_16x16x32_bf16 v[94:97], v[174:177], v[224:227], v[94:97]
	v_mfma_f32_16x16x32_bf16 v[90:93], v[182:185], v[224:227], v[90:93]
	v_mfma_f32_16x16x32_bf16 v[78:81], v[174:177], v[232:235], v[78:81]
	v_mfma_f32_16x16x32_bf16 v[74:77], v[182:185], v[232:235], v[74:77]
	v_mfma_f32_16x16x32_bf16 v[118:121], v[186:189], v[202:205], v[118:121]
	v_mfma_f32_16x16x32_bf16 v[114:117], v[194:197], v[202:205], v[114:117]
	v_mfma_f32_16x16x32_bf16 v[102:105], v[186:189], v[212:215], v[102:105]
	v_mfma_f32_16x16x32_bf16 v[98:101], v[194:197], v[212:215], v[98:101]
	v_mfma_f32_16x16x32_bf16 v[86:89], v[186:189], v[220:223], v[86:89]
	v_mfma_f32_16x16x32_bf16 v[82:85], v[194:197], v[220:223], v[82:85]
	v_mfma_f32_16x16x32_bf16 v[70:73], v[186:189], v[228:231], v[70:73]
	v_mfma_f32_16x16x32_bf16 v[66:69], v[194:197], v[228:231], v[66:69]
	v_mfma_f32_16x16x32_bf16 v[118:121], v[190:193], v[208:211], v[118:121]
	v_mfma_f32_16x16x32_bf16 v[114:117], v[198:201], v[208:211], v[114:117]
	v_mfma_f32_16x16x32_bf16 v[102:105], v[190:193], v[216:219], v[102:105]
	v_mfma_f32_16x16x32_bf16 v[98:101], v[198:201], v[216:219], v[98:101]
	v_mfma_f32_16x16x32_bf16 v[86:89], v[190:193], v[224:227], v[86:89]
	v_mfma_f32_16x16x32_bf16 v[82:85], v[198:201], v[224:227], v[82:85]
	v_mfma_f32_16x16x32_bf16 v[70:73], v[190:193], v[232:235], v[70:73]
	v_mfma_f32_16x16x32_bf16 v[66:69], v[198:201], v[232:235], v[66:69]
	s_setprio 0
	s_barrier
	s_add_i32 s0, s62, s44
	v_lshl_add_u64 v[164:165], s[30:31], 0, v[134:135]
	s_mov_b32 m0, s0
	ds_read_b128 v[202:205], v168 offset:16384
	ds_read_b128 v[208:211], v168 offset:17408
	ds_read_b128 v[212:215], v168 offset:18432
	ds_read_b128 v[216:219], v168 offset:19456
	ds_read_b128 v[220:223], v168 offset:20480
	ds_read_b128 v[224:227], v168 offset:21504
	ds_read_b128 v[228:231], v168 offset:22528
	ds_read_b128 v[232:235], v168 offset:23552
	global_load_lds_dwordx4 v[164:165], off
	s_add_i32 m0, s0, 0x2000
	s_add_u32 s68, s30, 0x80000
	v_lshl_add_u64 v[236:237], s[30:31], 0, v[138:139]
	s_addc_u32 s69, s31, 0
	s_add_i32 s0, s63, s44
	global_load_lds_dwordx4 v[236:237], off
	v_lshl_add_u64 v[238:239], s[68:69], 0, v[134:135]
	s_mov_b32 m0, s0
	v_lshl_add_u64 v[240:241], s[34:35], 0, v[136:137]
	global_load_lds_dwordx4 v[238:239], off
	v_lshl_add_u64 v[238:239], s[68:69], 0, v[138:139]
	s_add_i32 m0, s0, 0x2000
	s_nop 0
	global_load_lds_dwordx4 v[238:239], off
	v_lshl_add_u64 v[238:239], s[34:35], 0, v[132:133]
	s_mov_b32 m0, s45
	s_nop 0
	global_load_lds_dwordx4 v[238:239], off
	s_mov_b32 m0, s56
	s_nop 0
	global_load_lds_dwordx4 v[240:241], off
	s_waitcnt vmcnt(8)
	s_waitcnt lgkmcnt(0)
	s_barrier
	s_setprio 1
	s_waitcnt lgkmcnt(0)
	v_mfma_f32_16x16x32_bf16 v[62:65], v[170:173], v[202:205], v[62:65]
	v_mfma_f32_16x16x32_bf16 v[58:61], v[178:181], v[202:205], v[58:61]
	v_mfma_f32_16x16x32_bf16 v[46:49], v[170:173], v[212:215], v[46:49]
	v_mfma_f32_16x16x32_bf16 v[42:45], v[178:181], v[212:215], v[42:45]
	v_mfma_f32_16x16x32_bf16 v[30:33], v[170:173], v[220:223], v[30:33]
	v_mfma_f32_16x16x32_bf16 v[26:29], v[178:181], v[220:223], v[26:29]
	v_mfma_f32_16x16x32_bf16 v[14:17], v[170:173], v[228:231], v[14:17]
	v_mfma_f32_16x16x32_bf16 v[10:13], v[178:181], v[228:231], v[10:13]
	v_mfma_f32_16x16x32_bf16 v[62:65], v[174:177], v[208:211], v[62:65]
	v_mfma_f32_16x16x32_bf16 v[58:61], v[182:185], v[208:211], v[58:61]
	v_mfma_f32_16x16x32_bf16 v[46:49], v[174:177], v[216:219], v[46:49]
	v_mfma_f32_16x16x32_bf16 v[42:45], v[182:185], v[216:219], v[42:45]
	v_mfma_f32_16x16x32_bf16 v[30:33], v[174:177], v[224:227], v[30:33]
	v_mfma_f32_16x16x32_bf16 v[26:29], v[182:185], v[224:227], v[26:29]
	v_mfma_f32_16x16x32_bf16 v[14:17], v[174:177], v[232:235], v[14:17]
	v_mfma_f32_16x16x32_bf16 v[10:13], v[182:185], v[232:235], v[10:13]
	v_mfma_f32_16x16x32_bf16 v[54:57], v[186:189], v[202:205], v[54:57]
	v_mfma_f32_16x16x32_bf16 v[50:53], v[194:197], v[202:205], v[50:53]
	v_mfma_f32_16x16x32_bf16 v[38:41], v[186:189], v[212:215], v[38:41]
	v_mfma_f32_16x16x32_bf16 v[34:37], v[194:197], v[212:215], v[34:37]
	v_mfma_f32_16x16x32_bf16 v[22:25], v[186:189], v[220:223], v[22:25]
	v_mfma_f32_16x16x32_bf16 v[18:21], v[194:197], v[220:223], v[18:21]
	v_mfma_f32_16x16x32_bf16 v[6:9], v[186:189], v[228:231], v[6:9]
	v_mfma_f32_16x16x32_bf16 v[2:5], v[194:197], v[228:231], v[2:5]
	v_mfma_f32_16x16x32_bf16 v[54:57], v[190:193], v[208:211], v[54:57]
	v_mfma_f32_16x16x32_bf16 v[50:53], v[198:201], v[208:211], v[50:53]
	v_mfma_f32_16x16x32_bf16 v[38:41], v[190:193], v[216:219], v[38:41]
	v_mfma_f32_16x16x32_bf16 v[34:37], v[198:201], v[216:219], v[34:37]
	v_mfma_f32_16x16x32_bf16 v[22:25], v[190:193], v[224:227], v[22:25]
	v_mfma_f32_16x16x32_bf16 v[18:21], v[198:201], v[224:227], v[18:21]
	v_mfma_f32_16x16x32_bf16 v[6:9], v[190:193], v[232:235], v[6:9]
	v_mfma_f32_16x16x32_bf16 v[2:5], v[198:201], v[232:235], v[2:5]
	s_setprio 0
	s_barrier
	s_add_i32 s0, 0, 0x18000
	v_add_u32_e32 v169, s0, v131
	s_add_i32 s1, 0, 0x1c000
	ds_read_b128 v[170:173], v169
	ds_read_b128 v[174:177], v169 offset:1024
	ds_read_b128 v[178:181], v169 offset:2048
	ds_read_b128 v[182:185], v169 offset:3072
	v_add_u32_e32 v169, s1, v131
	ds_read_b128 v[186:189], v169
	ds_read_b128 v[190:193], v169 offset:1024
	ds_read_b128 v[194:197], v169 offset:2048
	ds_read_b128 v[198:201], v169 offset:3072
	s_add_u32 s34, s34, 0x40000
	s_addc_u32 s35, s35, 0
	s_mov_b32 m0, s57
	v_lshl_add_u64 v[242:243], s[34:35], 0, v[132:133]
	ds_read_b128 v[202:205], v168 offset:32768
	ds_read_b128 v[208:211], v168 offset:33792
	ds_read_b128 v[212:215], v168 offset:34816
	ds_read_b128 v[216:219], v168 offset:35840
	ds_read_b128 v[220:223], v168 offset:36864
	ds_read_b128 v[224:227], v168 offset:37888
	ds_read_b128 v[228:231], v168 offset:38912
	ds_read_b128 v[232:235], v168 offset:39936
	global_load_lds_dwordx4 v[242:243], off
	v_lshl_add_u64 v[242:243], s[34:35], 0, v[136:137]
	s_mov_b32 m0, s58
	s_nop 0
	global_load_lds_dwordx4 v[242:243], off
	s_waitcnt vmcnt(8)
	s_waitcnt lgkmcnt(0)
	s_barrier
	s_setprio 1
	s_waitcnt lgkmcnt(0)
	v_mfma_f32_16x16x32_bf16 v[126:129], v[170:173], v[202:205], v[126:129]
	v_mfma_f32_16x16x32_bf16 v[122:125], v[178:181], v[202:205], v[122:125]
	v_mfma_f32_16x16x32_bf16 v[110:113], v[170:173], v[212:215], v[110:113]
	v_mfma_f32_16x16x32_bf16 v[106:109], v[178:181], v[212:215], v[106:109]
	v_mfma_f32_16x16x32_bf16 v[94:97], v[170:173], v[220:223], v[94:97]
	v_mfma_f32_16x16x32_bf16 v[90:93], v[178:181], v[220:223], v[90:93]
	v_mfma_f32_16x16x32_bf16 v[78:81], v[170:173], v[228:231], v[78:81]
	v_mfma_f32_16x16x32_bf16 v[74:77], v[178:181], v[228:231], v[74:77]
	v_mfma_f32_16x16x32_bf16 v[126:129], v[174:177], v[208:211], v[126:129]
	v_mfma_f32_16x16x32_bf16 v[122:125], v[182:185], v[208:211], v[122:125]
	v_mfma_f32_16x16x32_bf16 v[110:113], v[174:177], v[216:219], v[110:113]
	v_mfma_f32_16x16x32_bf16 v[106:109], v[182:185], v[216:219], v[106:109]
	v_mfma_f32_16x16x32_bf16 v[94:97], v[174:177], v[224:227], v[94:97]
	v_mfma_f32_16x16x32_bf16 v[90:93], v[182:185], v[224:227], v[90:93]
	v_mfma_f32_16x16x32_bf16 v[78:81], v[174:177], v[232:235], v[78:81]
	v_mfma_f32_16x16x32_bf16 v[74:77], v[182:185], v[232:235], v[74:77]
	v_mfma_f32_16x16x32_bf16 v[118:121], v[186:189], v[202:205], v[118:121]
	v_mfma_f32_16x16x32_bf16 v[114:117], v[194:197], v[202:205], v[114:117]
	v_mfma_f32_16x16x32_bf16 v[102:105], v[186:189], v[212:215], v[102:105]
	v_mfma_f32_16x16x32_bf16 v[98:101], v[194:197], v[212:215], v[98:101]
	v_mfma_f32_16x16x32_bf16 v[86:89], v[186:189], v[220:223], v[86:89]
	v_mfma_f32_16x16x32_bf16 v[82:85], v[194:197], v[220:223], v[82:85]
	v_mfma_f32_16x16x32_bf16 v[70:73], v[186:189], v[228:231], v[70:73]
	v_mfma_f32_16x16x32_bf16 v[66:69], v[194:197], v[228:231], v[66:69]
	v_mfma_f32_16x16x32_bf16 v[118:121], v[190:193], v[208:211], v[118:121]
	v_mfma_f32_16x16x32_bf16 v[114:117], v[198:201], v[208:211], v[114:117]
	v_mfma_f32_16x16x32_bf16 v[102:105], v[190:193], v[216:219], v[102:105]
	v_mfma_f32_16x16x32_bf16 v[98:101], v[198:201], v[216:219], v[98:101]
	v_mfma_f32_16x16x32_bf16 v[86:89], v[190:193], v[224:227], v[86:89]
	v_mfma_f32_16x16x32_bf16 v[82:85], v[198:201], v[224:227], v[82:85]
	v_mfma_f32_16x16x32_bf16 v[70:73], v[190:193], v[232:235], v[70:73]
	v_mfma_f32_16x16x32_bf16 v[66:69], v[198:201], v[232:235], v[66:69]
	s_setprio 0
	s_barrier
	s_add_i32 s0, s0, s44
	v_lshl_add_u64 v[164:165], v[164:165], 0, s[16:17]
	s_mov_b32 m0, s0
	ds_read_b128 v[202:205], v168 offset:49152
	ds_read_b128 v[208:211], v168 offset:50176
	ds_read_b128 v[212:215], v168 offset:51200
	ds_read_b128 v[216:219], v168 offset:52224
	ds_read_b128 v[220:223], v168 offset:53248
	ds_read_b128 v[224:227], v168 offset:54272
	ds_read_b128 v[228:231], v168 offset:55296
	ds_read_b128 v[232:235], v168 offset:56320
	global_load_lds_dwordx4 v[164:165], off
	s_add_i32 m0, s0, 0x2000
	s_add_u32 s30, s30, 0x80080
	v_lshl_add_u64 v[164:165], v[236:237], 0, s[16:17]
	s_addc_u32 s31, s31, 0
	s_add_i32 s0, s1, s44
	global_load_lds_dwordx4 v[164:165], off
	v_lshl_add_u64 v[164:165], s[30:31], 0, v[134:135]
	s_mov_b32 m0, s0
	s_nop 0
	global_load_lds_dwordx4 v[164:165], off
	v_lshl_add_u64 v[164:165], s[30:31], 0, v[138:139]
	s_add_i32 m0, s0, 0x2000
	s_nop 0
	global_load_lds_dwordx4 v[164:165], off
	v_lshl_add_u64 v[164:165], v[238:239], 0, s[16:17]
	s_mov_b32 m0, s60
	s_nop 0
	global_load_lds_dwordx4 v[164:165], off
	v_lshl_add_u64 v[164:165], v[240:241], 0, s[16:17]
	s_mov_b32 m0, s61
	s_nop 0
	global_load_lds_dwordx4 v[164:165], off
	s_waitcnt vmcnt(8)
	s_waitcnt lgkmcnt(0)
	s_barrier
	s_setprio 1
	s_waitcnt lgkmcnt(0)
	v_mfma_f32_16x16x32_bf16 v[62:65], v[170:173], v[202:205], v[62:65]
	v_mfma_f32_16x16x32_bf16 v[58:61], v[178:181], v[202:205], v[58:61]
	v_mfma_f32_16x16x32_bf16 v[46:49], v[170:173], v[212:215], v[46:49]
	v_mfma_f32_16x16x32_bf16 v[42:45], v[178:181], v[212:215], v[42:45]
	v_mfma_f32_16x16x32_bf16 v[30:33], v[170:173], v[220:223], v[30:33]
	v_mfma_f32_16x16x32_bf16 v[26:29], v[178:181], v[220:223], v[26:29]
	v_mfma_f32_16x16x32_bf16 v[14:17], v[170:173], v[228:231], v[14:17]
	v_mfma_f32_16x16x32_bf16 v[10:13], v[178:181], v[228:231], v[10:13]
	v_mfma_f32_16x16x32_bf16 v[62:65], v[174:177], v[208:211], v[62:65]
	v_mfma_f32_16x16x32_bf16 v[58:61], v[182:185], v[208:211], v[58:61]
	v_mfma_f32_16x16x32_bf16 v[46:49], v[174:177], v[216:219], v[46:49]
	v_mfma_f32_16x16x32_bf16 v[42:45], v[182:185], v[216:219], v[42:45]
	v_mfma_f32_16x16x32_bf16 v[30:33], v[174:177], v[224:227], v[30:33]
	v_mfma_f32_16x16x32_bf16 v[26:29], v[182:185], v[224:227], v[26:29]
	v_mfma_f32_16x16x32_bf16 v[14:17], v[174:177], v[232:235], v[14:17]
	v_mfma_f32_16x16x32_bf16 v[10:13], v[182:185], v[232:235], v[10:13]
	v_mfma_f32_16x16x32_bf16 v[54:57], v[186:189], v[202:205], v[54:57]
	v_mfma_f32_16x16x32_bf16 v[50:53], v[194:197], v[202:205], v[50:53]
	v_mfma_f32_16x16x32_bf16 v[38:41], v[186:189], v[212:215], v[38:41]
	v_mfma_f32_16x16x32_bf16 v[34:37], v[194:197], v[212:215], v[34:37]
	v_mfma_f32_16x16x32_bf16 v[22:25], v[186:189], v[220:223], v[22:25]
	v_mfma_f32_16x16x32_bf16 v[18:21], v[194:197], v[220:223], v[18:21]
	v_mfma_f32_16x16x32_bf16 v[6:9], v[186:189], v[228:231], v[6:9]
	v_mfma_f32_16x16x32_bf16 v[2:5], v[194:197], v[228:231], v[2:5]
	v_mfma_f32_16x16x32_bf16 v[54:57], v[190:193], v[208:211], v[54:57]
	v_mfma_f32_16x16x32_bf16 v[50:53], v[198:201], v[208:211], v[50:53]
	v_mfma_f32_16x16x32_bf16 v[38:41], v[190:193], v[216:219], v[38:41]
	v_mfma_f32_16x16x32_bf16 v[34:37], v[198:201], v[216:219], v[34:37]
	v_mfma_f32_16x16x32_bf16 v[22:25], v[190:193], v[224:227], v[22:25]
	v_mfma_f32_16x16x32_bf16 v[18:21], v[198:201], v[224:227], v[18:21]
	v_mfma_f32_16x16x32_bf16 v[6:9], v[190:193], v[232:235], v[6:9]
	v_mfma_f32_16x16x32_bf16 v[2:5], v[198:201], v[232:235], v[2:5]
	s_setprio 0
	s_barrier
	s_add_i32 s66, s66, 2
	s_add_u32 s28, s28, 0x100
	s_addc_u32 s29, s29, 0
	s_add_u32 s39, s39, 0x100
	s_addc_u32 s65, s65, 0
	s_cmp_gt_u32 s66, 29
	s_cbranch_scc0 .LBB0_674
	s_and_b64 vcc, exec, s[18:19]
	s_cbranch_vccz .LBB0_677
	s_barrier

.LBB0_2017:
	v_add_u32_e32 v3, s83, v1
	ds_read_b128 v[178:181], v3
	ds_read_b128 v[186:189], v3 offset:1024
	ds_read_b128 v[190:193], v3 offset:2048
	ds_read_b128 v[194:197], v3 offset:3072
	v_add_u32_e32 v3, s84, v1
	ds_read_b128 v[198:201], v3
	ds_read_b128 v[202:205], v3 offset:1024
	ds_read_b128 v[208:211], v3 offset:2048
	ds_read_b128 v[212:215], v3 offset:3072
	s_add_i32 vcc_lo, s8, 2
	s_add_u32 s6, s64, s60
	s_addc_u32 s7, s65, s61
	s_add_u32 s33, s62, s60
	s_addc_u32 s40, s63, s61
	s_cmp_eq_u32 s27, s8
	s_cselect_b32 s69, s35, s7
	s_cselect_b32 s68, s34, s6
	s_cselect_b32 s67, s37, s40
	s_cselect_b32 s66, s36, s33
	v_lshl_add_u64 v[182:183], v[176:177], 0, s[60:61]
	s_add_i32 m0, s73, 0xc000
	ds_read_b128 v[216:219], v185
	ds_read_b128 v[220:223], v185 offset:1024
	ds_read_b128 v[224:227], v185 offset:2048
	ds_read_b128 v[228:231], v185 offset:3072
	ds_read_b128 v[232:235], v185 offset:4096
	ds_read_b128 v[236:239], v185 offset:5120
	ds_read_b128 v[240:243], v185 offset:6144
	ds_read_b128 v[244:247], v185 offset:7168
	global_load_lds_dwordx4 v[182:183], off
	v_lshl_add_u64 v[182:183], v[4:5], 0, s[60:61]
	s_add_i32 m0, s73, 0xe000
	s_nop 0
	global_load_lds_dwordx4 v[182:183], off
	s_waitcnt vmcnt(8)
	s_waitcnt lgkmcnt(0)
	s_barrier
	s_setprio 1
	s_waitcnt lgkmcnt(0)
	v_mfma_f32_16x16x32_bf16 v[66:69], v[178:181], v[216:219], v[66:69]
	v_mfma_f32_16x16x32_bf16 v[62:65], v[190:193], v[216:219], v[62:65]
	v_mfma_f32_16x16x32_bf16 v[50:53], v[178:181], v[224:227], v[50:53]
	v_mfma_f32_16x16x32_bf16 v[46:49], v[190:193], v[224:227], v[46:49]
	v_mfma_f32_16x16x32_bf16 v[34:37], v[178:181], v[232:235], v[34:37]
	v_mfma_f32_16x16x32_bf16 v[30:33], v[190:193], v[232:235], v[30:33]
	v_mfma_f32_16x16x32_bf16 v[18:21], v[178:181], v[240:243], v[18:21]
	v_mfma_f32_16x16x32_bf16 v[14:17], v[190:193], v[240:243], v[14:17]
	v_mfma_f32_16x16x32_bf16 v[66:69], v[186:189], v[220:223], v[66:69]
	v_mfma_f32_16x16x32_bf16 v[62:65], v[194:197], v[220:223], v[62:65]
	v_mfma_f32_16x16x32_bf16 v[50:53], v[186:189], v[228:231], v[50:53]
	v_mfma_f32_16x16x32_bf16 v[46:49], v[194:197], v[228:231], v[46:49]
	v_mfma_f32_16x16x32_bf16 v[34:37], v[186:189], v[236:239], v[34:37]
	v_mfma_f32_16x16x32_bf16 v[30:33], v[194:197], v[236:239], v[30:33]
	v_mfma_f32_16x16x32_bf16 v[18:21], v[186:189], v[244:247], v[18:21]
	v_mfma_f32_16x16x32_bf16 v[14:17], v[194:197], v[244:247], v[14:17]
	v_mfma_f32_16x16x32_bf16 v[58:61], v[198:201], v[216:219], v[58:61]
	v_mfma_f32_16x16x32_bf16 v[54:57], v[208:211], v[216:219], v[54:57]
	v_mfma_f32_16x16x32_bf16 v[42:45], v[198:201], v[224:227], v[42:45]
	v_mfma_f32_16x16x32_bf16 v[38:41], v[208:211], v[224:227], v[38:41]
	v_mfma_f32_16x16x32_bf16 v[26:29], v[198:201], v[232:235], v[26:29]
	v_mfma_f32_16x16x32_bf16 v[22:25], v[208:211], v[232:235], v[22:25]
	v_mfma_f32_16x16x32_bf16 v[10:13], v[198:201], v[240:243], v[10:13]
	v_mfma_f32_16x16x32_bf16 v[6:9], v[208:211], v[240:243], v[6:9]
	v_mfma_f32_16x16x32_bf16 v[58:61], v[202:205], v[220:223], v[58:61]
	v_mfma_f32_16x16x32_bf16 v[54:57], v[212:215], v[220:223], v[54:57]
	v_mfma_f32_16x16x32_bf16 v[42:45], v[202:205], v[228:231], v[42:45]
	v_mfma_f32_16x16x32_bf16 v[38:41], v[212:215], v[228:231], v[38:41]
	v_mfma_f32_16x16x32_bf16 v[26:29], v[202:205], v[236:239], v[26:29]
	v_mfma_f32_16x16x32_bf16 v[22:25], v[212:215], v[236:239], v[22:25]
	v_mfma_f32_16x16x32_bf16 v[10:13], v[202:205], v[244:247], v[10:13]
	v_mfma_f32_16x16x32_bf16 v[6:9], v[212:215], v[244:247], v[6:9]
	s_setprio 0
	s_barrier
	s_add_i32 s6, s83, s72
	v_lshl_add_u64 v[182:183], s[66:67], 0, v[134:135]
	s_mov_b32 m0, s6
	ds_read_b128 v[216:219], v185 offset:16384
	ds_read_b128 v[220:223], v185 offset:17408
	ds_read_b128 v[224:227], v185 offset:18432
	ds_read_b128 v[228:231], v185 offset:19456
	ds_read_b128 v[232:235], v185 offset:20480
	ds_read_b128 v[236:239], v185 offset:21504
	ds_read_b128 v[240:243], v185 offset:22528
	ds_read_b128 v[244:247], v185 offset:23552
	global_load_lds_dwordx4 v[182:183], off
	s_add_i32 m0, s6, 0x2000
	s_add_u32 s6, s66, 0x80000
	v_lshl_add_u64 v[248:249], s[66:67], 0, v[136:137]
	s_addc_u32 s7, s67, 0
	s_add_i32 s8, s84, s72
	global_load_lds_dwordx4 v[248:249], off
	v_lshl_add_u64 v[250:251], s[6:7], 0, v[134:135]
	s_mov_b32 m0, s8
	v_lshl_add_u64 v[252:253], s[68:69], 0, v[136:137]
	global_load_lds_dwordx4 v[250:251], off
	v_lshl_add_u64 v[250:251], s[6:7], 0, v[136:137]
	s_add_i32 m0, s8, 0x2000
	s_nop 0
	global_load_lds_dwordx4 v[250:251], off
	v_lshl_add_u64 v[250:251], s[68:69], 0, v[134:135]
	s_mov_b32 m0, s73
	s_nop 0
	global_load_lds_dwordx4 v[250:251], off
	s_mov_b32 m0, s74
	s_nop 0
	global_load_lds_dwordx4 v[252:253], off
	s_waitcnt vmcnt(8)
	s_waitcnt lgkmcnt(0)
	s_barrier
	s_setprio 1
	s_waitcnt lgkmcnt(0)
	v_mfma_f32_16x16x32_bf16 v[130:133], v[178:181], v[216:219], v[130:133]
	v_mfma_f32_16x16x32_bf16 v[126:129], v[190:193], v[216:219], v[126:129]
	v_mfma_f32_16x16x32_bf16 v[114:117], v[178:181], v[224:227], v[114:117]
	v_mfma_f32_16x16x32_bf16 v[110:113], v[190:193], v[224:227], v[110:113]
	v_mfma_f32_16x16x32_bf16 v[98:101], v[178:181], v[232:235], v[98:101]
	v_mfma_f32_16x16x32_bf16 v[94:97], v[190:193], v[232:235], v[94:97]
	v_mfma_f32_16x16x32_bf16 v[82:85], v[178:181], v[240:243], v[82:85]
	v_mfma_f32_16x16x32_bf16 v[78:81], v[190:193], v[240:243], v[78:81]
	v_mfma_f32_16x16x32_bf16 v[130:133], v[186:189], v[220:223], v[130:133]
	v_mfma_f32_16x16x32_bf16 v[126:129], v[194:197], v[220:223], v[126:129]
	v_mfma_f32_16x16x32_bf16 v[114:117], v[186:189], v[228:231], v[114:117]
	v_mfma_f32_16x16x32_bf16 v[110:113], v[194:197], v[228:231], v[110:113]
	v_mfma_f32_16x16x32_bf16 v[98:101], v[186:189], v[236:239], v[98:101]
	v_mfma_f32_16x16x32_bf16 v[94:97], v[194:197], v[236:239], v[94:97]
	v_mfma_f32_16x16x32_bf16 v[82:85], v[186:189], v[244:247], v[82:85]
	v_mfma_f32_16x16x32_bf16 v[78:81], v[194:197], v[244:247], v[78:81]
	v_mfma_f32_16x16x32_bf16 v[122:125], v[198:201], v[216:219], v[122:125]
	v_mfma_f32_16x16x32_bf16 v[118:121], v[208:211], v[216:219], v[118:121]
	v_mfma_f32_16x16x32_bf16 v[106:109], v[198:201], v[224:227], v[106:109]
	v_mfma_f32_16x16x32_bf16 v[102:105], v[208:211], v[224:227], v[102:105]
	v_mfma_f32_16x16x32_bf16 v[90:93], v[198:201], v[232:235], v[90:93]
	v_mfma_f32_16x16x32_bf16 v[86:89], v[208:211], v[232:235], v[86:89]
	v_mfma_f32_16x16x32_bf16 v[74:77], v[198:201], v[240:243], v[74:77]
	v_mfma_f32_16x16x32_bf16 v[70:73], v[208:211], v[240:243], v[70:73]
	v_mfma_f32_16x16x32_bf16 v[122:125], v[202:205], v[220:223], v[122:125]
	v_mfma_f32_16x16x32_bf16 v[118:121], v[212:215], v[220:223], v[118:121]
	v_mfma_f32_16x16x32_bf16 v[106:109], v[202:205], v[228:231], v[106:109]
	v_mfma_f32_16x16x32_bf16 v[102:105], v[212:215], v[228:231], v[102:105]
	v_mfma_f32_16x16x32_bf16 v[90:93], v[202:205], v[236:239], v[90:93]
	v_mfma_f32_16x16x32_bf16 v[86:89], v[212:215], v[236:239], v[86:89]
	v_mfma_f32_16x16x32_bf16 v[74:77], v[202:205], v[244:247], v[74:77]
	v_mfma_f32_16x16x32_bf16 v[70:73], v[212:215], v[244:247], v[70:73]
	s_setprio 0
	s_barrier
	s_add_i32 s8, 0, 0x18000
	v_add_u32_e32 v3, s8, v1
	s_add_i32 s33, 0, 0x1c000
	ds_read_b128 v[178:181], v3
	ds_read_b128 v[186:189], v3 offset:1024
	ds_read_b128 v[190:193], v3 offset:2048
	ds_read_b128 v[194:197], v3 offset:3072
	v_add_u32_e32 v3, s33, v1
	ds_read_b128 v[198:201], v3
	ds_read_b128 v[202:205], v3 offset:1024
	ds_read_b128 v[208:211], v3 offset:2048
	ds_read_b128 v[212:215], v3 offset:3072
	s_add_u32 s6, s68, 0x80000
	s_addc_u32 s7, s69, 0
	s_mov_b32 m0, s75
	v_lshl_add_u64 v[146:147], s[6:7], 0, v[134:135]
	ds_read_b128 v[216:219], v185 offset:32768
	ds_read_b128 v[220:223], v185 offset:33792
	ds_read_b128 v[224:227], v185 offset:34816
	ds_read_b128 v[228:231], v185 offset:35840
	ds_read_b128 v[232:235], v185 offset:36864
	ds_read_b128 v[236:239], v185 offset:37888
	ds_read_b128 v[240:243], v185 offset:38912
	ds_read_b128 v[244:247], v185 offset:39936
	global_load_lds_dwordx4 v[146:147], off
	v_lshl_add_u64 v[146:147], s[6:7], 0, v[136:137]
	s_mov_b32 m0, s76
	s_nop 0
	global_load_lds_dwordx4 v[146:147], off
	s_waitcnt vmcnt(8)
	s_waitcnt lgkmcnt(0)
	s_barrier
	s_setprio 1
	s_waitcnt lgkmcnt(0)
	v_mfma_f32_16x16x32_bf16 v[66:69], v[178:181], v[216:219], v[66:69]
	v_mfma_f32_16x16x32_bf16 v[62:65], v[190:193], v[216:219], v[62:65]
	v_mfma_f32_16x16x32_bf16 v[50:53], v[178:181], v[224:227], v[50:53]
	v_mfma_f32_16x16x32_bf16 v[46:49], v[190:193], v[224:227], v[46:49]
	v_mfma_f32_16x16x32_bf16 v[34:37], v[178:181], v[232:235], v[34:37]
	v_mfma_f32_16x16x32_bf16 v[30:33], v[190:193], v[232:235], v[30:33]
	v_mfma_f32_16x16x32_bf16 v[18:21], v[178:181], v[240:243], v[18:21]
	v_mfma_f32_16x16x32_bf16 v[14:17], v[190:193], v[240:243], v[14:17]
	v_mfma_f32_16x16x32_bf16 v[66:69], v[186:189], v[220:223], v[66:69]
	v_mfma_f32_16x16x32_bf16 v[62:65], v[194:197], v[220:223], v[62:65]
	v_mfma_f32_16x16x32_bf16 v[50:53], v[186:189], v[228:231], v[50:53]
	v_mfma_f32_16x16x32_bf16 v[46:49], v[194:197], v[228:231], v[46:49]
	v_mfma_f32_16x16x32_bf16 v[34:37], v[186:189], v[236:239], v[34:37]
	v_mfma_f32_16x16x32_bf16 v[30:33], v[194:197], v[236:239], v[30:33]
	v_mfma_f32_16x16x32_bf16 v[18:21], v[186:189], v[244:247], v[18:21]
	v_mfma_f32_16x16x32_bf16 v[14:17], v[194:197], v[244:247], v[14:17]
	v_mfma_f32_16x16x32_bf16 v[58:61], v[198:201], v[216:219], v[58:61]
	v_mfma_f32_16x16x32_bf16 v[54:57], v[208:211], v[216:219], v[54:57]
	v_mfma_f32_16x16x32_bf16 v[42:45], v[198:201], v[224:227], v[42:45]
	v_mfma_f32_16x16x32_bf16 v[38:41], v[208:211], v[224:227], v[38:41]
	v_mfma_f32_16x16x32_bf16 v[26:29], v[198:201], v[232:235], v[26:29]
	v_mfma_f32_16x16x32_bf16 v[22:25], v[208:211], v[232:235], v[22:25]
	v_mfma_f32_16x16x32_bf16 v[10:13], v[198:201], v[240:243], v[10:13]
	v_mfma_f32_16x16x32_bf16 v[6:9], v[208:211], v[240:243], v[6:9]
	v_mfma_f32_16x16x32_bf16 v[58:61], v[202:205], v[220:223], v[58:61]
	v_mfma_f32_16x16x32_bf16 v[54:57], v[212:215], v[220:223], v[54:57]
	v_mfma_f32_16x16x32_bf16 v[42:45], v[202:205], v[228:231], v[42:45]
	v_mfma_f32_16x16x32_bf16 v[38:41], v[212:215], v[228:231], v[38:41]
	v_mfma_f32_16x16x32_bf16 v[26:29], v[202:205], v[236:239], v[26:29]
	v_mfma_f32_16x16x32_bf16 v[22:25], v[212:215], v[236:239], v[22:25]
	v_mfma_f32_16x16x32_bf16 v[10:13], v[202:205], v[244:247], v[10:13]
	v_mfma_f32_16x16x32_bf16 v[6:9], v[212:215], v[244:247], v[6:9]
	s_setprio 0
	s_barrier
	s_add_i32 s6, s8, s72
	v_lshl_add_u64 v[146:147], v[182:183], 0, s[16:17]
	s_mov_b32 m0, s6
	ds_read_b128 v[216:219], v185 offset:49152
	ds_read_b128 v[220:223], v185 offset:50176
	ds_read_b128 v[224:227], v185 offset:51200
	ds_read_b128 v[228:231], v185 offset:52224
	ds_read_b128 v[232:235], v185 offset:53248
	ds_read_b128 v[236:239], v185 offset:54272
	ds_read_b128 v[240:243], v185 offset:55296
	ds_read_b128 v[244:247], v185 offset:56320
	global_load_lds_dwordx4 v[146:147], off
	s_add_i32 m0, s6, 0x2000
	s_add_u32 s6, s66, 0x80080
	v_lshl_add_u64 v[146:147], v[248:249], 0, s[16:17]
	s_addc_u32 s7, s67, 0
	s_add_i32 s8, s33, s72
	global_load_lds_dwordx4 v[146:147], off
	v_lshl_add_u64 v[146:147], s[6:7], 0, v[134:135]
	s_mov_b32 m0, s8
	s_nop 0
	global_load_lds_dwordx4 v[146:147], off
	v_lshl_add_u64 v[146:147], s[6:7], 0, v[136:137]
	s_add_i32 m0, s8, 0x2000
	s_nop 0
	global_load_lds_dwordx4 v[146:147], off
	v_lshl_add_u64 v[146:147], v[250:251], 0, s[16:17]
	s_mov_b32 m0, s79
	s_nop 0
	global_load_lds_dwordx4 v[146:147], off
	v_lshl_add_u64 v[146:147], v[252:253], 0, s[16:17]
	s_mov_b32 m0, s80
	s_nop 0
	global_load_lds_dwordx4 v[146:147], off
	s_waitcnt vmcnt(8)
	s_waitcnt lgkmcnt(0)
	s_barrier
	s_setprio 1
	s_waitcnt lgkmcnt(0)
	v_mfma_f32_16x16x32_bf16 v[130:133], v[178:181], v[216:219], v[130:133]
	v_mfma_f32_16x16x32_bf16 v[126:129], v[190:193], v[216:219], v[126:129]
	v_mfma_f32_16x16x32_bf16 v[114:117], v[178:181], v[224:227], v[114:117]
	v_mfma_f32_16x16x32_bf16 v[110:113], v[190:193], v[224:227], v[110:113]
	v_mfma_f32_16x16x32_bf16 v[98:101], v[178:181], v[232:235], v[98:101]
	v_mfma_f32_16x16x32_bf16 v[94:97], v[190:193], v[232:235], v[94:97]
	v_mfma_f32_16x16x32_bf16 v[82:85], v[178:181], v[240:243], v[82:85]
	v_mfma_f32_16x16x32_bf16 v[78:81], v[190:193], v[240:243], v[78:81]
	v_mfma_f32_16x16x32_bf16 v[130:133], v[186:189], v[220:223], v[130:133]
	v_mfma_f32_16x16x32_bf16 v[126:129], v[194:197], v[220:223], v[126:129]
	v_mfma_f32_16x16x32_bf16 v[114:117], v[186:189], v[228:231], v[114:117]
	v_mfma_f32_16x16x32_bf16 v[110:113], v[194:197], v[228:231], v[110:113]
	v_mfma_f32_16x16x32_bf16 v[98:101], v[186:189], v[236:239], v[98:101]
	v_mfma_f32_16x16x32_bf16 v[94:97], v[194:197], v[236:239], v[94:97]
	v_mfma_f32_16x16x32_bf16 v[82:85], v[186:189], v[244:247], v[82:85]
	v_mfma_f32_16x16x32_bf16 v[78:81], v[194:197], v[244:247], v[78:81]
	v_mfma_f32_16x16x32_bf16 v[122:125], v[198:201], v[216:219], v[122:125]
	v_mfma_f32_16x16x32_bf16 v[118:121], v[208:211], v[216:219], v[118:121]
	v_mfma_f32_16x16x32_bf16 v[106:109], v[198:201], v[224:227], v[106:109]
	v_mfma_f32_16x16x32_bf16 v[102:105], v[208:211], v[224:227], v[102:105]
	v_mfma_f32_16x16x32_bf16 v[90:93], v[198:201], v[232:235], v[90:93]
	v_mfma_f32_16x16x32_bf16 v[86:89], v[208:211], v[232:235], v[86:89]
	v_mfma_f32_16x16x32_bf16 v[74:77], v[198:201], v[240:243], v[74:77]
	v_mfma_f32_16x16x32_bf16 v[70:73], v[208:211], v[240:243], v[70:73]
	v_mfma_f32_16x16x32_bf16 v[122:125], v[202:205], v[220:223], v[122:125]
	v_mfma_f32_16x16x32_bf16 v[118:121], v[212:215], v[220:223], v[118:121]
	v_mfma_f32_16x16x32_bf16 v[106:109], v[202:205], v[228:231], v[106:109]
	v_mfma_f32_16x16x32_bf16 v[102:105], v[212:215], v[228:231], v[102:105]
	v_mfma_f32_16x16x32_bf16 v[90:93], v[202:205], v[236:239], v[90:93]
	v_mfma_f32_16x16x32_bf16 v[86:89], v[212:215], v[236:239], v[86:89]
	v_mfma_f32_16x16x32_bf16 v[74:77], v[202:205], v[244:247], v[74:77]
	v_mfma_f32_16x16x32_bf16 v[70:73], v[212:215], v[244:247], v[70:73]
	s_setprio 0
	s_barrier
	s_add_u32 s64, s64, 0x100
	s_addc_u32 s65, s65, 0
	s_add_u32 s62, s62, 0x100
	s_addc_u32 s63, s63, 0
	v_lshl_add_u64 v[176:177], v[176:177], 0, s[20:21]
	v_lshl_add_u64 v[4:5], v[4:5], 0, s[20:21]
	s_cmp_ge_u32 vcc_lo, s97
	s_mov_b32 s8, vcc_lo
	s_cbranch_scc0 .LBB0_2017
	s_and_b64 vcc, exec, s[58:59]
	s_cbranch_vccz .LBB0_2015
	v_mov_b32_e32 v3, 0
	v_lshlrev_b64 v[178:179], 1, v[164:165]
	v_add_u32_e32 v3, v3, v138
	v_add_u32_e32 v4, s29, v3
	v_ashrrev_i32_e32 v5, 31, v4
	v_lshlrev_b64 v[4:5], 13, v[4:5]
	v_lshl_add_u64 v[4:5], s[12:13], 0, v[4:5]
	v_lshl_add_u64 v[182:183], v[4:5], 0, s[22:23]
	v_lshl_add_u64 v[146:147], v[4:5], 0, v[178:179]
	v_lshl_add_u64 v[4:5], v[182:183], 0, v[178:179]
	v_lshlrev_b64 v[180:181], 1, v[170:171]
	global_load_dwordx2 v[186:187], v[146:147], off
	global_load_dwordx2 v[188:189], v[146:147], off offset:32
	global_load_dwordx2 v[190:191], v[146:147], off offset:256
	global_load_dwordx2 v[192:193], v[4:5], off
	v_lshl_add_u64 v[4:5], v[182:183], 0, v[180:181]
	v_lshlrev_b64 v[176:177], 1, v[168:169]
	global_load_dwordx2 v[194:195], v[4:5], off
	v_add_u32_e32 v198, s31, v3
	global_load_dwordx2 v[146:147], v[146:147], off offset:288
	v_lshl_add_u64 v[4:5], v[182:183], 0, v[176:177]
	global_load_dwordx2 v[196:197], v[4:5], off
	v_lshlrev_b64 v[4:5], 1, v[166:167]
	v_lshl_add_u64 v[182:183], v[182:183], 0, v[4:5]
	global_load_dwordx2 v[202:203], v[182:183], off
	v_ashrrev_i32_e32 v199, 31, v198
	v_lshlrev_b64 v[198:199], 13, v[198:199]
	v_lshl_add_u64 v[198:199], s[12:13], 0, v[198:199]
	v_lshl_add_u64 v[200:201], v[198:199], 0, v[178:179]
	v_lshl_add_u64 v[198:199], v[198:199], 0, s[22:23]
	v_lshl_add_u64 v[182:183], v[198:199], 0, v[178:179]
	v_lshl_add_u64 v[204:205], v[198:199], 0, v[180:181]
	global_load_dwordx2 v[208:209], v[200:201], off
	global_load_dwordx2 v[210:211], v[182:183], off
	s_nop 0
	global_load_dwordx2 v[182:183], v[204:205], off
	s_waitcnt vmcnt(0)
	v_lshlrev_b32_e32 v204, 16, v186
	v_and_b32_e32 v205, 0xffff0000, v186
	v_lshlrev_b32_e32 v186, 16, v187
	v_lshlrev_b32_e32 v207, 16, v193
	v_and_b32_e32 v193, 0xffff0000, v193
	v_max_f32_e32 v193, v193, v193
	v_lshlrev_b32_e32 v216, 16, v194
	v_and_b32_e32 v194, 0xffff0000, v194
	v_lshlrev_b32_e32 v217, 16, v195
	v_and_b32_e32 v195, 0xffff0000, v195
	v_lshlrev_b32_e32 v219, 16, v197
	v_and_b32_e32 v220, 0xffff0000, v197
	v_max_f32_e32 v197, v207, v207
	v_max_f32_e32 v194, v194, v194
	v_max_f32_e32 v195, v195, v195
	v_max_f32_e32 v221, v219, v219
	v_max_f32_e32 v197, 0xda24260, v197
	v_max_f32_e32 v219, 0xda24260, v193
	v_lshlrev_b32_e32 v218, 16, v196
	v_max_f32_e32 v207, v216, v216
	v_max_f32_e32 v216, v217, v217
	v_max_f32_e32 v222, 0xda24260, v194
	v_max_f32_e32 v223, 0xda24260, v195
	v_rcp_f32_e32 v194, v197
	v_rcp_f32_e32 v195, v219
	v_max_f32_e32 v217, v218, v218
	v_max_f32_e32 v216, 0xda24260, v216
	v_max_f32_e32 v224, 0xda24260, v217
	v_rcp_f32_e32 v216, v216
	v_rcp_f32_e32 v217, v223
	v_and_b32_e32 v187, 0xffff0000, v187
	v_pk_mul_f32 v[186:187], v[194:195], v[186:187]
	v_lshlrev_b32_e32 v212, 16, v188
	v_and_b32_e32 v213, 0xffff0000, v188
	v_lshlrev_b32_e32 v188, 16, v189
	v_and_b32_e32 v189, 0xffff0000, v189
	v_lshlrev_b32_e32 v214, 16, v190
	v_and_b32_e32 v215, 0xffff0000, v190
	v_lshlrev_b32_e32 v190, 16, v192
	v_and_b32_e32 v192, 0xffff0000, v192
	v_pk_mul_f32 v[68:69], v[68:69], v[186:187]
	v_max_f32_e32 v187, v220, v220
	v_and_b32_e32 v196, 0xffff0000, v196
	v_max_f32_e32 v190, v190, v190
	v_max_f32_e32 v192, v192, v192
	v_pk_mul_f32 v[188:189], v[216:217], v[188:189]
	v_max_f32_e32 v186, 0xda24260, v221
	v_max_f32_e32 v187, 0xda24260, v187
	v_max_f32_e32 v196, v196, v196
	v_max_f32_e32 v190, 0xda24260, v190
	v_max_f32_e32 v218, 0xda24260, v192
	v_max_f32_e32 v207, 0xda24260, v207
	v_pk_mul_f32 v[64:65], v[64:65], v[188:189]
	v_rcp_f32_e32 v186, v186
	global_load_dwordx2 v[188:189], v[200:201], off offset:32
	v_rcp_f32_e32 v187, v187
	v_max_f32_e32 v225, 0xda24260, v196
	v_rcp_f32_e32 v192, v190
	v_rcp_f32_e32 v193, v218
	v_rcp_f32_e32 v196, v207
	v_rcp_f32_e32 v197, v222
	v_rcp_f32_e32 v218, v224
	v_rcp_f32_e32 v219, v225
	v_lshlrev_b32_e32 v190, 16, v191
	v_and_b32_e32 v191, 0xffff0000, v191
	v_pk_mul_f32 v[186:187], v[186:187], v[190:191]
	v_pk_mul_f32 v[192:193], v[192:193], v[204:205]
	v_pk_mul_f32 v[194:195], v[196:197], v[212:213]
	v_pk_mul_f32 v[60:61], v[60:61], v[186:187]
	v_lshlrev_b32_e32 v186, 16, v202
	v_and_b32_e32 v187, 0xffff0000, v202
	v_pk_mul_f32 v[66:67], v[66:67], v[192:193]
	v_pk_mul_f32 v[62:63], v[62:63], v[194:195]
	v_pk_mul_f32 v[192:193], v[218:219], v[214:215]
	v_lshlrev_b32_e32 v194, 16, v203
	v_max_f32_e32 v186, v186, v186
	v_max_f32_e32 v187, v187, v187
	v_pk_mul_f32 v[58:59], v[58:59], v[192:193]
	v_max_f32_e32 v186, 0xda24260, v186
	v_max_f32_e32 v187, 0xda24260, v187
	v_lshl_add_u64 v[190:191], v[198:199], 0, v[176:177]
	v_lshlrev_b32_e32 v192, 16, v146
	v_and_b32_e32 v193, 0xffff0000, v146
	v_max_f32_e32 v146, v194, v194
	v_and_b32_e32 v195, 0xffff0000, v203
	v_rcp_f32_e32 v186, v186
	v_rcp_f32_e32 v187, v187
	v_max_f32_e32 v146, 0xda24260, v146
	global_load_dwordx2 v[196:197], v[200:201], off offset:256
	v_rcp_f32_e32 v194, v146
	global_load_dwordx2 v[190:191], v[190:191], off
	v_max_f32_e32 v146, v195, v195
	v_max_f32_e32 v146, 0xda24260, v146
	v_rcp_f32_e32 v195, v146
	v_pk_mul_f32 v[186:187], v[186:187], v[192:193]
	v_lshlrev_b32_e32 v146, 16, v147
	v_pk_mul_f32 v[54:55], v[54:55], v[186:187]
	v_lshlrev_b32_e32 v186, 16, v210
	v_and_b32_e32 v187, 0xffff0000, v210
	v_and_b32_e32 v147, 0xffff0000, v147
	v_max_f32_e32 v186, v186, v186
	v_max_f32_e32 v187, v187, v187
	v_pk_mul_f32 v[146:147], v[194:195], v[146:147]
	v_max_f32_e32 v186, 0xda24260, v186
	v_max_f32_e32 v187, 0xda24260, v187
	v_pk_mul_f32 v[56:57], v[56:57], v[146:147]
	v_lshl_add_u64 v[146:147], v[198:199], 0, v[4:5]
	v_rcp_f32_e32 v186, v186
	v_rcp_f32_e32 v187, v187
	global_load_dwordx2 v[146:147], v[146:147], off
	v_lshlrev_b32_e32 v198, 16, v211
	v_and_b32_e32 v199, 0xffff0000, v211
	global_load_dwordx2 v[192:193], v[200:201], off offset:288
	v_max_f32_e32 v198, v198, v198
	v_max_f32_e32 v199, v199, v199
	v_lshlrev_b32_e32 v194, 16, v208
	v_and_b32_e32 v195, 0xffff0000, v208
	v_max_f32_e32 v198, 0xda24260, v198
	v_max_f32_e32 v199, 0xda24260, v199
	v_rcp_f32_e32 v198, v198
	v_rcp_f32_e32 v199, v199
	v_pk_mul_f32 v[186:187], v[186:187], v[194:195]
	v_lshlrev_b32_e32 v194, 16, v209
	v_pk_mul_f32 v[50:51], v[50:51], v[186:187]
	v_add_u32_e32 v186, s45, v3
	v_ashrrev_i32_e32 v187, 31, v186
	v_and_b32_e32 v195, 0xffff0000, v209
	v_lshlrev_b64 v[186:187], 13, v[186:187]
	v_pk_mul_f32 v[194:195], v[198:199], v[194:195]
	v_lshl_add_u64 v[186:187], s[12:13], 0, v[186:187]
	v_pk_mul_f32 v[52:53], v[52:53], v[194:195]
	v_lshl_add_u64 v[194:195], v[186:187], 0, s[22:23]
	v_lshl_add_u64 v[198:199], v[194:195], 0, v[178:179]
	global_load_dwordx2 v[198:199], v[198:199], off
	v_lshl_add_u64 v[186:187], v[186:187], 0, v[178:179]
	global_load_dwordx2 v[202:203], v[186:187], off
	v_lshlrev_b32_e32 v200, 16, v182
	v_and_b32_e32 v201, 0xffff0000, v182
	v_lshlrev_b32_e32 v204, 16, v183
	v_and_b32_e32 v205, 0xffff0000, v183
	v_max_f32_e32 v182, v200, v200
	v_max_f32_e32 v183, v201, v201
	s_waitcnt vmcnt(6)
	v_lshlrev_b32_e32 v200, 16, v188
	v_and_b32_e32 v201, 0xffff0000, v188
	v_max_f32_e32 v188, v204, v204
	v_max_f32_e32 v188, 0xda24260, v188
	v_rcp_f32_e32 v204, v188
	v_max_f32_e32 v188, v205, v205
	v_max_f32_e32 v182, 0xda24260, v182
	v_max_f32_e32 v183, 0xda24260, v183
	v_max_f32_e32 v188, 0xda24260, v188
	v_rcp_f32_e32 v182, v182
	v_rcp_f32_e32 v183, v183
	v_rcp_f32_e32 v205, v188
	v_lshlrev_b32_e32 v188, 16, v189
	v_and_b32_e32 v189, 0xffff0000, v189
	v_pk_mul_f32 v[182:183], v[182:183], v[200:201]
	v_pk_mul_f32 v[188:189], v[204:205], v[188:189]
	v_pk_mul_f32 v[46:47], v[46:47], v[182:183]
	v_pk_mul_f32 v[48:49], v[48:49], v[188:189]
	v_lshl_add_u64 v[182:183], v[194:195], 0, v[180:181]
	global_load_dwordx2 v[204:205], v[186:187], off offset:32
	s_waitcnt vmcnt(5)
	v_lshlrev_b32_e32 v200, 16, v191
	v_lshlrev_b32_e32 v188, 16, v190
	v_and_b32_e32 v189, 0xffff0000, v190
	v_and_b32_e32 v201, 0xffff0000, v191
	v_lshlrev_b32_e32 v190, 16, v196
	v_and_b32_e32 v191, 0xffff0000, v196
	v_max_f32_e32 v196, v200, v200
	v_max_f32_e32 v188, v188, v188
	v_max_f32_e32 v189, v189, v189
	v_max_f32_e32 v196, 0xda24260, v196
	v_max_f32_e32 v188, 0xda24260, v188
	v_max_f32_e32 v189, 0xda24260, v189
	v_rcp_f32_e32 v200, v196
	v_max_f32_e32 v196, v201, v201
	v_rcp_f32_e32 v188, v188
	v_rcp_f32_e32 v189, v189
	v_max_f32_e32 v196, 0xda24260, v196
	global_load_dwordx2 v[182:183], v[182:183], off
	v_rcp_f32_e32 v201, v196
	v_pk_mul_f32 v[188:189], v[188:189], v[190:191]
	v_lshlrev_b32_e32 v190, 16, v197
	v_and_b32_e32 v191, 0xffff0000, v197
	v_pk_mul_f32 v[190:191], v[200:201], v[190:191]
	s_waitcnt vmcnt(5)
	v_lshlrev_b32_e32 v196, 16, v147
	v_pk_mul_f32 v[44:45], v[44:45], v[190:191]
	v_pk_mul_f32 v[42:43], v[42:43], v[188:189]
	v_lshlrev_b32_e32 v188, 16, v146
	v_and_b32_e32 v189, 0xffff0000, v146
	s_waitcnt vmcnt(4)
	v_lshlrev_b32_e32 v190, 16, v192
	v_and_b32_e32 v191, 0xffff0000, v192
	v_max_f32_e32 v192, v196, v196
	v_and_b32_e32 v197, 0xffff0000, v147
	v_max_f32_e32 v146, v188, v188
	v_max_f32_e32 v147, v189, v189
	v_max_f32_e32 v192, 0xda24260, v192
	v_max_f32_e32 v146, 0xda24260, v146
	v_max_f32_e32 v147, 0xda24260, v147
	v_rcp_f32_e32 v196, v192
	v_max_f32_e32 v192, v197, v197
	v_rcp_f32_e32 v146, v146
	v_lshl_add_u64 v[188:189], v[194:195], 0, v[176:177]
	v_rcp_f32_e32 v147, v147
	v_max_f32_e32 v192, 0xda24260, v192
	global_load_dwordx2 v[188:189], v[188:189], off
	v_rcp_f32_e32 v197, v192
	global_load_dwordx2 v[200:201], v[186:187], off offset:256
	v_pk_mul_f32 v[146:147], v[146:147], v[190:191]
	v_lshlrev_b32_e32 v190, 16, v193
	v_and_b32_e32 v191, 0xffff0000, v193
	v_pk_mul_f32 v[190:191], v[196:197], v[190:191]
	global_load_dwordx2 v[186:187], v[186:187], off offset:288
	v_pk_mul_f32 v[40:41], v[40:41], v[190:191]
	s_waitcnt vmcnt(6)
	v_lshlrev_b32_e32 v190, 16, v198
	v_and_b32_e32 v191, 0xffff0000, v198
	v_max_f32_e32 v190, v190, v190
	v_max_f32_e32 v191, v191, v191
	v_max_f32_e32 v190, 0xda24260, v190
	v_max_f32_e32 v191, 0xda24260, v191
	v_pk_mul_f32 v[38:39], v[38:39], v[146:147]
	v_lshl_add_u64 v[146:147], v[194:195], 0, v[4:5]
	v_rcp_f32_e32 v190, v190
	v_rcp_f32_e32 v191, v191
	global_load_dwordx2 v[146:147], v[146:147], off
	v_lshlrev_b32_e32 v194, 16, v199
	v_and_b32_e32 v195, 0xffff0000, v199
	v_max_f32_e32 v194, v194, v194
	v_max_f32_e32 v195, v195, v195
	s_waitcnt vmcnt(6)
	v_lshlrev_b32_e32 v192, 16, v202
	v_and_b32_e32 v193, 0xffff0000, v202
	v_max_f32_e32 v194, 0xda24260, v194
	v_max_f32_e32 v195, 0xda24260, v195
	v_rcp_f32_e32 v194, v194
	v_rcp_f32_e32 v195, v195
	v_pk_mul_f32 v[190:191], v[190:191], v[192:193]
	v_lshlrev_b32_e32 v192, 16, v203
	v_pk_mul_f32 v[34:35], v[34:35], v[190:191]
	v_add_u32_e32 v190, s86, v3
	v_ashrrev_i32_e32 v191, 31, v190
	v_and_b32_e32 v193, 0xffff0000, v203
	v_lshlrev_b64 v[190:191], 13, v[190:191]
	v_pk_mul_f32 v[192:193], v[194:195], v[192:193]
	v_lshl_add_u64 v[190:191], s[12:13], 0, v[190:191]
	v_pk_mul_f32 v[36:37], v[36:37], v[192:193]
	v_lshl_add_u64 v[192:193], v[190:191], 0, s[22:23]
	v_lshl_add_u64 v[194:195], v[192:193], 0, v[178:179]
	global_load_dwordx2 v[194:195], v[194:195], off
	v_lshl_add_u64 v[190:191], v[190:191], 0, v[178:179]
	global_load_dwordx2 v[198:199], v[190:191], off
	s_waitcnt vmcnt(6)
	v_lshlrev_b32_e32 v196, 16, v182
	v_and_b32_e32 v197, 0xffff0000, v182
	v_lshlrev_b32_e32 v202, 16, v183
	v_and_b32_e32 v203, 0xffff0000, v183
	v_max_f32_e32 v182, v196, v196
	v_max_f32_e32 v183, v197, v197
	v_max_f32_e32 v182, 0xda24260, v182
	v_max_f32_e32 v183, 0xda24260, v183
	v_max_f32_e32 v202, v202, v202
	v_max_f32_e32 v203, v203, v203
	v_rcp_f32_e32 v182, v182
	v_rcp_f32_e32 v183, v183
	v_max_f32_e32 v202, 0xda24260, v202
	v_max_f32_e32 v203, 0xda24260, v203
	v_rcp_f32_e32 v202, v202
	v_rcp_f32_e32 v203, v203
	v_lshlrev_b32_e32 v196, 16, v204
	v_and_b32_e32 v197, 0xffff0000, v204
	v_pk_mul_f32 v[182:183], v[182:183], v[196:197]
	v_lshlrev_b32_e32 v196, 16, v205
	v_and_b32_e32 v197, 0xffff0000, v205
	v_pk_mul_f32 v[196:197], v[202:203], v[196:197]
	v_pk_mul_f32 v[30:31], v[30:31], v[182:183]
	v_pk_mul_f32 v[32:33], v[32:33], v[196:197]
	v_lshl_add_u64 v[182:183], v[192:193], 0, v[180:181]
	global_load_dwordx2 v[182:183], v[182:183], off
	s_waitcnt vmcnt(6)
	v_lshlrev_b32_e32 v196, 16, v188
	v_and_b32_e32 v197, 0xffff0000, v188
	v_lshlrev_b32_e32 v202, 16, v189
	v_and_b32_e32 v203, 0xffff0000, v189
	v_max_f32_e32 v188, v196, v196
	v_max_f32_e32 v189, v197, v197
	s_waitcnt vmcnt(5)
	v_lshlrev_b32_e32 v196, 16, v200
	v_and_b32_e32 v197, 0xffff0000, v200
	v_max_f32_e32 v200, v202, v202
	v_max_f32_e32 v200, 0xda24260, v200
	v_max_f32_e32 v188, 0xda24260, v188
	v_max_f32_e32 v189, 0xda24260, v189
	v_rcp_f32_e32 v202, v200
	v_max_f32_e32 v200, v203, v203
	v_rcp_f32_e32 v188, v188
	v_rcp_f32_e32 v189, v189
	v_max_f32_e32 v200, 0xda24260, v200
	v_rcp_f32_e32 v203, v200
	global_load_dwordx2 v[204:205], v[190:191], off offset:32
	v_pk_mul_f32 v[188:189], v[188:189], v[196:197]
	v_lshlrev_b32_e32 v196, 16, v201
	v_and_b32_e32 v197, 0xffff0000, v201
	v_pk_mul_f32 v[196:197], v[202:203], v[196:197]
	s_waitcnt vmcnt(4)
	v_lshlrev_b32_e32 v200, 16, v147
	v_pk_mul_f32 v[28:29], v[28:29], v[196:197]
	v_lshlrev_b32_e32 v196, 16, v186
	v_and_b32_e32 v197, 0xffff0000, v186
	v_max_f32_e32 v186, v200, v200
	v_and_b32_e32 v201, 0xffff0000, v147
	v_max_f32_e32 v186, 0xda24260, v186
	v_rcp_f32_e32 v200, v186
	v_max_f32_e32 v186, v201, v201
	v_pk_mul_f32 v[26:27], v[26:27], v[188:189]
	v_lshlrev_b32_e32 v188, 16, v146
	v_and_b32_e32 v189, 0xffff0000, v146
	v_max_f32_e32 v186, 0xda24260, v186
	v_max_f32_e32 v146, v188, v188
	v_max_f32_e32 v147, v189, v189
	v_lshl_add_u64 v[188:189], v[192:193], 0, v[176:177]
	v_rcp_f32_e32 v201, v186
	global_load_dwordx2 v[188:189], v[188:189], off
	v_max_f32_e32 v146, 0xda24260, v146
	v_max_f32_e32 v147, 0xda24260, v147
	v_rcp_f32_e32 v146, v146
	v_rcp_f32_e32 v147, v147
	v_lshlrev_b32_e32 v186, 16, v187
	v_and_b32_e32 v187, 0xffff0000, v187
	v_pk_mul_f32 v[186:187], v[200:201], v[186:187]
	global_load_dwordx2 v[202:203], v[190:191], off offset:256
	v_pk_mul_f32 v[24:25], v[24:25], v[186:187]
	s_waitcnt vmcnt(5)
	v_lshlrev_b32_e32 v186, 16, v194
	v_and_b32_e32 v187, 0xffff0000, v194
	v_max_f32_e32 v186, v186, v186
	v_max_f32_e32 v187, v187, v187
	v_pk_mul_f32 v[146:147], v[146:147], v[196:197]
	v_max_f32_e32 v186, 0xda24260, v186
	v_max_f32_e32 v187, 0xda24260, v187
	v_pk_mul_f32 v[22:23], v[22:23], v[146:147]
	v_lshl_add_u64 v[146:147], v[192:193], 0, v[4:5]
	v_rcp_f32_e32 v186, v186
	v_rcp_f32_e32 v187, v187
	global_load_dwordx2 v[146:147], v[146:147], off
	v_lshlrev_b32_e32 v194, 16, v195
	v_and_b32_e32 v195, 0xffff0000, v195
	global_load_dwordx2 v[190:191], v[190:191], off offset:288
	v_max_f32_e32 v194, v194, v194
	v_max_f32_e32 v195, v195, v195
	s_waitcnt vmcnt(6)
	v_lshlrev_b32_e32 v192, 16, v198
	v_and_b32_e32 v193, 0xffff0000, v198
	v_max_f32_e32 v194, 0xda24260, v194
	v_max_f32_e32 v195, 0xda24260, v195
	v_rcp_f32_e32 v194, v194
	v_rcp_f32_e32 v195, v195
	v_pk_mul_f32 v[186:187], v[186:187], v[192:193]
	v_lshlrev_b32_e32 v192, 16, v199
	v_pk_mul_f32 v[18:19], v[18:19], v[186:187]
	v_add_u32_e32 v186, s87, v3
	v_ashrrev_i32_e32 v187, 31, v186
	v_and_b32_e32 v193, 0xffff0000, v199
	v_lshlrev_b64 v[186:187], 13, v[186:187]
	v_pk_mul_f32 v[192:193], v[194:195], v[192:193]
	v_lshl_add_u64 v[186:187], s[12:13], 0, v[186:187]
	v_pk_mul_f32 v[20:21], v[20:21], v[192:193]
	v_lshl_add_u64 v[192:193], v[186:187], 0, s[22:23]
	v_lshl_add_u64 v[194:195], v[192:193], 0, v[178:179]
	global_load_dwordx2 v[194:195], v[194:195], off
	v_lshl_add_u64 v[186:187], v[186:187], 0, v[178:179]
	global_load_dwordx2 v[198:199], v[186:187], off
	s_waitcnt vmcnt(7)
	v_lshlrev_b32_e32 v196, 16, v182
	v_and_b32_e32 v197, 0xffff0000, v182
	v_lshlrev_b32_e32 v200, 16, v183
	v_and_b32_e32 v201, 0xffff0000, v183
	v_max_f32_e32 v182, v196, v196
	v_max_f32_e32 v183, v197, v197
	v_max_f32_e32 v182, 0xda24260, v182
	v_max_f32_e32 v183, 0xda24260, v183
	v_max_f32_e32 v200, v200, v200
	v_max_f32_e32 v201, v201, v201
	v_rcp_f32_e32 v182, v182
	v_rcp_f32_e32 v183, v183
	v_max_f32_e32 v200, 0xda24260, v200
	v_max_f32_e32 v201, 0xda24260, v201
	v_rcp_f32_e32 v200, v200
	v_rcp_f32_e32 v201, v201
	s_waitcnt vmcnt(6)
	v_lshlrev_b32_e32 v196, 16, v204
	v_and_b32_e32 v197, 0xffff0000, v204
	v_pk_mul_f32 v[182:183], v[182:183], v[196:197]
	v_lshlrev_b32_e32 v196, 16, v205
	v_and_b32_e32 v197, 0xffff0000, v205
	v_pk_mul_f32 v[196:197], v[200:201], v[196:197]
	v_pk_mul_f32 v[14:15], v[14:15], v[182:183]
	v_pk_mul_f32 v[16:17], v[16:17], v[196:197]
	v_lshl_add_u64 v[182:183], v[192:193], 0, v[180:181]
	global_load_dwordx2 v[204:205], v[186:187], off offset:32
	s_waitcnt vmcnt(6)
	v_lshlrev_b32_e32 v196, 16, v188
	v_and_b32_e32 v197, 0xffff0000, v188
	v_lshlrev_b32_e32 v200, 16, v189
	v_and_b32_e32 v201, 0xffff0000, v189
	v_max_f32_e32 v188, v196, v196
	v_max_f32_e32 v189, v197, v197
	v_max_f32_e32 v188, 0xda24260, v188
	v_max_f32_e32 v189, 0xda24260, v189
	v_max_f32_e32 v200, v200, v200
	v_max_f32_e32 v201, v201, v201
	v_rcp_f32_e32 v188, v188
	v_rcp_f32_e32 v189, v189
	v_max_f32_e32 v200, 0xda24260, v200
	v_max_f32_e32 v201, 0xda24260, v201
	v_rcp_f32_e32 v200, v200
	v_rcp_f32_e32 v201, v201
	global_load_dwordx2 v[182:183], v[182:183], off
	s_waitcnt vmcnt(6)
	v_lshlrev_b32_e32 v196, 16, v202
	v_and_b32_e32 v197, 0xffff0000, v202
	v_pk_mul_f32 v[188:189], v[188:189], v[196:197]
	v_lshlrev_b32_e32 v196, 16, v203
	v_and_b32_e32 v197, 0xffff0000, v203
	v_pk_mul_f32 v[196:197], v[200:201], v[196:197]
	s_waitcnt vmcnt(5)
	v_lshlrev_b32_e32 v200, 16, v147
	v_pk_mul_f32 v[12:13], v[12:13], v[196:197]
	s_waitcnt vmcnt(4)
	v_lshlrev_b32_e32 v196, 16, v190
	v_and_b32_e32 v197, 0xffff0000, v190
	v_max_f32_e32 v190, v200, v200
	v_and_b32_e32 v201, 0xffff0000, v147
	v_max_f32_e32 v190, 0xda24260, v190
	v_rcp_f32_e32 v200, v190
	v_max_f32_e32 v190, v201, v201
	v_pk_mul_f32 v[10:11], v[10:11], v[188:189]
	v_lshlrev_b32_e32 v188, 16, v146
	v_and_b32_e32 v189, 0xffff0000, v146
	v_max_f32_e32 v190, 0xda24260, v190
	v_max_f32_e32 v146, v188, v188
	v_max_f32_e32 v147, v189, v189
	v_lshl_add_u64 v[188:189], v[192:193], 0, v[176:177]
	v_rcp_f32_e32 v201, v190
	global_load_dwordx2 v[188:189], v[188:189], off
	v_max_f32_e32 v146, 0xda24260, v146
	v_max_f32_e32 v147, 0xda24260, v147
	v_rcp_f32_e32 v146, v146
	v_rcp_f32_e32 v147, v147
	v_lshlrev_b32_e32 v190, 16, v191
	v_and_b32_e32 v191, 0xffff0000, v191
	v_pk_mul_f32 v[190:191], v[200:201], v[190:191]
	global_load_dwordx2 v[202:203], v[186:187], off offset:256
	v_pk_mul_f32 v[8:9], v[8:9], v[190:191]
	global_load_dwordx2 v[186:187], v[186:187], off offset:288
	s_waitcnt vmcnt(6)
	v_lshlrev_b32_e32 v190, 16, v194
	v_and_b32_e32 v191, 0xffff0000, v194
	v_max_f32_e32 v190, v190, v190
	v_max_f32_e32 v191, v191, v191
	v_pk_mul_f32 v[146:147], v[146:147], v[196:197]
	v_max_f32_e32 v190, 0xda24260, v190
	v_max_f32_e32 v191, 0xda24260, v191
	v_pk_mul_f32 v[6:7], v[6:7], v[146:147]
	v_lshl_add_u64 v[146:147], v[192:193], 0, v[4:5]
	v_rcp_f32_e32 v190, v190
	v_rcp_f32_e32 v191, v191
	global_load_dwordx2 v[146:147], v[146:147], off
	v_lshlrev_b32_e32 v194, 16, v195
	v_and_b32_e32 v195, 0xffff0000, v195
	v_max_f32_e32 v194, v194, v194
	v_max_f32_e32 v195, v195, v195
	s_waitcnt vmcnt(6)
	v_lshlrev_b32_e32 v192, 16, v198
	v_and_b32_e32 v193, 0xffff0000, v198
	v_max_f32_e32 v194, 0xda24260, v194
	v_max_f32_e32 v195, 0xda24260, v195
	v_rcp_f32_e32 v194, v194
	v_rcp_f32_e32 v195, v195
	v_pk_mul_f32 v[190:191], v[190:191], v[192:193]
	v_lshlrev_b32_e32 v192, 16, v199
	v_pk_mul_f32 v[130:131], v[130:131], v[190:191]
	v_add_u32_e32 v190, s88, v3
	v_ashrrev_i32_e32 v191, 31, v190
	v_and_b32_e32 v193, 0xffff0000, v199
	v_lshlrev_b64 v[190:191], 13, v[190:191]
	v_pk_mul_f32 v[192:193], v[194:195], v[192:193]
	v_lshl_add_u64 v[190:191], s[12:13], 0, v[190:191]
	v_pk_mul_f32 v[132:133], v[132:133], v[192:193]
	v_lshl_add_u64 v[192:193], v[190:191], 0, s[22:23]
	v_lshl_add_u64 v[194:195], v[192:193], 0, v[178:179]
	global_load_dwordx2 v[194:195], v[194:195], off
	v_lshl_add_u64 v[190:191], v[190:191], 0, v[178:179]
	global_load_dwordx2 v[198:199], v[190:191], off
	s_waitcnt vmcnt(6)
	v_lshlrev_b32_e32 v196, 16, v182
	v_and_b32_e32 v197, 0xffff0000, v182
	v_lshlrev_b32_e32 v200, 16, v183
	v_and_b32_e32 v201, 0xffff0000, v183
	v_max_f32_e32 v182, v196, v196
	v_max_f32_e32 v183, v197, v197
	v_max_f32_e32 v182, 0xda24260, v182
	v_max_f32_e32 v183, 0xda24260, v183
	v_max_f32_e32 v200, v200, v200
	v_max_f32_e32 v201, v201, v201
	v_rcp_f32_e32 v182, v182
	v_rcp_f32_e32 v183, v183
	v_max_f32_e32 v200, 0xda24260, v200
	v_max_f32_e32 v201, 0xda24260, v201
	v_rcp_f32_e32 v200, v200
	v_rcp_f32_e32 v201, v201
	v_lshlrev_b32_e32 v196, 16, v204
	v_and_b32_e32 v197, 0xffff0000, v204
	v_pk_mul_f32 v[182:183], v[182:183], v[196:197]
	v_lshlrev_b32_e32 v196, 16, v205
	v_and_b32_e32 v197, 0xffff0000, v205
	v_pk_mul_f32 v[196:197], v[200:201], v[196:197]
	v_pk_mul_f32 v[126:127], v[126:127], v[182:183]
	v_pk_mul_f32 v[128:129], v[128:129], v[196:197]
	v_lshl_add_u64 v[182:183], v[192:193], 0, v[180:181]
	s_waitcnt vmcnt(5)
	v_lshlrev_b32_e32 v196, 16, v188
	v_and_b32_e32 v197, 0xffff0000, v188
	global_load_dwordx2 v[182:183], v[182:183], off
	v_lshlrev_b32_e32 v200, 16, v189
	v_and_b32_e32 v201, 0xffff0000, v189
	v_max_f32_e32 v188, v196, v196
	v_max_f32_e32 v189, v197, v197
	v_max_f32_e32 v188, 0xda24260, v188
	v_max_f32_e32 v189, 0xda24260, v189
	v_max_f32_e32 v200, v200, v200
	v_max_f32_e32 v201, v201, v201
	v_rcp_f32_e32 v188, v188
	v_rcp_f32_e32 v189, v189
	v_max_f32_e32 v200, 0xda24260, v200
	v_max_f32_e32 v201, 0xda24260, v201
	v_rcp_f32_e32 v200, v200
	v_rcp_f32_e32 v201, v201
	s_waitcnt vmcnt(5)
	v_lshlrev_b32_e32 v196, 16, v202
	v_and_b32_e32 v197, 0xffff0000, v202
	global_load_dwordx2 v[204:205], v[190:191], off offset:32
	v_pk_mul_f32 v[188:189], v[188:189], v[196:197]
	v_lshlrev_b32_e32 v196, 16, v203
	v_and_b32_e32 v197, 0xffff0000, v203
	v_pk_mul_f32 v[196:197], v[200:201], v[196:197]
	v_pk_mul_f32 v[122:123], v[122:123], v[188:189]
	s_waitcnt vmcnt(4)
	v_lshlrev_b32_e32 v188, 16, v146
	v_and_b32_e32 v189, 0xffff0000, v146
	v_lshlrev_b32_e32 v200, 16, v147
	v_pk_mul_f32 v[124:125], v[124:125], v[196:197]
	v_and_b32_e32 v201, 0xffff0000, v147
	v_max_f32_e32 v146, v188, v188
	v_max_f32_e32 v147, v189, v189
	v_lshl_add_u64 v[188:189], v[192:193], 0, v[176:177]
	v_lshlrev_b32_e32 v196, 16, v186
	v_and_b32_e32 v197, 0xffff0000, v186
	v_max_f32_e32 v186, v200, v200
	global_load_dwordx2 v[188:189], v[188:189], off
	v_max_f32_e32 v186, 0xda24260, v186
	v_max_f32_e32 v146, 0xda24260, v146
	v_max_f32_e32 v147, 0xda24260, v147
	v_rcp_f32_e32 v200, v186
	v_max_f32_e32 v186, v201, v201
	v_rcp_f32_e32 v146, v146
	v_rcp_f32_e32 v147, v147
	v_max_f32_e32 v186, 0xda24260, v186
	v_rcp_f32_e32 v201, v186
	global_load_dwordx2 v[202:203], v[190:191], off offset:256
	v_pk_mul_f32 v[146:147], v[146:147], v[196:197]
	v_lshlrev_b32_e32 v186, 16, v187
	v_and_b32_e32 v187, 0xffff0000, v187
	v_pk_mul_f32 v[186:187], v[200:201], v[186:187]
	v_pk_mul_f32 v[118:119], v[118:119], v[146:147]
	v_lshl_add_u64 v[146:147], v[192:193], 0, v[4:5]
	v_pk_mul_f32 v[120:121], v[120:121], v[186:187]
	global_load_dwordx2 v[146:147], v[146:147], off
	s_waitcnt vmcnt(6)
	v_lshlrev_b32_e32 v186, 16, v194
	v_and_b32_e32 v187, 0xffff0000, v194
	v_max_f32_e32 v186, v186, v186
	v_max_f32_e32 v187, v187, v187
	v_max_f32_e32 v186, 0xda24260, v186
	v_max_f32_e32 v187, 0xda24260, v187
	v_rcp_f32_e32 v186, v186
	v_rcp_f32_e32 v187, v187
	v_lshlrev_b32_e32 v194, 16, v195
	v_and_b32_e32 v195, 0xffff0000, v195
	v_max_f32_e32 v194, v194, v194
	v_max_f32_e32 v195, v195, v195
	global_load_dwordx2 v[190:191], v[190:191], off offset:288
	s_waitcnt vmcnt(6)
	v_lshlrev_b32_e32 v192, 16, v198
	v_and_b32_e32 v193, 0xffff0000, v198
	v_max_f32_e32 v194, 0xda24260, v194
	v_max_f32_e32 v195, 0xda24260, v195
	v_rcp_f32_e32 v194, v194
	v_rcp_f32_e32 v195, v195
	v_pk_mul_f32 v[186:187], v[186:187], v[192:193]
	v_lshlrev_b32_e32 v192, 16, v199
	v_pk_mul_f32 v[114:115], v[114:115], v[186:187]
	v_add_u32_e32 v186, s89, v3
	v_ashrrev_i32_e32 v187, 31, v186
	v_and_b32_e32 v193, 0xffff0000, v199
	v_lshlrev_b64 v[186:187], 13, v[186:187]
	v_pk_mul_f32 v[192:193], v[194:195], v[192:193]
	v_lshl_add_u64 v[186:187], s[12:13], 0, v[186:187]
	v_pk_mul_f32 v[116:117], v[116:117], v[192:193]
	v_lshl_add_u64 v[192:193], v[186:187], 0, s[22:23]
	v_lshl_add_u64 v[194:195], v[192:193], 0, v[178:179]
	global_load_dwordx2 v[194:195], v[194:195], off
	v_lshl_add_u64 v[186:187], v[186:187], 0, v[178:179]
	global_load_dwordx2 v[198:199], v[186:187], off
	s_waitcnt vmcnt(7)
	v_lshlrev_b32_e32 v196, 16, v182
	v_and_b32_e32 v197, 0xffff0000, v182
	v_lshlrev_b32_e32 v200, 16, v183
	v_and_b32_e32 v201, 0xffff0000, v183
	v_max_f32_e32 v182, v196, v196
	v_max_f32_e32 v183, v197, v197
	v_max_f32_e32 v182, 0xda24260, v182
	v_max_f32_e32 v183, 0xda24260, v183
	v_max_f32_e32 v200, v200, v200
	v_max_f32_e32 v201, v201, v201
	v_rcp_f32_e32 v182, v182
	v_rcp_f32_e32 v183, v183
	v_max_f32_e32 v200, 0xda24260, v200
	v_max_f32_e32 v201, 0xda24260, v201
	v_rcp_f32_e32 v200, v200
	v_rcp_f32_e32 v201, v201
	s_waitcnt vmcnt(6)
	v_lshlrev_b32_e32 v196, 16, v204
	v_and_b32_e32 v197, 0xffff0000, v204
	v_pk_mul_f32 v[182:183], v[182:183], v[196:197]
	v_lshlrev_b32_e32 v196, 16, v205
	v_and_b32_e32 v197, 0xffff0000, v205
	v_pk_mul_f32 v[196:197], v[200:201], v[196:197]
	v_pk_mul_f32 v[110:111], v[110:111], v[182:183]
	v_lshl_add_u64 v[182:183], v[192:193], 0, v[180:181]
	v_pk_mul_f32 v[112:113], v[112:113], v[196:197]
	global_load_dwordx2 v[196:197], v[182:183], off
	global_load_dwordx2 v[204:205], v[186:187], off offset:32
	s_waitcnt vmcnt(7)
	v_lshlrev_b32_e32 v182, 16, v188
	v_and_b32_e32 v183, 0xffff0000, v188
	v_max_f32_e32 v182, v182, v182
	v_max_f32_e32 v183, v183, v183
	v_max_f32_e32 v182, 0xda24260, v182
	v_max_f32_e32 v183, 0xda24260, v183
	v_lshlrev_b32_e32 v200, 16, v189
	v_and_b32_e32 v201, 0xffff0000, v189
	v_rcp_f32_e32 v182, v182
	v_rcp_f32_e32 v183, v183
	v_max_f32_e32 v200, v200, v200
	v_max_f32_e32 v201, v201, v201
	v_max_f32_e32 v200, 0xda24260, v200
	v_max_f32_e32 v201, 0xda24260, v201
	s_waitcnt vmcnt(6)
	v_lshlrev_b32_e32 v188, 16, v202
	v_and_b32_e32 v189, 0xffff0000, v202
	v_rcp_f32_e32 v200, v200
	v_rcp_f32_e32 v201, v201
	v_pk_mul_f32 v[182:183], v[182:183], v[188:189]
	v_lshlrev_b32_e32 v188, 16, v203
	v_pk_mul_f32 v[106:107], v[106:107], v[182:183]
	s_waitcnt vmcnt(5)
	v_lshlrev_b32_e32 v182, 16, v146
	v_and_b32_e32 v146, 0xffff0000, v146
	v_and_b32_e32 v189, 0xffff0000, v203
	v_max_f32_e32 v182, v182, v182
	v_max_f32_e32 v146, v146, v146
	v_pk_mul_f32 v[188:189], v[200:201], v[188:189]
	v_max_f32_e32 v182, 0xda24260, v182
	v_max_f32_e32 v146, 0xda24260, v146
	v_pk_mul_f32 v[108:109], v[108:109], v[188:189]
	v_rcp_f32_e32 v182, v182
	v_rcp_f32_e32 v183, v146
	v_lshl_add_u64 v[188:189], v[192:193], 0, v[176:177]
	global_load_dwordx2 v[188:189], v[188:189], off
	v_lshlrev_b32_e32 v200, 16, v147
	v_and_b32_e32 v201, 0xffff0000, v147
	s_waitcnt vmcnt(5)
	v_lshlrev_b32_e32 v146, 16, v190
	v_and_b32_e32 v147, 0xffff0000, v190
	v_pk_mul_f32 v[146:147], v[182:183], v[146:147]
	v_max_f32_e32 v182, v200, v200
	v_max_f32_e32 v183, v201, v201
	v_max_f32_e32 v182, 0xda24260, v182
	v_max_f32_e32 v183, 0xda24260, v183
	v_rcp_f32_e32 v182, v182
	v_rcp_f32_e32 v183, v183
	global_load_dwordx2 v[200:201], v[186:187], off offset:256
	v_lshlrev_b32_e32 v190, 16, v191
	v_and_b32_e32 v191, 0xffff0000, v191
	v_pk_mul_f32 v[182:183], v[182:183], v[190:191]
	v_pk_mul_f32 v[102:103], v[102:103], v[146:147]
	v_pk_mul_f32 v[104:105], v[104:105], v[182:183]
	s_waitcnt vmcnt(5)
	v_lshlrev_b32_e32 v182, 16, v194
	v_max_f32_e32 v182, v182, v182
	v_and_b32_e32 v183, 0xffff0000, v194
	v_max_f32_e32 v182, 0xda24260, v182
	v_rcp_f32_e32 v190, v182
	v_max_f32_e32 v182, v183, v183
	v_lshl_add_u64 v[146:147], v[192:193], 0, v[4:5]
	v_max_f32_e32 v182, 0xda24260, v182
	v_rcp_f32_e32 v191, v182
	global_load_dwordx2 v[182:183], v[186:187], off offset:288
	v_lshlrev_b32_e32 v192, 16, v195
	global_load_dwordx2 v[146:147], v[146:147], off
	v_and_b32_e32 v193, 0xffff0000, v195
	v_max_f32_e32 v192, v192, v192
	v_max_f32_e32 v193, v193, v193
	s_waitcnt vmcnt(6)
	v_lshlrev_b32_e32 v186, 16, v198
	v_and_b32_e32 v187, 0xffff0000, v198
	v_max_f32_e32 v192, 0xda24260, v192
	v_max_f32_e32 v193, 0xda24260, v193
	v_rcp_f32_e32 v192, v192
	v_rcp_f32_e32 v193, v193
	v_pk_mul_f32 v[186:187], v[190:191], v[186:187]
	v_lshlrev_b32_e32 v190, 16, v199
	v_pk_mul_f32 v[98:99], v[98:99], v[186:187]
	v_add_u32_e32 v186, s96, v3
	v_ashrrev_i32_e32 v187, 31, v186
	v_and_b32_e32 v191, 0xffff0000, v199
	v_lshlrev_b64 v[186:187], 13, v[186:187]
	v_pk_mul_f32 v[190:191], v[192:193], v[190:191]
	v_lshl_add_u64 v[186:187], s[12:13], 0, v[186:187]
	v_pk_mul_f32 v[100:101], v[100:101], v[190:191]
	v_lshl_add_u64 v[190:191], v[186:187], 0, s[22:23]
	v_lshl_add_u64 v[192:193], v[190:191], 0, v[178:179]
	global_load_dwordx2 v[192:193], v[192:193], off
	v_lshl_add_u64 v[178:179], v[186:187], 0, v[178:179]
	v_lshl_add_u64 v[180:181], v[190:191], 0, v[180:181]
	global_load_dwordx2 v[186:187], v[178:179], off
	s_waitcnt vmcnt(7)
	v_lshlrev_b32_e32 v194, 16, v196
	global_load_dwordx2 v[180:181], v[180:181], off
	v_and_b32_e32 v195, 0xffff0000, v196
	v_lshlrev_b32_e32 v198, 16, v197
	v_and_b32_e32 v3, 0xffff0000, v197
	v_max_f32_e32 v194, v194, v194
	v_max_f32_e32 v195, v195, v195
	v_max_f32_e32 v194, 0xda24260, v194
	v_max_f32_e32 v195, 0xda24260, v195
	v_max_f32_e32 v198, v198, v198
	v_max_f32_e32 v3, v3, v3
	v_rcp_f32_e32 v194, v194
	v_rcp_f32_e32 v195, v195
	v_max_f32_e32 v198, 0xda24260, v198
	v_max_f32_e32 v3, 0xda24260, v3
	v_rcp_f32_e32 v198, v198
	v_rcp_f32_e32 v199, v3
	s_waitcnt vmcnt(7)
	v_lshlrev_b32_e32 v196, 16, v204
	v_and_b32_e32 v197, 0xffff0000, v204
	v_pk_mul_f32 v[194:195], v[194:195], v[196:197]
	v_lshlrev_b32_e32 v196, 16, v205
	v_and_b32_e32 v197, 0xffff0000, v205
	v_pk_mul_f32 v[196:197], v[198:199], v[196:197]
	v_lshl_add_u64 v[176:177], v[190:191], 0, v[176:177]
	s_waitcnt vmcnt(6)
	v_lshlrev_b32_e32 v3, 16, v188
	v_max_f32_e32 v3, v3, v3
	v_and_b32_e32 v188, 0xffff0000, v188
	v_max_f32_e32 v3, 0xda24260, v3
	v_pk_mul_f32 v[96:97], v[96:97], v[196:197]
	v_pk_mul_f32 v[94:95], v[94:95], v[194:195]
	v_rcp_f32_e32 v194, v3
	v_max_f32_e32 v3, v188, v188
	global_load_dwordx2 v[196:197], v[178:179], off offset:32
	v_max_f32_e32 v3, 0xda24260, v3
	global_load_dwordx2 v[176:177], v[176:177], off
	v_rcp_f32_e32 v195, v3
	v_lshlrev_b32_e32 v198, 16, v189
	v_and_b32_e32 v3, 0xffff0000, v189
	s_waitcnt vmcnt(7)
	v_lshlrev_b32_e32 v188, 16, v200
	v_and_b32_e32 v189, 0xffff0000, v200
	v_pk_mul_f32 v[188:189], v[194:195], v[188:189]
	v_max_f32_e32 v194, v198, v198
	v_max_f32_e32 v3, v3, v3
	v_max_f32_e32 v194, 0xda24260, v194
	v_max_f32_e32 v3, 0xda24260, v3
	v_rcp_f32_e32 v194, v194
	v_rcp_f32_e32 v195, v3
	v_lshlrev_b32_e32 v198, 16, v201
	v_and_b32_e32 v199, 0xffff0000, v201
	v_lshl_add_u64 v[4:5], v[190:191], 0, v[4:5]
	v_pk_mul_f32 v[194:195], v[194:195], v[198:199]
	v_pk_mul_f32 v[90:91], v[90:91], v[188:189]
	global_load_dwordx2 v[4:5], v[4:5], off
	s_waitcnt vmcnt(6)
	v_lshlrev_b32_e32 v3, 16, v146
	v_and_b32_e32 v189, 0xffff0000, v146
	v_lshlrev_b32_e32 v198, 16, v147
	v_and_b32_e32 v199, 0xffff0000, v147
	global_load_dwordx2 v[146:147], v[178:179], off offset:256
	v_max_f32_e32 v3, v3, v3
	global_load_dwordx2 v[178:179], v[178:179], off offset:288
	v_max_f32_e32 v3, 0xda24260, v3
	v_rcp_f32_e32 v188, v3
	v_max_f32_e32 v3, v189, v189
	v_max_f32_e32 v3, 0xda24260, v3
	v_rcp_f32_e32 v189, v3
	v_max_f32_e32 v3, v198, v198
	v_max_f32_e32 v3, 0xda24260, v3
	v_rcp_f32_e32 v198, v3
	v_max_f32_e32 v3, v199, v199
	v_max_f32_e32 v3, 0xda24260, v3
	v_rcp_f32_e32 v199, v3
	v_pk_mul_f32 v[92:93], v[92:93], v[194:195]
	v_lshlrev_b32_e32 v194, 16, v182
	v_and_b32_e32 v195, 0xffff0000, v182
	v_lshlrev_b32_e32 v182, 16, v183
	v_and_b32_e32 v183, 0xffff0000, v183
	s_waitcnt vmcnt(7)
	v_lshlrev_b32_e32 v3, 16, v192
	v_pk_mul_f32 v[182:183], v[198:199], v[182:183]
	v_max_f32_e32 v3, v3, v3
	v_pk_mul_f32 v[88:89], v[88:89], v[182:183]
	v_and_b32_e32 v183, 0xffff0000, v192
	v_max_f32_e32 v3, 0xda24260, v3
	v_rcp_f32_e32 v182, v3
	v_max_f32_e32 v3, v183, v183
	v_lshlrev_b32_e32 v190, 16, v193
	v_max_f32_e32 v3, 0xda24260, v3
	v_rcp_f32_e32 v183, v3
	v_max_f32_e32 v3, v190, v190
	v_and_b32_e32 v191, 0xffff0000, v193
	v_max_f32_e32 v3, 0xda24260, v3
	v_rcp_f32_e32 v190, v3
	v_max_f32_e32 v3, v191, v191
	v_max_f32_e32 v3, 0xda24260, v3
	v_pk_mul_f32 v[188:189], v[188:189], v[194:195]
	v_rcp_f32_e32 v191, v3
	v_pk_mul_f32 v[86:87], v[86:87], v[188:189]
	s_waitcnt vmcnt(6)
	v_lshlrev_b32_e32 v188, 16, v186
	v_and_b32_e32 v189, 0xffff0000, v186
	s_waitcnt vmcnt(5)
	v_lshlrev_b32_e32 v3, 16, v180
	v_pk_mul_f32 v[182:183], v[182:183], v[188:189]
	v_max_f32_e32 v3, v3, v3
	v_lshlrev_b32_e32 v186, 16, v187
	v_and_b32_e32 v187, 0xffff0000, v187
	v_pk_mul_f32 v[82:83], v[82:83], v[182:183]
	v_and_b32_e32 v182, 0xffff0000, v180
	v_max_f32_e32 v3, 0xda24260, v3
	v_pk_mul_f32 v[186:187], v[190:191], v[186:187]
	v_rcp_f32_e32 v180, v3
	v_max_f32_e32 v3, v182, v182
	v_pk_mul_f32 v[84:85], v[84:85], v[186:187]
	v_lshlrev_b32_e32 v186, 16, v181
	v_max_f32_e32 v3, 0xda24260, v3
	v_and_b32_e32 v187, 0xffff0000, v181
	v_rcp_f32_e32 v181, v3
	v_max_f32_e32 v3, v186, v186
	v_max_f32_e32 v3, 0xda24260, v3
	v_rcp_f32_e32 v186, v3
	v_max_f32_e32 v3, v187, v187
	v_max_f32_e32 v3, 0xda24260, v3
	v_rcp_f32_e32 v187, v3
	s_waitcnt vmcnt(4)
	v_lshlrev_b32_e32 v182, 16, v196
	v_and_b32_e32 v183, 0xffff0000, v196
	s_waitcnt vmcnt(3)
	v_lshlrev_b32_e32 v3, 16, v176
	v_pk_mul_f32 v[180:181], v[180:181], v[182:183]
	v_max_f32_e32 v3, v3, v3
	v_lshlrev_b32_e32 v182, 16, v197
	v_and_b32_e32 v183, 0xffff0000, v197
	v_pk_mul_f32 v[78:79], v[78:79], v[180:181]
	v_and_b32_e32 v180, 0xffff0000, v176
	v_max_f32_e32 v3, 0xda24260, v3
	v_pk_mul_f32 v[182:183], v[186:187], v[182:183]
	v_rcp_f32_e32 v176, v3
	v_max_f32_e32 v3, v180, v180
	v_pk_mul_f32 v[80:81], v[80:81], v[182:183]
	v_lshlrev_b32_e32 v182, 16, v177
	v_max_f32_e32 v3, 0xda24260, v3
	v_and_b32_e32 v183, 0xffff0000, v177
	v_rcp_f32_e32 v177, v3
	v_max_f32_e32 v3, v182, v182
	v_max_f32_e32 v3, 0xda24260, v3
	v_rcp_f32_e32 v182, v3
	v_max_f32_e32 v3, v183, v183
	v_max_f32_e32 v3, 0xda24260, v3
	v_rcp_f32_e32 v183, v3
	s_waitcnt vmcnt(1)
	v_lshlrev_b32_e32 v180, 16, v146
	v_and_b32_e32 v181, 0xffff0000, v146
	v_lshlrev_b32_e32 v146, 16, v147
	v_and_b32_e32 v147, 0xffff0000, v147
	v_lshlrev_b32_e32 v3, 16, v4
	v_pk_mul_f32 v[146:147], v[182:183], v[146:147]
	v_max_f32_e32 v3, v3, v3
	v_pk_mul_f32 v[76:77], v[76:77], v[146:147]
	v_and_b32_e32 v146, 0xffff0000, v4
	v_max_f32_e32 v3, 0xda24260, v3
	v_pk_mul_f32 v[176:177], v[176:177], v[180:181]
	v_rcp_f32_e32 v4, v3
	v_max_f32_e32 v3, v146, v146
	v_pk_mul_f32 v[74:75], v[74:75], v[176:177]
	v_lshlrev_b32_e32 v176, 16, v5
	v_max_f32_e32 v3, 0xda24260, v3
	v_and_b32_e32 v177, 0xffff0000, v5
	v_rcp_f32_e32 v5, v3
	v_max_f32_e32 v3, v176, v176
	v_max_f32_e32 v3, 0xda24260, v3
	v_rcp_f32_e32 v176, v3
	v_max_f32_e32 v3, v177, v177
	v_max_f32_e32 v3, 0xda24260, v3
	v_rcp_f32_e32 v177, v3
	s_waitcnt vmcnt(0)
	v_lshlrev_b32_e32 v146, 16, v178
	v_and_b32_e32 v147, 0xffff0000, v178
	v_pk_mul_f32 v[4:5], v[4:5], v[146:147]
	v_lshlrev_b32_e32 v146, 16, v179
	v_and_b32_e32 v147, 0xffff0000, v179
	v_pk_mul_f32 v[146:147], v[176:177], v[146:147]
	v_pk_mul_f32 v[70:71], v[70:71], v[4:5]
	v_pk_mul_f32 v[72:73], v[72:73], v[146:147]
	s_branch .LBB0_2015

.LBB0_2143:
	ds_read_b128 v[160:163], v167
	ds_read_b128 v[170:173], v167 offset:1024
	ds_read_b128 v[174:177], v167 offset:2048
	ds_read_b128 v[178:181], v167 offset:3072
	ds_read_b128 v[182:185], v168
	ds_read_b128 v[186:189], v168 offset:1024
	ds_read_b128 v[190:193], v168 offset:2048
	ds_read_b128 v[194:197], v168 offset:3072
	s_add_i32 s80, s57, 2
	s_add_u32 s0, s58, 0xfff80080
	s_addc_u32 s1, s59, -1
	s_cmp_eq_u32 s37, s57
	s_cselect_b32 s63, s49, s1
	s_cselect_b32 s62, s48, s0
	s_cselect_b32 s61, s51, s47
	s_cselect_b32 s60, s50, s45
	v_lshl_add_u64 v[164:165], s[58:59], 0, v[152:153]
	s_add_i32 m0, s68, 0xc000
	ds_read_b128 v[198:201], v169
	ds_read_b128 v[202:205], v169 offset:1024
	ds_read_b128 v[208:211], v169 offset:2048
	ds_read_b128 v[212:215], v169 offset:3072
	ds_read_b128 v[216:219], v169 offset:4096
	ds_read_b128 v[220:223], v169 offset:5120
	ds_read_b128 v[224:227], v169 offset:6144
	ds_read_b128 v[228:231], v169 offset:7168
	global_load_lds_dwordx4 v[164:165], off
	v_lshl_add_u64 v[164:165], s[58:59], 0, v[154:155]
	s_add_i32 m0, s68, 0xe000
	s_nop 0
	global_load_lds_dwordx4 v[164:165], off
	s_waitcnt vmcnt(8)
	s_waitcnt lgkmcnt(0)
	s_barrier
	s_setprio 1
	s_waitcnt lgkmcnt(0)
	v_mfma_f32_16x16x32_bf16 v[66:69], v[160:163], v[198:201], v[66:69]
	v_mfma_f32_16x16x32_bf16 v[62:65], v[174:177], v[198:201], v[62:65]
	v_mfma_f32_16x16x32_bf16 v[58:61], v[160:163], v[208:211], v[58:61]
	v_mfma_f32_16x16x32_bf16 v[54:57], v[174:177], v[208:211], v[54:57]
	v_mfma_f32_16x16x32_bf16 v[50:53], v[160:163], v[216:219], v[50:53]
	v_mfma_f32_16x16x32_bf16 v[42:45], v[174:177], v[216:219], v[42:45]
	v_mfma_f32_16x16x32_bf16 v[34:37], v[160:163], v[224:227], v[34:37]
	v_mfma_f32_16x16x32_bf16 v[26:29], v[174:177], v[224:227], v[26:29]
	v_mfma_f32_16x16x32_bf16 v[66:69], v[170:173], v[202:205], v[66:69]
	v_mfma_f32_16x16x32_bf16 v[62:65], v[178:181], v[202:205], v[62:65]
	v_mfma_f32_16x16x32_bf16 v[58:61], v[170:173], v[212:215], v[58:61]
	v_mfma_f32_16x16x32_bf16 v[54:57], v[178:181], v[212:215], v[54:57]
	v_mfma_f32_16x16x32_bf16 v[50:53], v[170:173], v[220:223], v[50:53]
	v_mfma_f32_16x16x32_bf16 v[42:45], v[178:181], v[220:223], v[42:45]
	v_mfma_f32_16x16x32_bf16 v[34:37], v[170:173], v[228:231], v[34:37]
	v_mfma_f32_16x16x32_bf16 v[26:29], v[178:181], v[228:231], v[26:29]
	v_mfma_f32_16x16x32_bf16 v[46:49], v[182:185], v[198:201], v[46:49]
	v_mfma_f32_16x16x32_bf16 v[38:41], v[190:193], v[198:201], v[38:41]
	v_mfma_f32_16x16x32_bf16 v[30:33], v[182:185], v[208:211], v[30:33]
	v_mfma_f32_16x16x32_bf16 v[22:25], v[190:193], v[208:211], v[22:25]
	v_mfma_f32_16x16x32_bf16 v[14:17], v[182:185], v[216:219], v[14:17]
	v_mfma_f32_16x16x32_bf16 v[10:13], v[190:193], v[216:219], v[10:13]
	v_mfma_f32_16x16x32_bf16 v[6:9], v[182:185], v[224:227], v[6:9]
	v_mfma_f32_16x16x32_bf16 v[2:5], v[190:193], v[224:227], v[2:5]
	v_mfma_f32_16x16x32_bf16 v[46:49], v[186:189], v[202:205], v[46:49]
	v_mfma_f32_16x16x32_bf16 v[38:41], v[194:197], v[202:205], v[38:41]
	v_mfma_f32_16x16x32_bf16 v[30:33], v[186:189], v[212:215], v[30:33]
	v_mfma_f32_16x16x32_bf16 v[22:25], v[194:197], v[212:215], v[22:25]
	v_mfma_f32_16x16x32_bf16 v[14:17], v[186:189], v[220:223], v[14:17]
	v_mfma_f32_16x16x32_bf16 v[10:13], v[194:197], v[220:223], v[10:13]
	v_mfma_f32_16x16x32_bf16 v[6:9], v[186:189], v[228:231], v[6:9]
	v_mfma_f32_16x16x32_bf16 v[2:5], v[194:197], v[228:231], v[2:5]
	s_setprio 0
	s_barrier
	s_add_i32 s0, s77, s67
	v_lshl_add_u64 v[164:165], s[60:61], 0, v[130:131]
	s_mov_b32 m0, s0
	ds_read_b128 v[198:201], v169 offset:16384
	ds_read_b128 v[202:205], v169 offset:17408
	ds_read_b128 v[208:211], v169 offset:18432
	ds_read_b128 v[212:215], v169 offset:19456
	ds_read_b128 v[216:219], v169 offset:20480
	ds_read_b128 v[220:223], v169 offset:21504
	ds_read_b128 v[224:227], v169 offset:22528
	ds_read_b128 v[228:231], v169 offset:23552
	global_load_lds_dwordx4 v[164:165], off
	s_add_i32 m0, s0, 0x2000
	s_add_u32 s0, s60, 0x80000
	v_lshl_add_u64 v[232:233], s[60:61], 0, v[132:133]
	s_addc_u32 s1, s61, 0
	s_add_i32 s33, s78, s67
	global_load_lds_dwordx4 v[232:233], off
	v_lshl_add_u64 v[234:235], s[0:1], 0, v[130:131]
	s_mov_b32 m0, s33
	v_lshl_add_u64 v[236:237], s[62:63], 0, v[132:133]
	global_load_lds_dwordx4 v[234:235], off
	v_lshl_add_u64 v[234:235], s[0:1], 0, v[132:133]
	s_add_i32 m0, s33, 0x2000
	s_nop 0
	global_load_lds_dwordx4 v[234:235], off
	v_lshl_add_u64 v[234:235], s[62:63], 0, v[130:131]
	s_mov_b32 m0, s68
	s_nop 0
	global_load_lds_dwordx4 v[234:235], off
	s_mov_b32 m0, s69
	s_nop 0
	global_load_lds_dwordx4 v[236:237], off
	s_waitcnt vmcnt(8)
	s_waitcnt lgkmcnt(0)
	s_barrier
	s_setprio 1
	s_waitcnt lgkmcnt(0)
	v_mfma_f32_16x16x32_bf16 v[126:129], v[160:163], v[198:201], v[126:129]
	v_mfma_f32_16x16x32_bf16 v[122:125], v[174:177], v[198:201], v[122:125]
	v_mfma_f32_16x16x32_bf16 v[110:113], v[160:163], v[208:211], v[110:113]
	v_mfma_f32_16x16x32_bf16 v[106:109], v[174:177], v[208:211], v[106:109]
	v_mfma_f32_16x16x32_bf16 v[94:97], v[160:163], v[216:219], v[94:97]
	v_mfma_f32_16x16x32_bf16 v[90:93], v[174:177], v[216:219], v[90:93]
	v_mfma_f32_16x16x32_bf16 v[78:81], v[160:163], v[224:227], v[78:81]
	v_mfma_f32_16x16x32_bf16 v[74:77], v[174:177], v[224:227], v[74:77]
	v_mfma_f32_16x16x32_bf16 v[126:129], v[170:173], v[202:205], v[126:129]
	v_mfma_f32_16x16x32_bf16 v[122:125], v[178:181], v[202:205], v[122:125]
	v_mfma_f32_16x16x32_bf16 v[110:113], v[170:173], v[212:215], v[110:113]
	v_mfma_f32_16x16x32_bf16 v[106:109], v[178:181], v[212:215], v[106:109]
	v_mfma_f32_16x16x32_bf16 v[94:97], v[170:173], v[220:223], v[94:97]
	v_mfma_f32_16x16x32_bf16 v[90:93], v[178:181], v[220:223], v[90:93]
	v_mfma_f32_16x16x32_bf16 v[78:81], v[170:173], v[228:231], v[78:81]
	v_mfma_f32_16x16x32_bf16 v[74:77], v[178:181], v[228:231], v[74:77]
	v_mfma_f32_16x16x32_bf16 v[118:121], v[182:185], v[198:201], v[118:121]
	v_mfma_f32_16x16x32_bf16 v[114:117], v[190:193], v[198:201], v[114:117]
	v_mfma_f32_16x16x32_bf16 v[102:105], v[182:185], v[208:211], v[102:105]
	v_mfma_f32_16x16x32_bf16 v[98:101], v[190:193], v[208:211], v[98:101]
	v_mfma_f32_16x16x32_bf16 v[86:89], v[182:185], v[216:219], v[86:89]
	v_mfma_f32_16x16x32_bf16 v[82:85], v[190:193], v[216:219], v[82:85]
	v_mfma_f32_16x16x32_bf16 v[70:73], v[182:185], v[224:227], v[70:73]
	v_mfma_f32_16x16x32_bf16 v[18:21], v[190:193], v[224:227], v[18:21]
	v_mfma_f32_16x16x32_bf16 v[118:121], v[186:189], v[202:205], v[118:121]
	v_mfma_f32_16x16x32_bf16 v[114:117], v[194:197], v[202:205], v[114:117]
	v_mfma_f32_16x16x32_bf16 v[102:105], v[186:189], v[212:215], v[102:105]
	v_mfma_f32_16x16x32_bf16 v[98:101], v[194:197], v[212:215], v[98:101]
	v_mfma_f32_16x16x32_bf16 v[86:89], v[186:189], v[220:223], v[86:89]
	v_mfma_f32_16x16x32_bf16 v[82:85], v[194:197], v[220:223], v[82:85]
	v_mfma_f32_16x16x32_bf16 v[70:73], v[186:189], v[228:231], v[70:73]
	v_mfma_f32_16x16x32_bf16 v[18:21], v[194:197], v[228:231], v[18:21]
	s_setprio 0
	s_barrier
	s_add_i32 s33, 0, 0x18000
	s_add_i32 s40, 0, 0x1c000
	v_add_u32_e32 v178, s33, v1
	v_add_u32_e32 v194, s40, v1
	ds_read_b128 v[160:163], v178
	ds_read_b128 v[170:173], v178 offset:1024
	ds_read_b128 v[174:177], v178 offset:2048
	ds_read_b128 v[178:181], v178 offset:3072
	ds_read_b128 v[182:185], v194
	ds_read_b128 v[186:189], v194 offset:1024
	ds_read_b128 v[190:193], v194 offset:2048
	ds_read_b128 v[194:197], v194 offset:3072
	s_add_u32 s0, s62, 0x80000
	s_addc_u32 s1, s63, 0
	s_mov_b32 m0, s70
	v_lshl_add_u64 v[238:239], s[0:1], 0, v[130:131]
	ds_read_b128 v[198:201], v169 offset:32768
	ds_read_b128 v[202:205], v169 offset:33792
	ds_read_b128 v[208:211], v169 offset:34816
	ds_read_b128 v[212:215], v169 offset:35840
	ds_read_b128 v[216:219], v169 offset:36864
	ds_read_b128 v[220:223], v169 offset:37888
	ds_read_b128 v[224:227], v169 offset:38912
	ds_read_b128 v[228:231], v169 offset:39936
	global_load_lds_dwordx4 v[238:239], off
	v_lshl_add_u64 v[238:239], s[0:1], 0, v[132:133]
	s_mov_b32 m0, s71
	s_nop 0
	global_load_lds_dwordx4 v[238:239], off
	s_waitcnt vmcnt(8)
	s_waitcnt lgkmcnt(0)
	s_barrier
	s_setprio 1
	s_waitcnt lgkmcnt(0)
	v_mfma_f32_16x16x32_bf16 v[66:69], v[160:163], v[198:201], v[66:69]
	v_mfma_f32_16x16x32_bf16 v[62:65], v[174:177], v[198:201], v[62:65]
	v_mfma_f32_16x16x32_bf16 v[58:61], v[160:163], v[208:211], v[58:61]
	v_mfma_f32_16x16x32_bf16 v[54:57], v[174:177], v[208:211], v[54:57]
	v_mfma_f32_16x16x32_bf16 v[50:53], v[160:163], v[216:219], v[50:53]
	v_mfma_f32_16x16x32_bf16 v[42:45], v[174:177], v[216:219], v[42:45]
	v_mfma_f32_16x16x32_bf16 v[34:37], v[160:163], v[224:227], v[34:37]
	v_mfma_f32_16x16x32_bf16 v[26:29], v[174:177], v[224:227], v[26:29]
	v_mfma_f32_16x16x32_bf16 v[66:69], v[170:173], v[202:205], v[66:69]
	v_mfma_f32_16x16x32_bf16 v[62:65], v[178:181], v[202:205], v[62:65]
	v_mfma_f32_16x16x32_bf16 v[58:61], v[170:173], v[212:215], v[58:61]
	v_mfma_f32_16x16x32_bf16 v[54:57], v[178:181], v[212:215], v[54:57]
	v_mfma_f32_16x16x32_bf16 v[50:53], v[170:173], v[220:223], v[50:53]
	v_mfma_f32_16x16x32_bf16 v[42:45], v[178:181], v[220:223], v[42:45]
	v_mfma_f32_16x16x32_bf16 v[34:37], v[170:173], v[228:231], v[34:37]
	v_mfma_f32_16x16x32_bf16 v[26:29], v[178:181], v[228:231], v[26:29]
	v_mfma_f32_16x16x32_bf16 v[46:49], v[182:185], v[198:201], v[46:49]
	v_mfma_f32_16x16x32_bf16 v[38:41], v[190:193], v[198:201], v[38:41]
	v_mfma_f32_16x16x32_bf16 v[30:33], v[182:185], v[208:211], v[30:33]
	v_mfma_f32_16x16x32_bf16 v[22:25], v[190:193], v[208:211], v[22:25]
	v_mfma_f32_16x16x32_bf16 v[14:17], v[182:185], v[216:219], v[14:17]
	v_mfma_f32_16x16x32_bf16 v[10:13], v[190:193], v[216:219], v[10:13]
	v_mfma_f32_16x16x32_bf16 v[6:9], v[182:185], v[224:227], v[6:9]
	v_mfma_f32_16x16x32_bf16 v[2:5], v[190:193], v[224:227], v[2:5]
	v_mfma_f32_16x16x32_bf16 v[46:49], v[186:189], v[202:205], v[46:49]
	v_mfma_f32_16x16x32_bf16 v[38:41], v[194:197], v[202:205], v[38:41]
	v_mfma_f32_16x16x32_bf16 v[30:33], v[186:189], v[212:215], v[30:33]
	v_mfma_f32_16x16x32_bf16 v[22:25], v[194:197], v[212:215], v[22:25]
	v_mfma_f32_16x16x32_bf16 v[14:17], v[186:189], v[220:223], v[14:17]
	v_mfma_f32_16x16x32_bf16 v[10:13], v[194:197], v[220:223], v[10:13]
	v_mfma_f32_16x16x32_bf16 v[6:9], v[186:189], v[228:231], v[6:9]
	v_mfma_f32_16x16x32_bf16 v[2:5], v[194:197], v[228:231], v[2:5]
	s_setprio 0
	s_barrier
	s_add_i32 s0, s33, s67
	v_lshl_add_u64 v[164:165], v[164:165], 0, s[22:23]
	s_mov_b32 m0, s0
	ds_read_b128 v[198:201], v169 offset:49152
	ds_read_b128 v[202:205], v169 offset:50176
	ds_read_b128 v[208:211], v169 offset:51200
	ds_read_b128 v[212:215], v169 offset:52224
	ds_read_b128 v[216:219], v169 offset:53248
	ds_read_b128 v[220:223], v169 offset:54272
	ds_read_b128 v[224:227], v169 offset:55296
	ds_read_b128 v[228:231], v169 offset:56320
	global_load_lds_dwordx4 v[164:165], off
	s_add_i32 m0, s0, 0x2000
	s_add_u32 s0, s60, 0x80080
	v_lshl_add_u64 v[164:165], v[232:233], 0, s[22:23]
	s_addc_u32 s1, s61, 0
	s_add_i32 s33, s40, s67
	global_load_lds_dwordx4 v[164:165], off
	v_lshl_add_u64 v[164:165], s[0:1], 0, v[130:131]
	s_mov_b32 m0, s33
	s_nop 0
	global_load_lds_dwordx4 v[164:165], off
	v_lshl_add_u64 v[164:165], s[0:1], 0, v[132:133]
	s_add_i32 m0, s33, 0x2000
	s_nop 0
	global_load_lds_dwordx4 v[164:165], off
	v_lshl_add_u64 v[164:165], v[234:235], 0, s[22:23]
	s_mov_b32 m0, s75
	s_nop 0
	global_load_lds_dwordx4 v[164:165], off
	v_lshl_add_u64 v[164:165], v[236:237], 0, s[22:23]
	s_mov_b32 m0, s76
	s_nop 0
	global_load_lds_dwordx4 v[164:165], off
	s_waitcnt vmcnt(8)
	s_waitcnt lgkmcnt(0)
	s_barrier
	s_setprio 1
	s_waitcnt lgkmcnt(0)
	v_mfma_f32_16x16x32_bf16 v[126:129], v[160:163], v[198:201], v[126:129]
	v_mfma_f32_16x16x32_bf16 v[122:125], v[174:177], v[198:201], v[122:125]
	v_mfma_f32_16x16x32_bf16 v[110:113], v[160:163], v[208:211], v[110:113]
	v_mfma_f32_16x16x32_bf16 v[106:109], v[174:177], v[208:211], v[106:109]
	v_mfma_f32_16x16x32_bf16 v[94:97], v[160:163], v[216:219], v[94:97]
	v_mfma_f32_16x16x32_bf16 v[90:93], v[174:177], v[216:219], v[90:93]
	v_mfma_f32_16x16x32_bf16 v[78:81], v[160:163], v[224:227], v[78:81]
	v_mfma_f32_16x16x32_bf16 v[74:77], v[174:177], v[224:227], v[74:77]
	v_mfma_f32_16x16x32_bf16 v[126:129], v[170:173], v[202:205], v[126:129]
	v_mfma_f32_16x16x32_bf16 v[122:125], v[178:181], v[202:205], v[122:125]
	v_mfma_f32_16x16x32_bf16 v[110:113], v[170:173], v[212:215], v[110:113]
	v_mfma_f32_16x16x32_bf16 v[106:109], v[178:181], v[212:215], v[106:109]
	v_mfma_f32_16x16x32_bf16 v[94:97], v[170:173], v[220:223], v[94:97]
	v_mfma_f32_16x16x32_bf16 v[90:93], v[178:181], v[220:223], v[90:93]
	v_mfma_f32_16x16x32_bf16 v[78:81], v[170:173], v[228:231], v[78:81]
	v_mfma_f32_16x16x32_bf16 v[74:77], v[178:181], v[228:231], v[74:77]
	v_mfma_f32_16x16x32_bf16 v[118:121], v[182:185], v[198:201], v[118:121]
	v_mfma_f32_16x16x32_bf16 v[114:117], v[190:193], v[198:201], v[114:117]
	v_mfma_f32_16x16x32_bf16 v[102:105], v[182:185], v[208:211], v[102:105]
	v_mfma_f32_16x16x32_bf16 v[98:101], v[190:193], v[208:211], v[98:101]
	v_mfma_f32_16x16x32_bf16 v[86:89], v[182:185], v[216:219], v[86:89]
	v_mfma_f32_16x16x32_bf16 v[82:85], v[190:193], v[216:219], v[82:85]
	v_mfma_f32_16x16x32_bf16 v[70:73], v[182:185], v[224:227], v[70:73]
	v_mfma_f32_16x16x32_bf16 v[18:21], v[190:193], v[224:227], v[18:21]
	v_mfma_f32_16x16x32_bf16 v[118:121], v[186:189], v[202:205], v[118:121]
	v_mfma_f32_16x16x32_bf16 v[114:117], v[194:197], v[202:205], v[114:117]
	v_mfma_f32_16x16x32_bf16 v[102:105], v[186:189], v[212:215], v[102:105]
	v_mfma_f32_16x16x32_bf16 v[98:101], v[194:197], v[212:215], v[98:101]
	v_mfma_f32_16x16x32_bf16 v[86:89], v[186:189], v[220:223], v[86:89]
	v_mfma_f32_16x16x32_bf16 v[82:85], v[194:197], v[220:223], v[82:85]
	v_mfma_f32_16x16x32_bf16 v[70:73], v[186:189], v[228:231], v[70:73]
	v_mfma_f32_16x16x32_bf16 v[18:21], v[194:197], v[228:231], v[18:21]
	s_setprio 0
	s_barrier
	s_add_u32 s58, s58, 0x100
	s_addc_u32 s59, s59, 0
	s_add_u32 s45, s45, 0x100
	s_addc_u32 s47, s47, 0
	s_cmp_ge_u32 s80, s15
	s_mov_b32 s57, s80
	s_cbranch_scc0 .LBB0_2143
	s_and_b64 vcc, exec, s[24:25]
	s_cbranch_vccz .LBB0_2146
	s_barrier

.LBB0_2294:
	ds_read_b128 v[150:153], v146
	ds_read_b128 v[154:157], v146 offset:1024
	ds_read_b128 v[158:161], v146 offset:2048
	ds_read_b128 v[162:165], v146 offset:3072
	ds_read_b128 v[166:169], v147
	ds_read_b128 v[170:173], v147 offset:1024
	ds_read_b128 v[174:177], v147 offset:2048
	ds_read_b128 v[178:181], v147 offset:3072
	s_add_u32 s0, s26, 0xfff80080
	s_addc_u32 s1, s27, -1
	s_cmp_eq_u32 s61, 12
	s_cselect_b32 s31, s51, s1
	s_cselect_b32 s30, s56, s0
	s_cselect_b32 s29, s57, s60
	s_cselect_b32 s28, s58, s59
	v_lshl_add_u64 v[140:141], s[26:27], 0, v[136:137]
	s_add_i32 m0, s7, 0xc000
	ds_read_b128 v[182:185], v148
	ds_read_b128 v[186:189], v148 offset:1024
	ds_read_b128 v[190:193], v148 offset:2048
	ds_read_b128 v[194:197], v148 offset:3072
	ds_read_b128 v[198:201], v148 offset:4096
	ds_read_b128 v[202:205], v148 offset:5120
	ds_read_b128 v[208:211], v148 offset:6144
	ds_read_b128 v[212:215], v148 offset:7168
	global_load_lds_dwordx4 v[140:141], off
	v_lshl_add_u64 v[140:141], s[26:27], 0, v[138:139]
	s_add_i32 m0, s7, 0xe000
	s_nop 0
	global_load_lds_dwordx4 v[140:141], off
	s_waitcnt vmcnt(8)
	s_waitcnt lgkmcnt(0)
	s_barrier
	s_setprio 1
	s_waitcnt lgkmcnt(0)
	v_mfma_f32_16x16x32_bf16 v[126:129], v[150:153], v[182:185], v[126:129]
	v_mfma_f32_16x16x32_bf16 v[122:125], v[158:161], v[182:185], v[122:125]
	v_mfma_f32_16x16x32_bf16 v[114:117], v[150:153], v[190:193], v[114:117]
	v_mfma_f32_16x16x32_bf16 v[106:109], v[158:161], v[190:193], v[106:109]
	v_mfma_f32_16x16x32_bf16 v[98:101], v[150:153], v[198:201], v[98:101]
	v_mfma_f32_16x16x32_bf16 v[90:93], v[158:161], v[198:201], v[90:93]
	v_mfma_f32_16x16x32_bf16 v[82:85], v[150:153], v[208:211], v[82:85]
	v_mfma_f32_16x16x32_bf16 v[74:77], v[158:161], v[208:211], v[74:77]
	v_mfma_f32_16x16x32_bf16 v[126:129], v[154:157], v[186:189], v[126:129]
	v_mfma_f32_16x16x32_bf16 v[122:125], v[162:165], v[186:189], v[122:125]
	v_mfma_f32_16x16x32_bf16 v[114:117], v[154:157], v[194:197], v[114:117]
	v_mfma_f32_16x16x32_bf16 v[106:109], v[162:165], v[194:197], v[106:109]
	v_mfma_f32_16x16x32_bf16 v[98:101], v[154:157], v[202:205], v[98:101]
	v_mfma_f32_16x16x32_bf16 v[90:93], v[162:165], v[202:205], v[90:93]
	v_mfma_f32_16x16x32_bf16 v[82:85], v[154:157], v[212:215], v[82:85]
	v_mfma_f32_16x16x32_bf16 v[74:77], v[162:165], v[212:215], v[74:77]
	v_mfma_f32_16x16x32_bf16 v[118:121], v[166:169], v[182:185], v[118:121]
	v_mfma_f32_16x16x32_bf16 v[110:113], v[174:177], v[182:185], v[110:113]
	v_mfma_f32_16x16x32_bf16 v[102:105], v[166:169], v[190:193], v[102:105]
	v_mfma_f32_16x16x32_bf16 v[94:97], v[174:177], v[190:193], v[94:97]
	v_mfma_f32_16x16x32_bf16 v[86:89], v[166:169], v[198:201], v[86:89]
	v_mfma_f32_16x16x32_bf16 v[78:81], v[174:177], v[198:201], v[78:81]
	v_mfma_f32_16x16x32_bf16 v[70:73], v[166:169], v[208:211], v[70:73]
	v_mfma_f32_16x16x32_bf16 v[66:69], v[174:177], v[208:211], v[66:69]
	v_mfma_f32_16x16x32_bf16 v[118:121], v[170:173], v[186:189], v[118:121]
	v_mfma_f32_16x16x32_bf16 v[110:113], v[178:181], v[186:189], v[110:113]
	v_mfma_f32_16x16x32_bf16 v[102:105], v[170:173], v[194:197], v[102:105]
	v_mfma_f32_16x16x32_bf16 v[94:97], v[178:181], v[194:197], v[94:97]
	v_mfma_f32_16x16x32_bf16 v[86:89], v[170:173], v[202:205], v[86:89]
	v_mfma_f32_16x16x32_bf16 v[78:81], v[178:181], v[202:205], v[78:81]
	v_mfma_f32_16x16x32_bf16 v[70:73], v[170:173], v[212:215], v[70:73]
	v_mfma_f32_16x16x32_bf16 v[66:69], v[178:181], v[212:215], v[66:69]
	s_setprio 0
	s_barrier
	s_add_i32 s0, s46, s38
	v_lshl_add_u64 v[140:141], s[28:29], 0, v[132:133]
	s_mov_b32 m0, s0
	ds_read_b128 v[182:185], v148 offset:16384
	ds_read_b128 v[186:189], v148 offset:17408
	ds_read_b128 v[190:193], v148 offset:18432
	ds_read_b128 v[194:197], v148 offset:19456
	ds_read_b128 v[198:201], v148 offset:20480
	ds_read_b128 v[202:205], v148 offset:21504
	ds_read_b128 v[208:211], v148 offset:22528
	ds_read_b128 v[212:215], v148 offset:23552
	global_load_lds_dwordx4 v[140:141], off
	s_add_i32 m0, s0, 0x2000
	s_add_u32 s0, s28, 0x80000
	v_lshl_add_u64 v[216:217], s[28:29], 0, v[130:131]
	s_addc_u32 s1, s29, 0
	s_add_i32 s33, s47, s38
	global_load_lds_dwordx4 v[216:217], off
	v_lshl_add_u64 v[218:219], s[0:1], 0, v[132:133]
	s_mov_b32 m0, s33
	v_lshl_add_u64 v[220:221], s[30:31], 0, v[130:131]
	global_load_lds_dwordx4 v[218:219], off
	v_lshl_add_u64 v[218:219], s[0:1], 0, v[130:131]
	s_add_i32 m0, s33, 0x2000
	s_nop 0
	global_load_lds_dwordx4 v[218:219], off
	v_lshl_add_u64 v[218:219], s[30:31], 0, v[132:133]
	s_mov_b32 m0, s7
	s_nop 0
	global_load_lds_dwordx4 v[218:219], off
	s_mov_b32 m0, s41
	s_nop 0
	global_load_lds_dwordx4 v[220:221], off
	s_waitcnt vmcnt(8)
	s_waitcnt lgkmcnt(0)
	s_barrier
	s_setprio 1
	s_waitcnt lgkmcnt(0)
	v_mfma_f32_16x16x32_bf16 v[62:65], v[150:153], v[182:185], v[62:65]
	v_mfma_f32_16x16x32_bf16 v[58:61], v[158:161], v[182:185], v[58:61]
	v_mfma_f32_16x16x32_bf16 v[50:53], v[150:153], v[190:193], v[50:53]
	v_mfma_f32_16x16x32_bf16 v[42:45], v[158:161], v[190:193], v[42:45]
	v_mfma_f32_16x16x32_bf16 v[34:37], v[150:153], v[198:201], v[34:37]
	v_mfma_f32_16x16x32_bf16 v[26:29], v[158:161], v[198:201], v[26:29]
	v_mfma_f32_16x16x32_bf16 v[18:21], v[150:153], v[208:211], v[18:21]
	v_mfma_f32_16x16x32_bf16 v[10:13], v[158:161], v[208:211], v[10:13]
	v_mfma_f32_16x16x32_bf16 v[62:65], v[154:157], v[186:189], v[62:65]
	v_mfma_f32_16x16x32_bf16 v[58:61], v[162:165], v[186:189], v[58:61]
	v_mfma_f32_16x16x32_bf16 v[50:53], v[154:157], v[194:197], v[50:53]
	v_mfma_f32_16x16x32_bf16 v[42:45], v[162:165], v[194:197], v[42:45]
	v_mfma_f32_16x16x32_bf16 v[34:37], v[154:157], v[202:205], v[34:37]
	v_mfma_f32_16x16x32_bf16 v[26:29], v[162:165], v[202:205], v[26:29]
	v_mfma_f32_16x16x32_bf16 v[18:21], v[154:157], v[212:215], v[18:21]
	v_mfma_f32_16x16x32_bf16 v[10:13], v[162:165], v[212:215], v[10:13]
	v_mfma_f32_16x16x32_bf16 v[54:57], v[166:169], v[182:185], v[54:57]
	v_mfma_f32_16x16x32_bf16 v[46:49], v[174:177], v[182:185], v[46:49]
	v_mfma_f32_16x16x32_bf16 v[38:41], v[166:169], v[190:193], v[38:41]
	v_mfma_f32_16x16x32_bf16 v[30:33], v[174:177], v[190:193], v[30:33]
	v_mfma_f32_16x16x32_bf16 v[22:25], v[166:169], v[198:201], v[22:25]
	v_mfma_f32_16x16x32_bf16 v[14:17], v[174:177], v[198:201], v[14:17]
	v_mfma_f32_16x16x32_bf16 v[6:9], v[166:169], v[208:211], v[6:9]
	v_mfma_f32_16x16x32_bf16 v[2:5], v[174:177], v[208:211], v[2:5]
	v_mfma_f32_16x16x32_bf16 v[54:57], v[170:173], v[186:189], v[54:57]
	v_mfma_f32_16x16x32_bf16 v[46:49], v[178:181], v[186:189], v[46:49]
	v_mfma_f32_16x16x32_bf16 v[38:41], v[170:173], v[194:197], v[38:41]
	v_mfma_f32_16x16x32_bf16 v[30:33], v[178:181], v[194:197], v[30:33]
	v_mfma_f32_16x16x32_bf16 v[22:25], v[170:173], v[202:205], v[22:25]
	v_mfma_f32_16x16x32_bf16 v[14:17], v[178:181], v[202:205], v[14:17]
	v_mfma_f32_16x16x32_bf16 v[6:9], v[170:173], v[212:215], v[6:9]
	v_mfma_f32_16x16x32_bf16 v[2:5], v[178:181], v[212:215], v[2:5]
	s_setprio 0
	s_barrier
	s_add_i32 s33, 0, 0x18000
	v_add_u32_e32 v149, s33, v142
	s_add_i32 s52, 0, 0x1c000
	ds_read_b128 v[150:153], v149
	ds_read_b128 v[154:157], v149 offset:1024
	ds_read_b128 v[158:161], v149 offset:2048
	ds_read_b128 v[162:165], v149 offset:3072
	v_add_u32_e32 v149, s52, v142
	ds_read_b128 v[166:169], v149
	ds_read_b128 v[170:173], v149 offset:1024
	ds_read_b128 v[174:177], v149 offset:2048
	ds_read_b128 v[178:181], v149 offset:3072
	s_add_u32 s0, s30, 0x80000
	s_addc_u32 s1, s31, 0
	s_mov_b32 m0, s42
	v_lshl_add_u64 v[222:223], s[0:1], 0, v[132:133]
	ds_read_b128 v[182:185], v148 offset:32768
	ds_read_b128 v[186:189], v148 offset:33792
	ds_read_b128 v[190:193], v148 offset:34816
	ds_read_b128 v[194:197], v148 offset:35840
	ds_read_b128 v[198:201], v148 offset:36864
	ds_read_b128 v[202:205], v148 offset:37888
	ds_read_b128 v[208:211], v148 offset:38912
	ds_read_b128 v[212:215], v148 offset:39936
	global_load_lds_dwordx4 v[222:223], off
	v_lshl_add_u64 v[222:223], s[0:1], 0, v[130:131]
	s_mov_b32 m0, s43
	s_nop 0
	global_load_lds_dwordx4 v[222:223], off
	s_waitcnt vmcnt(8)
	s_waitcnt lgkmcnt(0)
	s_barrier
	s_setprio 1
	s_waitcnt lgkmcnt(0)
	v_mfma_f32_16x16x32_bf16 v[126:129], v[150:153], v[182:185], v[126:129]
	v_mfma_f32_16x16x32_bf16 v[122:125], v[158:161], v[182:185], v[122:125]
	v_mfma_f32_16x16x32_bf16 v[114:117], v[150:153], v[190:193], v[114:117]
	v_mfma_f32_16x16x32_bf16 v[106:109], v[158:161], v[190:193], v[106:109]
	v_mfma_f32_16x16x32_bf16 v[98:101], v[150:153], v[198:201], v[98:101]
	v_mfma_f32_16x16x32_bf16 v[90:93], v[158:161], v[198:201], v[90:93]
	v_mfma_f32_16x16x32_bf16 v[82:85], v[150:153], v[208:211], v[82:85]
	v_mfma_f32_16x16x32_bf16 v[74:77], v[158:161], v[208:211], v[74:77]
	v_mfma_f32_16x16x32_bf16 v[126:129], v[154:157], v[186:189], v[126:129]
	v_mfma_f32_16x16x32_bf16 v[122:125], v[162:165], v[186:189], v[122:125]
	v_mfma_f32_16x16x32_bf16 v[114:117], v[154:157], v[194:197], v[114:117]
	v_mfma_f32_16x16x32_bf16 v[106:109], v[162:165], v[194:197], v[106:109]
	v_mfma_f32_16x16x32_bf16 v[98:101], v[154:157], v[202:205], v[98:101]
	v_mfma_f32_16x16x32_bf16 v[90:93], v[162:165], v[202:205], v[90:93]
	v_mfma_f32_16x16x32_bf16 v[82:85], v[154:157], v[212:215], v[82:85]
	v_mfma_f32_16x16x32_bf16 v[74:77], v[162:165], v[212:215], v[74:77]
	v_mfma_f32_16x16x32_bf16 v[118:121], v[166:169], v[182:185], v[118:121]
	v_mfma_f32_16x16x32_bf16 v[110:113], v[174:177], v[182:185], v[110:113]
	v_mfma_f32_16x16x32_bf16 v[102:105], v[166:169], v[190:193], v[102:105]
	v_mfma_f32_16x16x32_bf16 v[94:97], v[174:177], v[190:193], v[94:97]
	v_mfma_f32_16x16x32_bf16 v[86:89], v[166:169], v[198:201], v[86:89]
	v_mfma_f32_16x16x32_bf16 v[78:81], v[174:177], v[198:201], v[78:81]
	v_mfma_f32_16x16x32_bf16 v[70:73], v[166:169], v[208:211], v[70:73]
	v_mfma_f32_16x16x32_bf16 v[66:69], v[174:177], v[208:211], v[66:69]
	v_mfma_f32_16x16x32_bf16 v[118:121], v[170:173], v[186:189], v[118:121]
	v_mfma_f32_16x16x32_bf16 v[110:113], v[178:181], v[186:189], v[110:113]
	v_mfma_f32_16x16x32_bf16 v[102:105], v[170:173], v[194:197], v[102:105]
	v_mfma_f32_16x16x32_bf16 v[94:97], v[178:181], v[194:197], v[94:97]
	v_mfma_f32_16x16x32_bf16 v[86:89], v[170:173], v[202:205], v[86:89]
	v_mfma_f32_16x16x32_bf16 v[78:81], v[178:181], v[202:205], v[78:81]
	v_mfma_f32_16x16x32_bf16 v[70:73], v[170:173], v[212:215], v[70:73]
	v_mfma_f32_16x16x32_bf16 v[66:69], v[178:181], v[212:215], v[66:69]
	s_setprio 0
	s_barrier
	s_add_i32 s0, s33, s38
	v_lshl_add_u64 v[140:141], v[140:141], 0, s[20:21]
	s_mov_b32 m0, s0
	ds_read_b128 v[182:185], v148 offset:49152
	ds_read_b128 v[186:189], v148 offset:50176
	ds_read_b128 v[190:193], v148 offset:51200
	ds_read_b128 v[194:197], v148 offset:52224
	ds_read_b128 v[198:201], v148 offset:53248
	ds_read_b128 v[202:205], v148 offset:54272
	ds_read_b128 v[208:211], v148 offset:55296
	ds_read_b128 v[212:215], v148 offset:56320
	global_load_lds_dwordx4 v[140:141], off
	s_add_i32 m0, s0, 0x2000
	s_add_u32 s0, s28, 0x80080
	v_lshl_add_u64 v[140:141], v[216:217], 0, s[20:21]
	s_addc_u32 s1, s29, 0
	s_add_i32 s28, s52, s38
	global_load_lds_dwordx4 v[140:141], off
	v_lshl_add_u64 v[140:141], s[0:1], 0, v[132:133]
	s_mov_b32 m0, s28
	s_nop 0
	global_load_lds_dwordx4 v[140:141], off
	v_lshl_add_u64 v[140:141], s[0:1], 0, v[130:131]
	s_add_i32 m0, s28, 0x2000
	s_nop 0
	global_load_lds_dwordx4 v[140:141], off
	v_lshl_add_u64 v[140:141], v[218:219], 0, s[20:21]
	s_mov_b32 m0, s44
	s_nop 0
	global_load_lds_dwordx4 v[140:141], off
	v_lshl_add_u64 v[140:141], v[220:221], 0, s[20:21]
	s_mov_b32 m0, s45
	s_nop 0
	global_load_lds_dwordx4 v[140:141], off
	s_waitcnt vmcnt(8)
	s_waitcnt lgkmcnt(0)
	s_barrier
	s_setprio 1
	s_waitcnt lgkmcnt(0)
	v_mfma_f32_16x16x32_bf16 v[62:65], v[150:153], v[182:185], v[62:65]
	v_mfma_f32_16x16x32_bf16 v[58:61], v[158:161], v[182:185], v[58:61]
	v_mfma_f32_16x16x32_bf16 v[50:53], v[150:153], v[190:193], v[50:53]
	v_mfma_f32_16x16x32_bf16 v[42:45], v[158:161], v[190:193], v[42:45]
	v_mfma_f32_16x16x32_bf16 v[34:37], v[150:153], v[198:201], v[34:37]
	v_mfma_f32_16x16x32_bf16 v[26:29], v[158:161], v[198:201], v[26:29]
	v_mfma_f32_16x16x32_bf16 v[18:21], v[150:153], v[208:211], v[18:21]
	v_mfma_f32_16x16x32_bf16 v[10:13], v[158:161], v[208:211], v[10:13]
	v_mfma_f32_16x16x32_bf16 v[62:65], v[154:157], v[186:189], v[62:65]
	v_mfma_f32_16x16x32_bf16 v[58:61], v[162:165], v[186:189], v[58:61]
	v_mfma_f32_16x16x32_bf16 v[50:53], v[154:157], v[194:197], v[50:53]
	v_mfma_f32_16x16x32_bf16 v[42:45], v[162:165], v[194:197], v[42:45]
	v_mfma_f32_16x16x32_bf16 v[34:37], v[154:157], v[202:205], v[34:37]
	v_mfma_f32_16x16x32_bf16 v[26:29], v[162:165], v[202:205], v[26:29]
	v_mfma_f32_16x16x32_bf16 v[18:21], v[154:157], v[212:215], v[18:21]
	v_mfma_f32_16x16x32_bf16 v[10:13], v[162:165], v[212:215], v[10:13]
	v_mfma_f32_16x16x32_bf16 v[54:57], v[166:169], v[182:185], v[54:57]
	v_mfma_f32_16x16x32_bf16 v[46:49], v[174:177], v[182:185], v[46:49]
	v_mfma_f32_16x16x32_bf16 v[38:41], v[166:169], v[190:193], v[38:41]
	v_mfma_f32_16x16x32_bf16 v[30:33], v[174:177], v[190:193], v[30:33]
	v_mfma_f32_16x16x32_bf16 v[22:25], v[166:169], v[198:201], v[22:25]
	v_mfma_f32_16x16x32_bf16 v[14:17], v[174:177], v[198:201], v[14:17]
	v_mfma_f32_16x16x32_bf16 v[6:9], v[166:169], v[208:211], v[6:9]
	v_mfma_f32_16x16x32_bf16 v[2:5], v[174:177], v[208:211], v[2:5]
	v_mfma_f32_16x16x32_bf16 v[54:57], v[170:173], v[186:189], v[54:57]
	v_mfma_f32_16x16x32_bf16 v[46:49], v[178:181], v[186:189], v[46:49]
	v_mfma_f32_16x16x32_bf16 v[38:41], v[170:173], v[194:197], v[38:41]
	v_mfma_f32_16x16x32_bf16 v[30:33], v[178:181], v[194:197], v[30:33]
	v_mfma_f32_16x16x32_bf16 v[22:25], v[170:173], v[202:205], v[22:25]
	v_mfma_f32_16x16x32_bf16 v[14:17], v[178:181], v[202:205], v[14:17]
	v_mfma_f32_16x16x32_bf16 v[6:9], v[170:173], v[212:215], v[6:9]
	v_mfma_f32_16x16x32_bf16 v[2:5], v[178:181], v[212:215], v[2:5]
	s_setprio 0
	s_barrier
	s_add_i32 s61, s61, 2
	s_add_u32 s26, s26, 0x100
	s_addc_u32 s27, s27, 0
	s_add_u32 s59, s59, 0x100
	s_addc_u32 s60, s60, 0
	s_cmp_gt_u32 s61, 13
	s_cbranch_scc0 .LBB0_2294
	s_and_b64 vcc, exec, s[22:23]
	s_cbranch_vccz .LBB0_2297
	s_barrier

.LBB0_2541:
	ds_read_b128 v[160:163], v173
	ds_read_b128 v[164:167], v173 offset:1024
	ds_read_b128 v[168:171], v173 offset:2048
	ds_read_b128 v[176:179], v173 offset:3072
	ds_read_b128 v[180:183], v174
	ds_read_b128 v[184:187], v174 offset:1024
	ds_read_b128 v[188:191], v174 offset:2048
	ds_read_b128 v[192:195], v174 offset:3072
	s_add_i32 s84, s59, 2
	s_add_u32 s0, s60, 0xfffe0080
	s_addc_u32 s1, s61, -1
	s_cmp_eq_u32 s47, s59
	s_cselect_b32 s65, s53, s1
	s_cselect_b32 s64, s52, s0
	s_cselect_b32 s63, s57, s51
	s_cselect_b32 s62, s56, s49
	v_lshl_add_u64 v[204:205], s[60:61], 0, v[152:153]
	s_add_i32 m0, s68, 0xc000
	ds_read_b128 v[196:199], v175
	ds_read_b128 v[200:203], v175 offset:1024
	ds_read_b128 v[208:211], v175 offset:2048
	ds_read_b128 v[212:215], v175 offset:3072
	ds_read_b128 v[216:219], v175 offset:4096
	ds_read_b128 v[220:223], v175 offset:5120
	ds_read_b128 v[224:227], v175 offset:6144
	ds_read_b128 v[228:231], v175 offset:7168
	global_load_lds_dwordx4 v[204:205], off
	v_lshl_add_u64 v[204:205], s[60:61], 0, v[154:155]
	s_add_i32 m0, s68, 0xe000
	s_nop 0
	global_load_lds_dwordx4 v[204:205], off
	s_waitcnt vmcnt(8)
	s_waitcnt lgkmcnt(0)
	s_barrier
	s_setprio 1
	s_waitcnt lgkmcnt(0)
	v_mfma_f32_16x16x32_bf16 v[66:69], v[160:163], v[196:199], v[66:69]
	v_mfma_f32_16x16x32_bf16 v[62:65], v[168:171], v[196:199], v[62:65]
	v_mfma_f32_16x16x32_bf16 v[58:61], v[160:163], v[208:211], v[58:61]
	v_mfma_f32_16x16x32_bf16 v[54:57], v[168:171], v[208:211], v[54:57]
	v_mfma_f32_16x16x32_bf16 v[50:53], v[160:163], v[216:219], v[50:53]
	v_mfma_f32_16x16x32_bf16 v[42:45], v[168:171], v[216:219], v[42:45]
	v_mfma_f32_16x16x32_bf16 v[34:37], v[160:163], v[224:227], v[34:37]
	v_mfma_f32_16x16x32_bf16 v[26:29], v[168:171], v[224:227], v[26:29]
	v_mfma_f32_16x16x32_bf16 v[66:69], v[164:167], v[200:203], v[66:69]
	v_mfma_f32_16x16x32_bf16 v[62:65], v[176:179], v[200:203], v[62:65]
	v_mfma_f32_16x16x32_bf16 v[58:61], v[164:167], v[212:215], v[58:61]
	v_mfma_f32_16x16x32_bf16 v[54:57], v[176:179], v[212:215], v[54:57]
	v_mfma_f32_16x16x32_bf16 v[50:53], v[164:167], v[220:223], v[50:53]
	v_mfma_f32_16x16x32_bf16 v[42:45], v[176:179], v[220:223], v[42:45]
	v_mfma_f32_16x16x32_bf16 v[34:37], v[164:167], v[228:231], v[34:37]
	v_mfma_f32_16x16x32_bf16 v[26:29], v[176:179], v[228:231], v[26:29]
	v_mfma_f32_16x16x32_bf16 v[46:49], v[180:183], v[196:199], v[46:49]
	v_mfma_f32_16x16x32_bf16 v[38:41], v[188:191], v[196:199], v[38:41]
	v_mfma_f32_16x16x32_bf16 v[30:33], v[180:183], v[208:211], v[30:33]
	v_mfma_f32_16x16x32_bf16 v[22:25], v[188:191], v[208:211], v[22:25]
	v_mfma_f32_16x16x32_bf16 v[14:17], v[180:183], v[216:219], v[14:17]
	v_mfma_f32_16x16x32_bf16 v[10:13], v[188:191], v[216:219], v[10:13]
	v_mfma_f32_16x16x32_bf16 v[6:9], v[180:183], v[224:227], v[6:9]
	v_mfma_f32_16x16x32_bf16 v[2:5], v[188:191], v[224:227], v[2:5]
	v_mfma_f32_16x16x32_bf16 v[46:49], v[184:187], v[200:203], v[46:49]
	v_mfma_f32_16x16x32_bf16 v[38:41], v[192:195], v[200:203], v[38:41]
	v_mfma_f32_16x16x32_bf16 v[30:33], v[184:187], v[212:215], v[30:33]
	v_mfma_f32_16x16x32_bf16 v[22:25], v[192:195], v[212:215], v[22:25]
	v_mfma_f32_16x16x32_bf16 v[14:17], v[184:187], v[220:223], v[14:17]
	v_mfma_f32_16x16x32_bf16 v[10:13], v[192:195], v[220:223], v[10:13]
	v_mfma_f32_16x16x32_bf16 v[6:9], v[184:187], v[228:231], v[6:9]
	v_mfma_f32_16x16x32_bf16 v[2:5], v[192:195], v[228:231], v[2:5]
	s_setprio 0
	s_barrier
	s_add_i32 s0, s81, s67
	v_lshl_add_u64 v[204:205], s[62:63], 0, v[130:131]
	s_mov_b32 m0, s0
	ds_read_b128 v[196:199], v175 offset:16384
	ds_read_b128 v[200:203], v175 offset:17408
	ds_read_b128 v[208:211], v175 offset:18432
	ds_read_b128 v[212:215], v175 offset:19456
	ds_read_b128 v[216:219], v175 offset:20480
	ds_read_b128 v[220:223], v175 offset:21504
	ds_read_b128 v[224:227], v175 offset:22528
	ds_read_b128 v[228:231], v175 offset:23552
	global_load_lds_dwordx4 v[204:205], off
	s_add_i32 m0, s0, 0x2000
	s_add_u32 s0, s62, 0x20000
	v_lshl_add_u64 v[232:233], s[62:63], 0, v[132:133]
	s_addc_u32 s1, s63, 0
	s_add_i32 s33, s82, s67
	global_load_lds_dwordx4 v[232:233], off
	v_lshl_add_u64 v[234:235], s[0:1], 0, v[130:131]
	s_mov_b32 m0, s33
	v_lshl_add_u64 v[236:237], s[64:65], 0, v[132:133]
	global_load_lds_dwordx4 v[234:235], off
	v_lshl_add_u64 v[234:235], s[0:1], 0, v[132:133]
	s_add_i32 m0, s33, 0x2000
	s_nop 0
	global_load_lds_dwordx4 v[234:235], off
	v_lshl_add_u64 v[234:235], s[64:65], 0, v[130:131]
	s_mov_b32 m0, s68
	s_nop 0
	global_load_lds_dwordx4 v[234:235], off
	s_mov_b32 m0, s69
	s_nop 0
	global_load_lds_dwordx4 v[236:237], off
	s_waitcnt vmcnt(8)
	s_waitcnt lgkmcnt(0)
	s_barrier
	s_setprio 1
	s_waitcnt lgkmcnt(0)
	v_mfma_f32_16x16x32_bf16 v[126:129], v[160:163], v[196:199], v[126:129]
	v_mfma_f32_16x16x32_bf16 v[122:125], v[168:171], v[196:199], v[122:125]
	v_mfma_f32_16x16x32_bf16 v[110:113], v[160:163], v[208:211], v[110:113]
	v_mfma_f32_16x16x32_bf16 v[106:109], v[168:171], v[208:211], v[106:109]
	v_mfma_f32_16x16x32_bf16 v[94:97], v[160:163], v[216:219], v[94:97]
	v_mfma_f32_16x16x32_bf16 v[90:93], v[168:171], v[216:219], v[90:93]
	v_mfma_f32_16x16x32_bf16 v[78:81], v[160:163], v[224:227], v[78:81]
	v_mfma_f32_16x16x32_bf16 v[74:77], v[168:171], v[224:227], v[74:77]
	v_mfma_f32_16x16x32_bf16 v[126:129], v[164:167], v[200:203], v[126:129]
	v_mfma_f32_16x16x32_bf16 v[122:125], v[176:179], v[200:203], v[122:125]
	v_mfma_f32_16x16x32_bf16 v[110:113], v[164:167], v[212:215], v[110:113]
	v_mfma_f32_16x16x32_bf16 v[106:109], v[176:179], v[212:215], v[106:109]
	v_mfma_f32_16x16x32_bf16 v[94:97], v[164:167], v[220:223], v[94:97]
	v_mfma_f32_16x16x32_bf16 v[90:93], v[176:179], v[220:223], v[90:93]
	v_mfma_f32_16x16x32_bf16 v[78:81], v[164:167], v[228:231], v[78:81]
	v_mfma_f32_16x16x32_bf16 v[74:77], v[176:179], v[228:231], v[74:77]
	v_mfma_f32_16x16x32_bf16 v[118:121], v[180:183], v[196:199], v[118:121]
	v_mfma_f32_16x16x32_bf16 v[114:117], v[188:191], v[196:199], v[114:117]
	v_mfma_f32_16x16x32_bf16 v[102:105], v[180:183], v[208:211], v[102:105]
	v_mfma_f32_16x16x32_bf16 v[98:101], v[188:191], v[208:211], v[98:101]
	v_mfma_f32_16x16x32_bf16 v[86:89], v[180:183], v[216:219], v[86:89]
	v_mfma_f32_16x16x32_bf16 v[82:85], v[188:191], v[216:219], v[82:85]
	v_mfma_f32_16x16x32_bf16 v[70:73], v[180:183], v[224:227], v[70:73]
	v_mfma_f32_16x16x32_bf16 v[18:21], v[188:191], v[224:227], v[18:21]
	v_mfma_f32_16x16x32_bf16 v[118:121], v[184:187], v[200:203], v[118:121]
	v_mfma_f32_16x16x32_bf16 v[114:117], v[192:195], v[200:203], v[114:117]
	v_mfma_f32_16x16x32_bf16 v[102:105], v[184:187], v[212:215], v[102:105]
	v_mfma_f32_16x16x32_bf16 v[98:101], v[192:195], v[212:215], v[98:101]
	v_mfma_f32_16x16x32_bf16 v[86:89], v[184:187], v[220:223], v[86:89]
	v_mfma_f32_16x16x32_bf16 v[82:85], v[192:195], v[220:223], v[82:85]
	v_mfma_f32_16x16x32_bf16 v[70:73], v[184:187], v[228:231], v[70:73]
	v_mfma_f32_16x16x32_bf16 v[18:21], v[192:195], v[228:231], v[18:21]
	s_setprio 0
	s_barrier
	s_add_i32 s33, 0, 0x18000
	s_add_i32 s54, 0, 0x1c000
	v_add_u32_e32 v176, s33, v1
	v_add_u32_e32 v192, s54, v1
	ds_read_b128 v[160:163], v176
	ds_read_b128 v[164:167], v176 offset:1024
	ds_read_b128 v[168:171], v176 offset:2048
	ds_read_b128 v[176:179], v176 offset:3072
	ds_read_b128 v[180:183], v192
	ds_read_b128 v[184:187], v192 offset:1024
	ds_read_b128 v[188:191], v192 offset:2048
	ds_read_b128 v[192:195], v192 offset:3072
	s_add_u32 s0, s64, 0x20000
	s_addc_u32 s1, s65, 0
	s_mov_b32 m0, s70
	v_lshl_add_u64 v[238:239], s[0:1], 0, v[130:131]
	ds_read_b128 v[196:199], v175 offset:32768
	ds_read_b128 v[200:203], v175 offset:33792
	ds_read_b128 v[208:211], v175 offset:34816
	ds_read_b128 v[212:215], v175 offset:35840
	ds_read_b128 v[216:219], v175 offset:36864
	ds_read_b128 v[220:223], v175 offset:37888
	ds_read_b128 v[224:227], v175 offset:38912
	ds_read_b128 v[228:231], v175 offset:39936
	global_load_lds_dwordx4 v[238:239], off
	v_lshl_add_u64 v[238:239], s[0:1], 0, v[132:133]
	s_mov_b32 m0, s71
	s_nop 0
	global_load_lds_dwordx4 v[238:239], off
	s_waitcnt vmcnt(8)
	s_waitcnt lgkmcnt(0)
	s_barrier
	s_setprio 1
	s_waitcnt lgkmcnt(0)
	v_mfma_f32_16x16x32_bf16 v[66:69], v[160:163], v[196:199], v[66:69]
	v_mfma_f32_16x16x32_bf16 v[62:65], v[168:171], v[196:199], v[62:65]
	v_mfma_f32_16x16x32_bf16 v[58:61], v[160:163], v[208:211], v[58:61]
	v_mfma_f32_16x16x32_bf16 v[54:57], v[168:171], v[208:211], v[54:57]
	v_mfma_f32_16x16x32_bf16 v[50:53], v[160:163], v[216:219], v[50:53]
	v_mfma_f32_16x16x32_bf16 v[42:45], v[168:171], v[216:219], v[42:45]
	v_mfma_f32_16x16x32_bf16 v[34:37], v[160:163], v[224:227], v[34:37]
	v_mfma_f32_16x16x32_bf16 v[26:29], v[168:171], v[224:227], v[26:29]
	v_mfma_f32_16x16x32_bf16 v[66:69], v[164:167], v[200:203], v[66:69]
	v_mfma_f32_16x16x32_bf16 v[62:65], v[176:179], v[200:203], v[62:65]
	v_mfma_f32_16x16x32_bf16 v[58:61], v[164:167], v[212:215], v[58:61]
	v_mfma_f32_16x16x32_bf16 v[54:57], v[176:179], v[212:215], v[54:57]
	v_mfma_f32_16x16x32_bf16 v[50:53], v[164:167], v[220:223], v[50:53]
	v_mfma_f32_16x16x32_bf16 v[42:45], v[176:179], v[220:223], v[42:45]
	v_mfma_f32_16x16x32_bf16 v[34:37], v[164:167], v[228:231], v[34:37]
	v_mfma_f32_16x16x32_bf16 v[26:29], v[176:179], v[228:231], v[26:29]
	v_mfma_f32_16x16x32_bf16 v[46:49], v[180:183], v[196:199], v[46:49]
	v_mfma_f32_16x16x32_bf16 v[38:41], v[188:191], v[196:199], v[38:41]
	v_mfma_f32_16x16x32_bf16 v[30:33], v[180:183], v[208:211], v[30:33]
	v_mfma_f32_16x16x32_bf16 v[22:25], v[188:191], v[208:211], v[22:25]
	v_mfma_f32_16x16x32_bf16 v[14:17], v[180:183], v[216:219], v[14:17]
	v_mfma_f32_16x16x32_bf16 v[10:13], v[188:191], v[216:219], v[10:13]
	v_mfma_f32_16x16x32_bf16 v[6:9], v[180:183], v[224:227], v[6:9]
	v_mfma_f32_16x16x32_bf16 v[2:5], v[188:191], v[224:227], v[2:5]
	v_mfma_f32_16x16x32_bf16 v[46:49], v[184:187], v[200:203], v[46:49]
	v_mfma_f32_16x16x32_bf16 v[38:41], v[192:195], v[200:203], v[38:41]
	v_mfma_f32_16x16x32_bf16 v[30:33], v[184:187], v[212:215], v[30:33]
	v_mfma_f32_16x16x32_bf16 v[22:25], v[192:195], v[212:215], v[22:25]
	v_mfma_f32_16x16x32_bf16 v[14:17], v[184:187], v[220:223], v[14:17]
	v_mfma_f32_16x16x32_bf16 v[10:13], v[192:195], v[220:223], v[10:13]
	v_mfma_f32_16x16x32_bf16 v[6:9], v[184:187], v[228:231], v[6:9]
	v_mfma_f32_16x16x32_bf16 v[2:5], v[192:195], v[228:231], v[2:5]
	s_setprio 0
	s_barrier
	s_add_i32 s0, s33, s67
	v_lshl_add_u64 v[204:205], v[204:205], 0, s[22:23]
	s_mov_b32 m0, s0
	ds_read_b128 v[196:199], v175 offset:49152
	ds_read_b128 v[200:203], v175 offset:50176
	ds_read_b128 v[208:211], v175 offset:51200
	ds_read_b128 v[212:215], v175 offset:52224
	ds_read_b128 v[216:219], v175 offset:53248
	ds_read_b128 v[220:223], v175 offset:54272
	ds_read_b128 v[224:227], v175 offset:55296
	ds_read_b128 v[228:231], v175 offset:56320
	global_load_lds_dwordx4 v[204:205], off
	s_add_i32 m0, s0, 0x2000
	s_add_u32 s0, s62, 0x20080
	v_lshl_add_u64 v[204:205], v[232:233], 0, s[22:23]
	s_addc_u32 s1, s63, 0
	s_add_i32 s33, s54, s67
	global_load_lds_dwordx4 v[204:205], off
	v_lshl_add_u64 v[204:205], s[0:1], 0, v[130:131]
	s_mov_b32 m0, s33
	s_nop 0
	global_load_lds_dwordx4 v[204:205], off
	v_lshl_add_u64 v[204:205], s[0:1], 0, v[132:133]
	s_add_i32 m0, s33, 0x2000
	s_nop 0
	global_load_lds_dwordx4 v[204:205], off
	v_lshl_add_u64 v[204:205], v[234:235], 0, s[22:23]
	s_mov_b32 m0, s77
	s_nop 0
	global_load_lds_dwordx4 v[204:205], off
	v_lshl_add_u64 v[204:205], v[236:237], 0, s[22:23]
	s_mov_b32 m0, s78
	s_nop 0
	global_load_lds_dwordx4 v[204:205], off
	s_waitcnt vmcnt(8)
	s_waitcnt lgkmcnt(0)
	s_barrier
	s_setprio 1
	s_waitcnt lgkmcnt(0)
	v_mfma_f32_16x16x32_bf16 v[126:129], v[160:163], v[196:199], v[126:129]
	v_mfma_f32_16x16x32_bf16 v[122:125], v[168:171], v[196:199], v[122:125]
	v_mfma_f32_16x16x32_bf16 v[110:113], v[160:163], v[208:211], v[110:113]
	v_mfma_f32_16x16x32_bf16 v[106:109], v[168:171], v[208:211], v[106:109]
	v_mfma_f32_16x16x32_bf16 v[94:97], v[160:163], v[216:219], v[94:97]
	v_mfma_f32_16x16x32_bf16 v[90:93], v[168:171], v[216:219], v[90:93]
	v_mfma_f32_16x16x32_bf16 v[78:81], v[160:163], v[224:227], v[78:81]
	v_mfma_f32_16x16x32_bf16 v[74:77], v[168:171], v[224:227], v[74:77]
	v_mfma_f32_16x16x32_bf16 v[126:129], v[164:167], v[200:203], v[126:129]
	v_mfma_f32_16x16x32_bf16 v[122:125], v[176:179], v[200:203], v[122:125]
	v_mfma_f32_16x16x32_bf16 v[110:113], v[164:167], v[212:215], v[110:113]
	v_mfma_f32_16x16x32_bf16 v[106:109], v[176:179], v[212:215], v[106:109]
	v_mfma_f32_16x16x32_bf16 v[94:97], v[164:167], v[220:223], v[94:97]
	v_mfma_f32_16x16x32_bf16 v[90:93], v[176:179], v[220:223], v[90:93]
	v_mfma_f32_16x16x32_bf16 v[78:81], v[164:167], v[228:231], v[78:81]
	v_mfma_f32_16x16x32_bf16 v[74:77], v[176:179], v[228:231], v[74:77]
	v_mfma_f32_16x16x32_bf16 v[118:121], v[180:183], v[196:199], v[118:121]
	v_mfma_f32_16x16x32_bf16 v[114:117], v[188:191], v[196:199], v[114:117]
	v_mfma_f32_16x16x32_bf16 v[102:105], v[180:183], v[208:211], v[102:105]
	v_mfma_f32_16x16x32_bf16 v[98:101], v[188:191], v[208:211], v[98:101]
	v_mfma_f32_16x16x32_bf16 v[86:89], v[180:183], v[216:219], v[86:89]
	v_mfma_f32_16x16x32_bf16 v[82:85], v[188:191], v[216:219], v[82:85]
	v_mfma_f32_16x16x32_bf16 v[70:73], v[180:183], v[224:227], v[70:73]
	v_mfma_f32_16x16x32_bf16 v[18:21], v[188:191], v[224:227], v[18:21]
	v_mfma_f32_16x16x32_bf16 v[118:121], v[184:187], v[200:203], v[118:121]
	v_mfma_f32_16x16x32_bf16 v[114:117], v[192:195], v[200:203], v[114:117]
	v_mfma_f32_16x16x32_bf16 v[102:105], v[184:187], v[212:215], v[102:105]
	v_mfma_f32_16x16x32_bf16 v[98:101], v[192:195], v[212:215], v[98:101]
	v_mfma_f32_16x16x32_bf16 v[86:89], v[184:187], v[220:223], v[86:89]
	v_mfma_f32_16x16x32_bf16 v[82:85], v[192:195], v[220:223], v[82:85]
	v_mfma_f32_16x16x32_bf16 v[70:73], v[184:187], v[228:231], v[70:73]
	v_mfma_f32_16x16x32_bf16 v[18:21], v[192:195], v[228:231], v[18:21]
	s_setprio 0
	s_barrier
	s_add_u32 s60, s60, 0x100
	s_addc_u32 s61, s61, 0
	s_add_u32 s49, s49, 0x100
	s_addc_u32 s51, s51, 0
	s_cmp_ge_u32 s84, s13
	s_mov_b32 s59, s84
	s_cbranch_scc0 .LBB0_2541
	s_and_b64 vcc, exec, s[24:25]
	s_cbranch_vccz .LBB0_2544
	s_barrier

.LBB0_2702:
	ds_read_b128 v[144:147], v149
	ds_read_b128 v[152:155], v149 offset:1024
	ds_read_b128 v[156:159], v149 offset:2048
	ds_read_b128 v[160:163], v149 offset:3072
	ds_read_b128 v[164:167], v150
	ds_read_b128 v[168:171], v150 offset:1024
	ds_read_b128 v[172:175], v150 offset:2048
	ds_read_b128 v[176:179], v150 offset:3072
	s_add_u32 s0, s28, 0xfff80080
	s_addc_u32 s1, s29, -1
	s_cmp_eq_u32 s59, 28
	s_cselect_b32 s35, s21, s1
	s_cselect_b32 s34, s53, s0
	s_cselect_b32 s31, s19, s58
	s_cselect_b32 s30, s56, s57
	v_lshl_add_u64 v[204:205], s[28:29], 0, v[136:137]
	s_add_i32 m0, s41, 0xc000
	ds_read_b128 v[180:183], v151
	ds_read_b128 v[184:187], v151 offset:1024
	ds_read_b128 v[188:191], v151 offset:2048
	ds_read_b128 v[192:195], v151 offset:3072
	ds_read_b128 v[196:199], v151 offset:4096
	ds_read_b128 v[200:203], v151 offset:5120
	ds_read_b128 v[208:211], v151 offset:6144
	ds_read_b128 v[212:215], v151 offset:7168
	global_load_lds_dwordx4 v[204:205], off
	v_lshl_add_u64 v[204:205], s[28:29], 0, v[138:139]
	s_add_i32 m0, s41, 0xe000
	s_nop 0
	global_load_lds_dwordx4 v[204:205], off
	s_waitcnt vmcnt(8)
	s_waitcnt lgkmcnt(0)
	s_barrier
	s_setprio 1
	s_waitcnt lgkmcnt(0)
	v_mfma_f32_16x16x32_bf16 v[126:129], v[144:147], v[180:183], v[126:129]
	v_mfma_f32_16x16x32_bf16 v[122:125], v[156:159], v[180:183], v[122:125]
	v_mfma_f32_16x16x32_bf16 v[114:117], v[144:147], v[188:191], v[114:117]
	v_mfma_f32_16x16x32_bf16 v[106:109], v[156:159], v[188:191], v[106:109]
	v_mfma_f32_16x16x32_bf16 v[98:101], v[144:147], v[196:199], v[98:101]
	v_mfma_f32_16x16x32_bf16 v[90:93], v[156:159], v[196:199], v[90:93]
	v_mfma_f32_16x16x32_bf16 v[82:85], v[144:147], v[208:211], v[82:85]
	v_mfma_f32_16x16x32_bf16 v[74:77], v[156:159], v[208:211], v[74:77]
	v_mfma_f32_16x16x32_bf16 v[126:129], v[152:155], v[184:187], v[126:129]
	v_mfma_f32_16x16x32_bf16 v[122:125], v[160:163], v[184:187], v[122:125]
	v_mfma_f32_16x16x32_bf16 v[114:117], v[152:155], v[192:195], v[114:117]
	v_mfma_f32_16x16x32_bf16 v[106:109], v[160:163], v[192:195], v[106:109]
	v_mfma_f32_16x16x32_bf16 v[98:101], v[152:155], v[200:203], v[98:101]
	v_mfma_f32_16x16x32_bf16 v[90:93], v[160:163], v[200:203], v[90:93]
	v_mfma_f32_16x16x32_bf16 v[82:85], v[152:155], v[212:215], v[82:85]
	v_mfma_f32_16x16x32_bf16 v[74:77], v[160:163], v[212:215], v[74:77]
	v_mfma_f32_16x16x32_bf16 v[118:121], v[164:167], v[180:183], v[118:121]
	v_mfma_f32_16x16x32_bf16 v[110:113], v[172:175], v[180:183], v[110:113]
	v_mfma_f32_16x16x32_bf16 v[102:105], v[164:167], v[188:191], v[102:105]
	v_mfma_f32_16x16x32_bf16 v[94:97], v[172:175], v[188:191], v[94:97]
	v_mfma_f32_16x16x32_bf16 v[86:89], v[164:167], v[196:199], v[86:89]
	v_mfma_f32_16x16x32_bf16 v[78:81], v[172:175], v[196:199], v[78:81]
	v_mfma_f32_16x16x32_bf16 v[70:73], v[164:167], v[208:211], v[70:73]
	v_mfma_f32_16x16x32_bf16 v[66:69], v[172:175], v[208:211], v[66:69]
	v_mfma_f32_16x16x32_bf16 v[118:121], v[168:171], v[184:187], v[118:121]
	v_mfma_f32_16x16x32_bf16 v[110:113], v[176:179], v[184:187], v[110:113]
	v_mfma_f32_16x16x32_bf16 v[102:105], v[168:171], v[192:195], v[102:105]
	v_mfma_f32_16x16x32_bf16 v[94:97], v[176:179], v[192:195], v[94:97]
	v_mfma_f32_16x16x32_bf16 v[86:89], v[168:171], v[200:203], v[86:89]
	v_mfma_f32_16x16x32_bf16 v[78:81], v[176:179], v[200:203], v[78:81]
	v_mfma_f32_16x16x32_bf16 v[70:73], v[168:171], v[212:215], v[70:73]
	v_mfma_f32_16x16x32_bf16 v[66:69], v[176:179], v[212:215], v[66:69]
	s_setprio 0
	s_barrier
	s_add_i32 s0, s50, s40
	v_lshl_add_u64 v[204:205], s[30:31], 0, v[130:131]
	s_mov_b32 m0, s0
	ds_read_b128 v[180:183], v151 offset:16384
	ds_read_b128 v[184:187], v151 offset:17408
	ds_read_b128 v[188:191], v151 offset:18432
	ds_read_b128 v[192:195], v151 offset:19456
	ds_read_b128 v[196:199], v151 offset:20480
	ds_read_b128 v[200:203], v151 offset:21504
	ds_read_b128 v[208:211], v151 offset:22528
	ds_read_b128 v[212:215], v151 offset:23552
	global_load_lds_dwordx4 v[204:205], off
	s_add_i32 m0, s0, 0x2000
	s_add_u32 s0, s30, 0x80000
	v_lshl_add_u64 v[216:217], s[30:31], 0, v[132:133]
	s_addc_u32 s1, s31, 0
	s_add_i32 s33, s51, s40
	global_load_lds_dwordx4 v[216:217], off
	v_lshl_add_u64 v[218:219], s[0:1], 0, v[130:131]
	s_mov_b32 m0, s33
	v_lshl_add_u64 v[220:221], s[34:35], 0, v[132:133]
	global_load_lds_dwordx4 v[218:219], off
	v_lshl_add_u64 v[218:219], s[0:1], 0, v[132:133]
	s_add_i32 m0, s33, 0x2000
	s_nop 0
	global_load_lds_dwordx4 v[218:219], off
	v_lshl_add_u64 v[218:219], s[34:35], 0, v[130:131]
	s_mov_b32 m0, s41
	s_nop 0
	global_load_lds_dwordx4 v[218:219], off
	s_mov_b32 m0, s42
	s_nop 0
	global_load_lds_dwordx4 v[220:221], off
	s_waitcnt vmcnt(8)
	s_waitcnt lgkmcnt(0)
	s_barrier
	s_setprio 1
	s_waitcnt lgkmcnt(0)
	v_mfma_f32_16x16x32_bf16 v[62:65], v[144:147], v[180:183], v[62:65]
	v_mfma_f32_16x16x32_bf16 v[58:61], v[156:159], v[180:183], v[58:61]
	v_mfma_f32_16x16x32_bf16 v[50:53], v[144:147], v[188:191], v[50:53]
	v_mfma_f32_16x16x32_bf16 v[42:45], v[156:159], v[188:191], v[42:45]
	v_mfma_f32_16x16x32_bf16 v[34:37], v[144:147], v[196:199], v[34:37]
	v_mfma_f32_16x16x32_bf16 v[26:29], v[156:159], v[196:199], v[26:29]
	v_mfma_f32_16x16x32_bf16 v[18:21], v[144:147], v[208:211], v[18:21]
	v_mfma_f32_16x16x32_bf16 v[10:13], v[156:159], v[208:211], v[10:13]
	v_mfma_f32_16x16x32_bf16 v[62:65], v[152:155], v[184:187], v[62:65]
	v_mfma_f32_16x16x32_bf16 v[58:61], v[160:163], v[184:187], v[58:61]
	v_mfma_f32_16x16x32_bf16 v[50:53], v[152:155], v[192:195], v[50:53]
	v_mfma_f32_16x16x32_bf16 v[42:45], v[160:163], v[192:195], v[42:45]
	v_mfma_f32_16x16x32_bf16 v[34:37], v[152:155], v[200:203], v[34:37]
	v_mfma_f32_16x16x32_bf16 v[26:29], v[160:163], v[200:203], v[26:29]
	v_mfma_f32_16x16x32_bf16 v[18:21], v[152:155], v[212:215], v[18:21]
	v_mfma_f32_16x16x32_bf16 v[10:13], v[160:163], v[212:215], v[10:13]
	v_mfma_f32_16x16x32_bf16 v[54:57], v[164:167], v[180:183], v[54:57]
	v_mfma_f32_16x16x32_bf16 v[46:49], v[172:175], v[180:183], v[46:49]
	v_mfma_f32_16x16x32_bf16 v[38:41], v[164:167], v[188:191], v[38:41]
	v_mfma_f32_16x16x32_bf16 v[30:33], v[172:175], v[188:191], v[30:33]
	v_mfma_f32_16x16x32_bf16 v[22:25], v[164:167], v[196:199], v[22:25]
	v_mfma_f32_16x16x32_bf16 v[14:17], v[172:175], v[196:199], v[14:17]
	v_mfma_f32_16x16x32_bf16 v[6:9], v[164:167], v[208:211], v[6:9]
	v_mfma_f32_16x16x32_bf16 v[2:5], v[172:175], v[208:211], v[2:5]
	v_mfma_f32_16x16x32_bf16 v[54:57], v[168:171], v[184:187], v[54:57]
	v_mfma_f32_16x16x32_bf16 v[46:49], v[176:179], v[184:187], v[46:49]
	v_mfma_f32_16x16x32_bf16 v[38:41], v[168:171], v[192:195], v[38:41]
	v_mfma_f32_16x16x32_bf16 v[30:33], v[176:179], v[192:195], v[30:33]
	v_mfma_f32_16x16x32_bf16 v[22:25], v[168:171], v[200:203], v[22:25]
	v_mfma_f32_16x16x32_bf16 v[14:17], v[176:179], v[200:203], v[14:17]
	v_mfma_f32_16x16x32_bf16 v[6:9], v[168:171], v[212:215], v[6:9]
	v_mfma_f32_16x16x32_bf16 v[2:5], v[176:179], v[212:215], v[2:5]
	s_setprio 0
	s_barrier
	s_add_i32 s33, 0, 0x18000
	s_add_i32 s54, 0, 0x1c000
	v_add_u32_e32 v160, s33, v148
	v_add_u32_e32 v176, s54, v148
	ds_read_b128 v[144:147], v160
	ds_read_b128 v[152:155], v160 offset:1024
	ds_read_b128 v[156:159], v160 offset:2048
	ds_read_b128 v[160:163], v160 offset:3072
	ds_read_b128 v[164:167], v176
	ds_read_b128 v[168:171], v176 offset:1024
	ds_read_b128 v[172:175], v176 offset:2048
	ds_read_b128 v[176:179], v176 offset:3072
	s_add_u32 s0, s34, 0x80000
	s_addc_u32 s1, s35, 0
	s_mov_b32 m0, s43
	v_lshl_add_u64 v[222:223], s[0:1], 0, v[130:131]
	ds_read_b128 v[180:183], v151 offset:32768
	ds_read_b128 v[184:187], v151 offset:33792
	ds_read_b128 v[188:191], v151 offset:34816
	ds_read_b128 v[192:195], v151 offset:35840
	ds_read_b128 v[196:199], v151 offset:36864
	ds_read_b128 v[200:203], v151 offset:37888
	ds_read_b128 v[208:211], v151 offset:38912
	ds_read_b128 v[212:215], v151 offset:39936
	global_load_lds_dwordx4 v[222:223], off
	v_lshl_add_u64 v[222:223], s[0:1], 0, v[132:133]
	s_mov_b32 m0, s44
	s_nop 0
	global_load_lds_dwordx4 v[222:223], off
	s_waitcnt vmcnt(8)
	s_waitcnt lgkmcnt(0)
	s_barrier
	s_setprio 1
	s_waitcnt lgkmcnt(0)
	v_mfma_f32_16x16x32_bf16 v[126:129], v[144:147], v[180:183], v[126:129]
	v_mfma_f32_16x16x32_bf16 v[122:125], v[156:159], v[180:183], v[122:125]
	v_mfma_f32_16x16x32_bf16 v[114:117], v[144:147], v[188:191], v[114:117]
	v_mfma_f32_16x16x32_bf16 v[106:109], v[156:159], v[188:191], v[106:109]
	v_mfma_f32_16x16x32_bf16 v[98:101], v[144:147], v[196:199], v[98:101]
	v_mfma_f32_16x16x32_bf16 v[90:93], v[156:159], v[196:199], v[90:93]
	v_mfma_f32_16x16x32_bf16 v[82:85], v[144:147], v[208:211], v[82:85]
	v_mfma_f32_16x16x32_bf16 v[74:77], v[156:159], v[208:211], v[74:77]
	v_mfma_f32_16x16x32_bf16 v[126:129], v[152:155], v[184:187], v[126:129]
	v_mfma_f32_16x16x32_bf16 v[122:125], v[160:163], v[184:187], v[122:125]
	v_mfma_f32_16x16x32_bf16 v[114:117], v[152:155], v[192:195], v[114:117]
	v_mfma_f32_16x16x32_bf16 v[106:109], v[160:163], v[192:195], v[106:109]
	v_mfma_f32_16x16x32_bf16 v[98:101], v[152:155], v[200:203], v[98:101]
	v_mfma_f32_16x16x32_bf16 v[90:93], v[160:163], v[200:203], v[90:93]
	v_mfma_f32_16x16x32_bf16 v[82:85], v[152:155], v[212:215], v[82:85]
	v_mfma_f32_16x16x32_bf16 v[74:77], v[160:163], v[212:215], v[74:77]
	v_mfma_f32_16x16x32_bf16 v[118:121], v[164:167], v[180:183], v[118:121]
	v_mfma_f32_16x16x32_bf16 v[110:113], v[172:175], v[180:183], v[110:113]
	v_mfma_f32_16x16x32_bf16 v[102:105], v[164:167], v[188:191], v[102:105]
	v_mfma_f32_16x16x32_bf16 v[94:97], v[172:175], v[188:191], v[94:97]
	v_mfma_f32_16x16x32_bf16 v[86:89], v[164:167], v[196:199], v[86:89]
	v_mfma_f32_16x16x32_bf16 v[78:81], v[172:175], v[196:199], v[78:81]
	v_mfma_f32_16x16x32_bf16 v[70:73], v[164:167], v[208:211], v[70:73]
	v_mfma_f32_16x16x32_bf16 v[66:69], v[172:175], v[208:211], v[66:69]
	v_mfma_f32_16x16x32_bf16 v[118:121], v[168:171], v[184:187], v[118:121]
	v_mfma_f32_16x16x32_bf16 v[110:113], v[176:179], v[184:187], v[110:113]
	v_mfma_f32_16x16x32_bf16 v[102:105], v[168:171], v[192:195], v[102:105]
	v_mfma_f32_16x16x32_bf16 v[94:97], v[176:179], v[192:195], v[94:97]
	v_mfma_f32_16x16x32_bf16 v[86:89], v[168:171], v[200:203], v[86:89]
	v_mfma_f32_16x16x32_bf16 v[78:81], v[176:179], v[200:203], v[78:81]
	v_mfma_f32_16x16x32_bf16 v[70:73], v[168:171], v[212:215], v[70:73]
	v_mfma_f32_16x16x32_bf16 v[66:69], v[176:179], v[212:215], v[66:69]
	s_setprio 0
	s_barrier
	s_add_i32 s0, s33, s40
	v_lshl_add_u64 v[204:205], v[204:205], 0, s[14:15]
	s_mov_b32 m0, s0
	ds_read_b128 v[180:183], v151 offset:49152
	ds_read_b128 v[184:187], v151 offset:50176
	ds_read_b128 v[188:191], v151 offset:51200
	ds_read_b128 v[192:195], v151 offset:52224
	ds_read_b128 v[196:199], v151 offset:53248
	ds_read_b128 v[200:203], v151 offset:54272
	ds_read_b128 v[208:211], v151 offset:55296
	ds_read_b128 v[212:215], v151 offset:56320
	global_load_lds_dwordx4 v[204:205], off
	s_add_i32 m0, s0, 0x2000
	s_add_u32 s0, s30, 0x80080
	v_lshl_add_u64 v[204:205], v[216:217], 0, s[14:15]
	s_addc_u32 s1, s31, 0
	s_add_i32 s30, s54, s40
	global_load_lds_dwordx4 v[204:205], off
	v_lshl_add_u64 v[204:205], s[0:1], 0, v[130:131]
	s_mov_b32 m0, s30
	s_nop 0
	global_load_lds_dwordx4 v[204:205], off
	v_lshl_add_u64 v[204:205], s[0:1], 0, v[132:133]
	s_add_i32 m0, s30, 0x2000
	s_nop 0
	global_load_lds_dwordx4 v[204:205], off
	v_lshl_add_u64 v[204:205], v[218:219], 0, s[14:15]
	s_mov_b32 m0, s47
	s_nop 0
	global_load_lds_dwordx4 v[204:205], off
	v_lshl_add_u64 v[204:205], v[220:221], 0, s[14:15]
	s_mov_b32 m0, s48
	s_nop 0
	global_load_lds_dwordx4 v[204:205], off
	s_waitcnt vmcnt(8)
	s_waitcnt lgkmcnt(0)
	s_barrier
	s_setprio 1
	s_waitcnt lgkmcnt(0)
	v_mfma_f32_16x16x32_bf16 v[62:65], v[144:147], v[180:183], v[62:65]
	v_mfma_f32_16x16x32_bf16 v[58:61], v[156:159], v[180:183], v[58:61]
	v_mfma_f32_16x16x32_bf16 v[50:53], v[144:147], v[188:191], v[50:53]
	v_mfma_f32_16x16x32_bf16 v[42:45], v[156:159], v[188:191], v[42:45]
	v_mfma_f32_16x16x32_bf16 v[34:37], v[144:147], v[196:199], v[34:37]
	v_mfma_f32_16x16x32_bf16 v[26:29], v[156:159], v[196:199], v[26:29]
	v_mfma_f32_16x16x32_bf16 v[18:21], v[144:147], v[208:211], v[18:21]
	v_mfma_f32_16x16x32_bf16 v[10:13], v[156:159], v[208:211], v[10:13]
	v_mfma_f32_16x16x32_bf16 v[62:65], v[152:155], v[184:187], v[62:65]
	v_mfma_f32_16x16x32_bf16 v[58:61], v[160:163], v[184:187], v[58:61]
	v_mfma_f32_16x16x32_bf16 v[50:53], v[152:155], v[192:195], v[50:53]
	v_mfma_f32_16x16x32_bf16 v[42:45], v[160:163], v[192:195], v[42:45]
	v_mfma_f32_16x16x32_bf16 v[34:37], v[152:155], v[200:203], v[34:37]
	v_mfma_f32_16x16x32_bf16 v[26:29], v[160:163], v[200:203], v[26:29]
	v_mfma_f32_16x16x32_bf16 v[18:21], v[152:155], v[212:215], v[18:21]
	v_mfma_f32_16x16x32_bf16 v[10:13], v[160:163], v[212:215], v[10:13]
	v_mfma_f32_16x16x32_bf16 v[54:57], v[164:167], v[180:183], v[54:57]
	v_mfma_f32_16x16x32_bf16 v[46:49], v[172:175], v[180:183], v[46:49]
	v_mfma_f32_16x16x32_bf16 v[38:41], v[164:167], v[188:191], v[38:41]
	v_mfma_f32_16x16x32_bf16 v[30:33], v[172:175], v[188:191], v[30:33]
	v_mfma_f32_16x16x32_bf16 v[22:25], v[164:167], v[196:199], v[22:25]
	v_mfma_f32_16x16x32_bf16 v[14:17], v[172:175], v[196:199], v[14:17]
	v_mfma_f32_16x16x32_bf16 v[6:9], v[164:167], v[208:211], v[6:9]
	v_mfma_f32_16x16x32_bf16 v[2:5], v[172:175], v[208:211], v[2:5]
	v_mfma_f32_16x16x32_bf16 v[54:57], v[168:171], v[184:187], v[54:57]
	v_mfma_f32_16x16x32_bf16 v[46:49], v[176:179], v[184:187], v[46:49]
	v_mfma_f32_16x16x32_bf16 v[38:41], v[168:171], v[192:195], v[38:41]
	v_mfma_f32_16x16x32_bf16 v[30:33], v[176:179], v[192:195], v[30:33]
	v_mfma_f32_16x16x32_bf16 v[22:25], v[168:171], v[200:203], v[22:25]
	v_mfma_f32_16x16x32_bf16 v[14:17], v[176:179], v[200:203], v[14:17]
	v_mfma_f32_16x16x32_bf16 v[6:9], v[168:171], v[212:215], v[6:9]
	v_mfma_f32_16x16x32_bf16 v[2:5], v[176:179], v[212:215], v[2:5]
	s_setprio 0
	s_barrier
	s_add_i32 s59, s59, 2
	s_add_u32 s28, s28, 0x100
	s_addc_u32 s29, s29, 0
	s_add_u32 s57, s57, 0x100
	s_addc_u32 s58, s58, 0
	s_cmp_gt_u32 s59, 29
	s_cbranch_scc0 .LBB0_2702
	s_and_b64 vcc, exec, s[16:17]
	s_cbranch_vccz .LBB0_2705
	s_barrier

.LBB0_2896:
	ds_read_b128 v[168:171], v145
	ds_read_b128 v[172:175], v145 offset:1024
	ds_read_b128 v[176:179], v145 offset:2048
	ds_read_b128 v[180:183], v145 offset:3072
	ds_read_b128 v[184:187], v147
	ds_read_b128 v[188:191], v147 offset:1024
	ds_read_b128 v[192:195], v147 offset:2048
	ds_read_b128 v[196:199], v147 offset:3072
	s_add_i32 s62, s8, 2
	s_add_u32 s0, s6, 0xffea0080
	s_addc_u32 s1, s7, -1
	s_cmp_eq_u32 s31, s8
	s_cselect_b32 s8, s28, s60
	s_cselect_b32 s41, s27, s1
	s_cselect_b32 s40, s26, s0
	s_cselect_b32 s9, s29, s61
	v_lshl_add_u64 v[204:205], s[6:7], 0, v[160:161]
	s_add_i32 m0, s45, 0xc000
	ds_read_b128 v[200:203], v149
	ds_read_b128 v[208:211], v149 offset:1024
	ds_read_b128 v[212:215], v149 offset:2048
	ds_read_b128 v[216:219], v149 offset:3072
	ds_read_b128 v[220:223], v149 offset:4096
	ds_read_b128 v[224:227], v149 offset:5120
	ds_read_b128 v[228:231], v149 offset:6144
	ds_read_b128 v[232:235], v149 offset:7168
	global_load_lds_dwordx4 v[204:205], off
	v_lshl_add_u64 v[204:205], s[6:7], 0, v[162:163]
	s_add_i32 m0, s45, 0xe000
	s_nop 0
	global_load_lds_dwordx4 v[204:205], off
	s_waitcnt vmcnt(8)
	s_waitcnt lgkmcnt(0)
	s_barrier
	s_setprio 1
	s_waitcnt lgkmcnt(0)
	v_mfma_f32_16x16x32_bf16 v[126:129], v[168:171], v[200:203], v[126:129]
	v_mfma_f32_16x16x32_bf16 v[122:125], v[176:179], v[200:203], v[122:125]
	v_mfma_f32_16x16x32_bf16 v[110:113], v[168:171], v[212:215], v[110:113]
	v_mfma_f32_16x16x32_bf16 v[106:109], v[176:179], v[212:215], v[106:109]
	v_mfma_f32_16x16x32_bf16 v[94:97], v[168:171], v[220:223], v[94:97]
	v_mfma_f32_16x16x32_bf16 v[90:93], v[176:179], v[220:223], v[90:93]
	v_mfma_f32_16x16x32_bf16 v[78:81], v[168:171], v[228:231], v[78:81]
	v_mfma_f32_16x16x32_bf16 v[74:77], v[176:179], v[228:231], v[74:77]
	v_mfma_f32_16x16x32_bf16 v[126:129], v[172:175], v[208:211], v[126:129]
	v_mfma_f32_16x16x32_bf16 v[122:125], v[180:183], v[208:211], v[122:125]
	v_mfma_f32_16x16x32_bf16 v[110:113], v[172:175], v[216:219], v[110:113]
	v_mfma_f32_16x16x32_bf16 v[106:109], v[180:183], v[216:219], v[106:109]
	v_mfma_f32_16x16x32_bf16 v[94:97], v[172:175], v[224:227], v[94:97]
	v_mfma_f32_16x16x32_bf16 v[90:93], v[180:183], v[224:227], v[90:93]
	v_mfma_f32_16x16x32_bf16 v[78:81], v[172:175], v[232:235], v[78:81]
	v_mfma_f32_16x16x32_bf16 v[74:77], v[180:183], v[232:235], v[74:77]
	v_mfma_f32_16x16x32_bf16 v[118:121], v[184:187], v[200:203], v[118:121]
	v_mfma_f32_16x16x32_bf16 v[114:117], v[192:195], v[200:203], v[114:117]
	v_mfma_f32_16x16x32_bf16 v[102:105], v[184:187], v[212:215], v[102:105]
	v_mfma_f32_16x16x32_bf16 v[98:101], v[192:195], v[212:215], v[98:101]
	v_mfma_f32_16x16x32_bf16 v[86:89], v[184:187], v[220:223], v[86:89]
	v_mfma_f32_16x16x32_bf16 v[82:85], v[192:195], v[220:223], v[82:85]
	v_mfma_f32_16x16x32_bf16 v[70:73], v[184:187], v[228:231], v[70:73]
	v_mfma_f32_16x16x32_bf16 v[66:69], v[192:195], v[228:231], v[66:69]
	v_mfma_f32_16x16x32_bf16 v[118:121], v[188:191], v[208:211], v[118:121]
	v_mfma_f32_16x16x32_bf16 v[114:117], v[196:199], v[208:211], v[114:117]
	v_mfma_f32_16x16x32_bf16 v[102:105], v[188:191], v[216:219], v[102:105]
	v_mfma_f32_16x16x32_bf16 v[98:101], v[196:199], v[216:219], v[98:101]
	v_mfma_f32_16x16x32_bf16 v[86:89], v[188:191], v[224:227], v[86:89]
	v_mfma_f32_16x16x32_bf16 v[82:85], v[196:199], v[224:227], v[82:85]
	v_mfma_f32_16x16x32_bf16 v[70:73], v[188:191], v[232:235], v[70:73]
	v_mfma_f32_16x16x32_bf16 v[66:69], v[196:199], v[232:235], v[66:69]
	s_setprio 0
	s_barrier
	s_add_i32 s0, s54, s44
	v_lshl_add_u64 v[204:205], s[8:9], 0, v[130:131]
	s_mov_b32 m0, s0
	ds_read_b128 v[200:203], v149 offset:16384
	ds_read_b128 v[208:211], v149 offset:17408
	ds_read_b128 v[212:215], v149 offset:18432
	ds_read_b128 v[216:219], v149 offset:19456
	ds_read_b128 v[220:223], v149 offset:20480
	ds_read_b128 v[224:227], v149 offset:21504
	ds_read_b128 v[228:231], v149 offset:22528
	ds_read_b128 v[232:235], v149 offset:23552
	global_load_lds_dwordx4 v[204:205], off
	s_add_i32 m0, s0, 0x2000
	s_add_u32 s0, s8, 0x160000
	v_lshl_add_u64 v[236:237], s[8:9], 0, v[132:133]
	s_addc_u32 s1, s9, 0
	s_add_i32 s33, s55, s44
	global_load_lds_dwordx4 v[236:237], off
	v_lshl_add_u64 v[238:239], s[0:1], 0, v[130:131]
	s_mov_b32 m0, s33
	v_lshl_add_u64 v[240:241], s[40:41], 0, v[132:133]
	global_load_lds_dwordx4 v[238:239], off
	v_lshl_add_u64 v[238:239], s[0:1], 0, v[132:133]
	s_add_i32 m0, s33, 0x2000
	s_nop 0
	global_load_lds_dwordx4 v[238:239], off
	v_lshl_add_u64 v[238:239], s[40:41], 0, v[130:131]
	s_mov_b32 m0, s45
	s_nop 0
	global_load_lds_dwordx4 v[238:239], off
	s_mov_b32 m0, s46
	s_nop 0
	global_load_lds_dwordx4 v[240:241], off
	s_waitcnt vmcnt(8)
	s_waitcnt lgkmcnt(0)
	s_barrier
	s_setprio 1
	s_waitcnt lgkmcnt(0)
	v_mfma_f32_16x16x32_bf16 v[62:65], v[168:171], v[200:203], v[62:65]
	v_mfma_f32_16x16x32_bf16 v[58:61], v[176:179], v[200:203], v[58:61]
	v_mfma_f32_16x16x32_bf16 v[46:49], v[168:171], v[212:215], v[46:49]
	v_mfma_f32_16x16x32_bf16 v[42:45], v[176:179], v[212:215], v[42:45]
	v_mfma_f32_16x16x32_bf16 v[30:33], v[168:171], v[220:223], v[30:33]
	v_mfma_f32_16x16x32_bf16 v[26:29], v[176:179], v[220:223], v[26:29]
	v_mfma_f32_16x16x32_bf16 v[14:17], v[168:171], v[228:231], v[14:17]
	v_mfma_f32_16x16x32_bf16 v[10:13], v[176:179], v[228:231], v[10:13]
	v_mfma_f32_16x16x32_bf16 v[62:65], v[172:175], v[208:211], v[62:65]
	v_mfma_f32_16x16x32_bf16 v[58:61], v[180:183], v[208:211], v[58:61]
	v_mfma_f32_16x16x32_bf16 v[46:49], v[172:175], v[216:219], v[46:49]
	v_mfma_f32_16x16x32_bf16 v[42:45], v[180:183], v[216:219], v[42:45]
	v_mfma_f32_16x16x32_bf16 v[30:33], v[172:175], v[224:227], v[30:33]
	v_mfma_f32_16x16x32_bf16 v[26:29], v[180:183], v[224:227], v[26:29]
	v_mfma_f32_16x16x32_bf16 v[14:17], v[172:175], v[232:235], v[14:17]
	v_mfma_f32_16x16x32_bf16 v[10:13], v[180:183], v[232:235], v[10:13]
	v_mfma_f32_16x16x32_bf16 v[54:57], v[184:187], v[200:203], v[54:57]
	v_mfma_f32_16x16x32_bf16 v[50:53], v[192:195], v[200:203], v[50:53]
	v_mfma_f32_16x16x32_bf16 v[38:41], v[184:187], v[212:215], v[38:41]
	v_mfma_f32_16x16x32_bf16 v[34:37], v[192:195], v[212:215], v[34:37]
	v_mfma_f32_16x16x32_bf16 v[22:25], v[184:187], v[220:223], v[22:25]
	v_mfma_f32_16x16x32_bf16 v[18:21], v[192:195], v[220:223], v[18:21]
	v_mfma_f32_16x16x32_bf16 v[6:9], v[184:187], v[228:231], v[6:9]
	v_mfma_f32_16x16x32_bf16 v[2:5], v[192:195], v[228:231], v[2:5]
	v_mfma_f32_16x16x32_bf16 v[54:57], v[188:191], v[208:211], v[54:57]
	v_mfma_f32_16x16x32_bf16 v[50:53], v[196:199], v[208:211], v[50:53]
	v_mfma_f32_16x16x32_bf16 v[38:41], v[188:191], v[216:219], v[38:41]
	v_mfma_f32_16x16x32_bf16 v[34:37], v[196:199], v[216:219], v[34:37]
	v_mfma_f32_16x16x32_bf16 v[22:25], v[188:191], v[224:227], v[22:25]
	v_mfma_f32_16x16x32_bf16 v[18:21], v[196:199], v[224:227], v[18:21]
	v_mfma_f32_16x16x32_bf16 v[6:9], v[188:191], v[232:235], v[6:9]
	v_mfma_f32_16x16x32_bf16 v[2:5], v[196:199], v[232:235], v[2:5]
	s_setprio 0
	s_barrier
	s_add_i32 s33, 0, 0x18000
	v_add_u32_e32 v134, s33, v1
	s_add_i32 s63, 0, 0x1c000
	ds_read_b128 v[168:171], v134
	ds_read_b128 v[172:175], v134 offset:1024
	ds_read_b128 v[176:179], v134 offset:2048
	ds_read_b128 v[180:183], v134 offset:3072
	v_add_u32_e32 v134, s63, v1
	ds_read_b128 v[184:187], v134
	ds_read_b128 v[188:191], v134 offset:1024
	ds_read_b128 v[192:195], v134 offset:2048
	ds_read_b128 v[196:199], v134 offset:3072
	s_add_u32 s0, s40, 0x160000
	s_addc_u32 s1, s41, 0
	s_mov_b32 m0, s47
	v_lshl_add_u64 v[242:243], s[0:1], 0, v[130:131]
	ds_read_b128 v[200:203], v149 offset:32768
	ds_read_b128 v[208:211], v149 offset:33792
	ds_read_b128 v[212:215], v149 offset:34816
	ds_read_b128 v[216:219], v149 offset:35840
	ds_read_b128 v[220:223], v149 offset:36864
	ds_read_b128 v[224:227], v149 offset:37888
	ds_read_b128 v[228:231], v149 offset:38912
	ds_read_b128 v[232:235], v149 offset:39936
	global_load_lds_dwordx4 v[242:243], off
	v_lshl_add_u64 v[242:243], s[0:1], 0, v[132:133]
	s_mov_b32 m0, s48
	s_nop 0
	global_load_lds_dwordx4 v[242:243], off
	s_waitcnt vmcnt(8)
	s_waitcnt lgkmcnt(0)
	s_barrier
	s_setprio 1
	s_waitcnt lgkmcnt(0)
	v_mfma_f32_16x16x32_bf16 v[126:129], v[168:171], v[200:203], v[126:129]
	v_mfma_f32_16x16x32_bf16 v[122:125], v[176:179], v[200:203], v[122:125]
	v_mfma_f32_16x16x32_bf16 v[110:113], v[168:171], v[212:215], v[110:113]
	v_mfma_f32_16x16x32_bf16 v[106:109], v[176:179], v[212:215], v[106:109]
	v_mfma_f32_16x16x32_bf16 v[94:97], v[168:171], v[220:223], v[94:97]
	v_mfma_f32_16x16x32_bf16 v[90:93], v[176:179], v[220:223], v[90:93]
	v_mfma_f32_16x16x32_bf16 v[78:81], v[168:171], v[228:231], v[78:81]
	v_mfma_f32_16x16x32_bf16 v[74:77], v[176:179], v[228:231], v[74:77]
	v_mfma_f32_16x16x32_bf16 v[126:129], v[172:175], v[208:211], v[126:129]
	v_mfma_f32_16x16x32_bf16 v[122:125], v[180:183], v[208:211], v[122:125]
	v_mfma_f32_16x16x32_bf16 v[110:113], v[172:175], v[216:219], v[110:113]
	v_mfma_f32_16x16x32_bf16 v[106:109], v[180:183], v[216:219], v[106:109]
	v_mfma_f32_16x16x32_bf16 v[94:97], v[172:175], v[224:227], v[94:97]
	v_mfma_f32_16x16x32_bf16 v[90:93], v[180:183], v[224:227], v[90:93]
	v_mfma_f32_16x16x32_bf16 v[78:81], v[172:175], v[232:235], v[78:81]
	v_mfma_f32_16x16x32_bf16 v[74:77], v[180:183], v[232:235], v[74:77]
	v_mfma_f32_16x16x32_bf16 v[118:121], v[184:187], v[200:203], v[118:121]
	v_mfma_f32_16x16x32_bf16 v[114:117], v[192:195], v[200:203], v[114:117]
	v_mfma_f32_16x16x32_bf16 v[102:105], v[184:187], v[212:215], v[102:105]
	v_mfma_f32_16x16x32_bf16 v[98:101], v[192:195], v[212:215], v[98:101]
	v_mfma_f32_16x16x32_bf16 v[86:89], v[184:187], v[220:223], v[86:89]
	v_mfma_f32_16x16x32_bf16 v[82:85], v[192:195], v[220:223], v[82:85]
	v_mfma_f32_16x16x32_bf16 v[70:73], v[184:187], v[228:231], v[70:73]
	v_mfma_f32_16x16x32_bf16 v[66:69], v[192:195], v[228:231], v[66:69]
	v_mfma_f32_16x16x32_bf16 v[118:121], v[188:191], v[208:211], v[118:121]
	v_mfma_f32_16x16x32_bf16 v[114:117], v[196:199], v[208:211], v[114:117]
	v_mfma_f32_16x16x32_bf16 v[102:105], v[188:191], v[216:219], v[102:105]
	v_mfma_f32_16x16x32_bf16 v[98:101], v[196:199], v[216:219], v[98:101]
	v_mfma_f32_16x16x32_bf16 v[86:89], v[188:191], v[224:227], v[86:89]
	v_mfma_f32_16x16x32_bf16 v[82:85], v[196:199], v[224:227], v[82:85]
	v_mfma_f32_16x16x32_bf16 v[70:73], v[188:191], v[232:235], v[70:73]
	v_mfma_f32_16x16x32_bf16 v[66:69], v[196:199], v[232:235], v[66:69]
	s_setprio 0
	s_barrier
	s_add_i32 s0, s33, s44
	v_lshl_add_u64 v[204:205], v[204:205], 0, s[18:19]
	s_mov_b32 m0, s0
	ds_read_b128 v[200:203], v149 offset:49152
	ds_read_b128 v[208:211], v149 offset:50176
	ds_read_b128 v[212:215], v149 offset:51200
	ds_read_b128 v[216:219], v149 offset:52224
	ds_read_b128 v[220:223], v149 offset:53248
	ds_read_b128 v[224:227], v149 offset:54272
	ds_read_b128 v[228:231], v149 offset:55296
	ds_read_b128 v[232:235], v149 offset:56320
	global_load_lds_dwordx4 v[204:205], off
	s_add_i32 m0, s0, 0x2000
	s_add_u32 s0, s8, 0x160080
	v_lshl_add_u64 v[204:205], v[236:237], 0, s[18:19]
	s_addc_u32 s1, s9, 0
	s_add_i32 s8, s63, s44
	global_load_lds_dwordx4 v[204:205], off
	v_lshl_add_u64 v[204:205], s[0:1], 0, v[130:131]
	s_mov_b32 m0, s8
	s_nop 0
	global_load_lds_dwordx4 v[204:205], off
	v_lshl_add_u64 v[204:205], s[0:1], 0, v[132:133]
	s_add_i32 m0, s8, 0x2000
	s_nop 0
	global_load_lds_dwordx4 v[204:205], off
	v_lshl_add_u64 v[204:205], v[238:239], 0, s[18:19]
	s_mov_b32 m0, s50
	s_nop 0
	global_load_lds_dwordx4 v[204:205], off
	v_lshl_add_u64 v[204:205], v[240:241], 0, s[18:19]
	s_mov_b32 m0, s51
	s_nop 0
	global_load_lds_dwordx4 v[204:205], off
	s_waitcnt vmcnt(8)
	s_waitcnt lgkmcnt(0)
	s_barrier
	s_setprio 1
	s_waitcnt lgkmcnt(0)
	v_mfma_f32_16x16x32_bf16 v[62:65], v[168:171], v[200:203], v[62:65]
	v_mfma_f32_16x16x32_bf16 v[58:61], v[176:179], v[200:203], v[58:61]
	v_mfma_f32_16x16x32_bf16 v[46:49], v[168:171], v[212:215], v[46:49]
	v_mfma_f32_16x16x32_bf16 v[42:45], v[176:179], v[212:215], v[42:45]
	v_mfma_f32_16x16x32_bf16 v[30:33], v[168:171], v[220:223], v[30:33]
	v_mfma_f32_16x16x32_bf16 v[26:29], v[176:179], v[220:223], v[26:29]
	v_mfma_f32_16x16x32_bf16 v[14:17], v[168:171], v[228:231], v[14:17]
	v_mfma_f32_16x16x32_bf16 v[10:13], v[176:179], v[228:231], v[10:13]
	v_mfma_f32_16x16x32_bf16 v[62:65], v[172:175], v[208:211], v[62:65]
	v_mfma_f32_16x16x32_bf16 v[58:61], v[180:183], v[208:211], v[58:61]
	v_mfma_f32_16x16x32_bf16 v[46:49], v[172:175], v[216:219], v[46:49]
	v_mfma_f32_16x16x32_bf16 v[42:45], v[180:183], v[216:219], v[42:45]
	v_mfma_f32_16x16x32_bf16 v[30:33], v[172:175], v[224:227], v[30:33]
	v_mfma_f32_16x16x32_bf16 v[26:29], v[180:183], v[224:227], v[26:29]
	v_mfma_f32_16x16x32_bf16 v[14:17], v[172:175], v[232:235], v[14:17]
	v_mfma_f32_16x16x32_bf16 v[10:13], v[180:183], v[232:235], v[10:13]
	v_mfma_f32_16x16x32_bf16 v[54:57], v[184:187], v[200:203], v[54:57]
	v_mfma_f32_16x16x32_bf16 v[50:53], v[192:195], v[200:203], v[50:53]
	v_mfma_f32_16x16x32_bf16 v[38:41], v[184:187], v[212:215], v[38:41]
	v_mfma_f32_16x16x32_bf16 v[34:37], v[192:195], v[212:215], v[34:37]
	v_mfma_f32_16x16x32_bf16 v[22:25], v[184:187], v[220:223], v[22:25]
	v_mfma_f32_16x16x32_bf16 v[18:21], v[192:195], v[220:223], v[18:21]
	v_mfma_f32_16x16x32_bf16 v[6:9], v[184:187], v[228:231], v[6:9]
	v_mfma_f32_16x16x32_bf16 v[2:5], v[192:195], v[228:231], v[2:5]
	v_mfma_f32_16x16x32_bf16 v[54:57], v[188:191], v[208:211], v[54:57]
	v_mfma_f32_16x16x32_bf16 v[50:53], v[196:199], v[208:211], v[50:53]
	v_mfma_f32_16x16x32_bf16 v[38:41], v[188:191], v[216:219], v[38:41]
	v_mfma_f32_16x16x32_bf16 v[34:37], v[196:199], v[216:219], v[34:37]
	v_mfma_f32_16x16x32_bf16 v[22:25], v[188:191], v[224:227], v[22:25]
	v_mfma_f32_16x16x32_bf16 v[18:21], v[196:199], v[224:227], v[18:21]
	v_mfma_f32_16x16x32_bf16 v[6:9], v[188:191], v[232:235], v[6:9]
	v_mfma_f32_16x16x32_bf16 v[2:5], v[196:199], v[232:235], v[2:5]
	s_setprio 0
	s_barrier
	s_add_u32 s6, s6, 0x100
	s_addc_u32 s7, s7, 0
	s_add_u32 s60, s60, 0x100
	s_addc_u32 s61, s61, 0
	s_cmp_ge_u32 s62, s25
	s_mov_b32 s8, s62
	s_cbranch_scc0 .LBB0_2896
	s_and_b64 vcc, exec, s[20:21]
	s_cbranch_vccz .LBB0_2899
	s_barrier
